# v6 + B-fragment LDS read addresses precomputed once per unit (4 VALU adds per K-loop iteration removed, immediate offsets instead)
# speedup vs baseline: 1.0044x; 1.0007x over previous
; #define PG8_STAGE(bufoff, gbase, voff) do { _Pragma("unroll") for (int _i = 0; _i < 2; ++_i) \
;         __builtin_amdgcn_global_load_lds((const unsigned*)((const char*)(gbase) + (voff)[_i]), (PG8_LAS unsigned*)(lds + (bufoff) + ldsw + _i * 8192), 16, 0, 0); } while (0)
; #define PG8_LDA(dst, b, h) do { _Pragma("unroll") for (int m = 0; m < 4; ++m) _Pragma("unroll") for (int k = 0; k < 2; ++k) dst[m][k] = *(const PG8_LAS bf16x8*)(lds + PG8_SA(b, h) + aoff + m * 2048 + k * 1024); } while (0)
; #define PG8_LDB(dst, b, h) do { _Pragma("unroll") for (int n = 0; n < 2; ++n) _Pragma("unroll") for (int k = 0; k < 2; ++k) dst[n][k] = *(const PG8_LAS bf16x8*)(lds + PG8_SB(b, h) + boff + n * 2048 + k * 1024); } while (0)
; #define PG8_MMA(ai, bj, At, Bt) do { __builtin_amdgcn_s_setprio(1); _Pragma("unroll") for (int m = 0; m < 4; ++m) _Pragma("unroll") for (int n = 0; n < 2; ++n) _Pragma("unroll") for (int k = 0; k < 2; ++k) \
;         acc[ai][bj][m][n] = __builtin_amdgcn_mfma_f32_16x16x32_bf16(Bt[n][k], At[m][k], acc[ai][bj][m][n], 0, 0, 0); __builtin_amdgcn_s_setprio(0); } while (0)
; #define PG8_WAIT_V(n) asm volatile("s_waitcnt vmcnt(" #n ")" ::: "memory")
; #define PG8_WAIT_L(n) asm volatile("s_waitcnt lgkmcnt(" #n ")" ::: "memory")
; #define PG8_BAR __builtin_amdgcn_s_barrier()
; #define PG8_SCHED __builtin_amdgcn_sched_barrier(0)
; template <class Epi>
; __device__ __forceinline__ void gemm_phase(PG8_LAS unsigned char* lds, PG8_LAS unsigned char* xl, const Gemm g, const Sched& S, const Epi& E, const int wid) {
;     ...
;             const char* a1 = cA + (size_t)(t + 1) * kstep + j1;
;             const char* a2 = last ? nA : cA + (size_t)(t + 2) * kstep + ja2; const char* b2 = last ? nB : cB + (size_t)(t + 2) * kstep + jb2;
;             const char* a3 = a2 + kstep; const char* b3 = b2 + kstep;
;             PG8_LDB(B0, 0, 0); PG8_LDB(B1, 0, 1); PG8_SCHED; PG8_LDA(At, 0, 0); PG8_STAGE(PG8_SA(1, 1), a1 + hstepA, voffA);
;             PG8_WAIT_V(8); PG8_WAIT_L(0); PG8_BAR; if (do0) { PG8_MMA(0, 0, At, B0); PG8_MMA(0, 1, At, B1); } PG8_BAR; PG8_SCHED;
;             PG8_LDA(At, 0, 1); PG8_STAGE(PG8_SB(0, 0), b2, voffB); PG8_STAGE(PG8_SB(0, 1), b2 + hstepB, voffB); PG8_STAGE(PG8_SA(0, 0), a2, voffA);
.Ldefbar_skip_0:
	v_add_u32_e32 v141, s22, v128
	v_add_u32_e32 v226, s22, v130
	v_add_u32_e32 v227, s22, v132
	v_add_u32_e32 v228, s22, v134
	v_add_u32_e32 v229, 0x10000, v142
.LBB0_220:
	s_add_u32 s52, s50, 0x100
	s_addc_u32 s53, s51, 0
	s_add_i32 s54, 0, 0x10000
	s_cmp_eq_u32 s43, 28
	s_cselect_b32 s59, s8, s53
	s_cselect_b32 s58, s9, s52
	s_cselect_b32 s57, s10, s21
	s_cselect_b32 s56, s11, s13
	s_add_i32 s55, 0, 0x14000
	ds_read_b128 v[144:147], v229 offset:0
	ds_read_b128 v[148:151], v229 offset:1024
	ds_read_b128 v[152:155], v229 offset:2048
	ds_read_b128 v[156:159], v229 offset:3072
	ds_read_b128 v[160:163], v229 offset:16384
	ds_read_b128 v[164:167], v229 offset:17408
	ds_read_b128 v[168:171], v229 offset:18432
	ds_read_b128 v[172:175], v229 offset:19456
	s_add_i32 m0, s37, 0xc000
	ds_read_b128 v[176:179], v143
	ds_read_b128 v[180:183], v143 offset:1024
	ds_read_b128 v[184:187], v143 offset:2048
	ds_read_b128 v[188:191], v143 offset:3072
	ds_read_b128 v[210:213], v143 offset:4096
	ds_read_b128 v[214:217], v143 offset:5120
	ds_read_b128 v[218:221], v143 offset:6144
	ds_read_b128 v[222:225], v143 offset:7168
	global_load_lds_dwordx4 v136, s[50:51]
	s_add_i32 m0, s37, 0xe000
	s_nop 0
	global_load_lds_dwordx4 v138, s[50:51]
	s_waitcnt vmcnt(8)
	s_waitcnt lgkmcnt(0)
	s_setprio 1
	s_barrier
	v_mfma_f32_16x16x32_bf16 v[124:127], v[144:147], v[176:179], v[124:127]
	v_mfma_f32_16x16x32_bf16 v[120:123], v[152:155], v[176:179], v[120:123]
	v_mfma_f32_16x16x32_bf16 v[116:119], v[144:147], v[184:187], v[116:119]
	v_mfma_f32_16x16x32_bf16 v[108:111], v[152:155], v[184:187], v[108:111]
	v_mfma_f32_16x16x32_bf16 v[100:103], v[144:147], v[210:213], v[100:103]
	v_mfma_f32_16x16x32_bf16 v[92:95], v[152:155], v[210:213], v[92:95]
	v_mfma_f32_16x16x32_bf16 v[84:87], v[144:147], v[218:221], v[84:87]
	v_mfma_f32_16x16x32_bf16 v[76:79], v[152:155], v[218:221], v[76:79]
	v_mfma_f32_16x16x32_bf16 v[124:127], v[148:151], v[180:183], v[124:127]
	v_mfma_f32_16x16x32_bf16 v[120:123], v[156:159], v[180:183], v[120:123]
	v_mfma_f32_16x16x32_bf16 v[116:119], v[148:151], v[188:191], v[116:119]
	v_mfma_f32_16x16x32_bf16 v[108:111], v[156:159], v[188:191], v[108:111]
	v_mfma_f32_16x16x32_bf16 v[100:103], v[148:151], v[214:217], v[100:103]
	v_mfma_f32_16x16x32_bf16 v[92:95], v[156:159], v[214:217], v[92:95]
	v_mfma_f32_16x16x32_bf16 v[84:87], v[148:151], v[222:225], v[84:87]
	v_mfma_f32_16x16x32_bf16 v[76:79], v[156:159], v[222:225], v[76:79]
	s_setprio 0
	s_setprio 1
	v_mfma_f32_16x16x32_bf16 v[112:115], v[160:163], v[176:179], v[112:115]
	v_mfma_f32_16x16x32_bf16 v[104:107], v[168:171], v[176:179], v[104:107]
	v_mfma_f32_16x16x32_bf16 v[96:99], v[160:163], v[184:187], v[96:99]
	v_mfma_f32_16x16x32_bf16 v[88:91], v[168:171], v[184:187], v[88:91]
	v_mfma_f32_16x16x32_bf16 v[80:83], v[160:163], v[210:213], v[80:83]
	v_mfma_f32_16x16x32_bf16 v[72:75], v[168:171], v[210:213], v[72:75]
	v_mfma_f32_16x16x32_bf16 v[68:71], v[160:163], v[218:221], v[68:71]
	v_mfma_f32_16x16x32_bf16 v[64:67], v[168:171], v[218:221], v[64:67]
	v_mfma_f32_16x16x32_bf16 v[112:115], v[164:167], v[180:183], v[112:115]
	v_mfma_f32_16x16x32_bf16 v[104:107], v[172:175], v[180:183], v[104:107]
	v_mfma_f32_16x16x32_bf16 v[96:99], v[164:167], v[188:191], v[96:99]
	v_mfma_f32_16x16x32_bf16 v[88:91], v[172:175], v[188:191], v[88:91]
	v_mfma_f32_16x16x32_bf16 v[80:83], v[164:167], v[214:217], v[80:83]
	v_mfma_f32_16x16x32_bf16 v[72:75], v[172:175], v[214:217], v[72:75]
	v_mfma_f32_16x16x32_bf16 v[68:71], v[164:167], v[222:225], v[68:71]
	v_mfma_f32_16x16x32_bf16 v[64:67], v[172:175], v[222:225], v[64:67]
	s_barrier
	s_setprio 0
	s_add_i32 s50, s54, s29
	s_mov_b32 m0, s50
	ds_read_b128 v[176:179], v143 offset:16384
	ds_read_b128 v[180:183], v143 offset:17408
	ds_read_b128 v[184:187], v143 offset:18432
	ds_read_b128 v[188:191], v143 offset:19456
	ds_read_b128 v[210:213], v143 offset:20480
	ds_read_b128 v[214:217], v143 offset:21504
	ds_read_b128 v[218:221], v143 offset:22528
	ds_read_b128 v[222:225], v143 offset:23552
	global_load_lds_dwordx4 v132, s[56:57]
	s_add_i32 m0, s50, 0x2000
	s_add_u32 s50, s56, 0x80000
	s_addc_u32 s51, s57, 0
	s_add_i32 s54, s55, s29
	global_load_lds_dwordx4 v128, s[56:57]
	s_mov_b32 m0, s54
	s_nop 0
	global_load_lds_dwordx4 v132, s[50:51]
	s_add_i32 m0, s54, 0x2000
	s_nop 0
	global_load_lds_dwordx4 v128, s[50:51]
	s_mov_b32 m0, s37
	s_nop 0
	global_load_lds_dwordx4 v134, s[58:59]
	s_mov_b32 m0, s68
	s_nop 0
	global_load_lds_dwordx4 v130, s[58:59]
	s_waitcnt vmcnt(8)
	s_waitcnt lgkmcnt(0)
	s_setprio 1
	s_barrier
; #define PG8_STAGE(bufoff, gbase, voff) do { _Pragma("unroll") for (int _i = 0; _i < 2; ++_i) \
;         __builtin_amdgcn_global_load_lds((const unsigned*)((const char*)(gbase) + (voff)[_i]), (PG8_LAS unsigned*)(lds + (bufoff) + ldsw + _i * 8192), 16, 0, 0); } while (0)
; #define PG8_LDA(dst, b, h) do { _Pragma("unroll") for (int m = 0; m < 4; ++m) _Pragma("unroll") for (int k = 0; k < 2; ++k) dst[m][k] = *(const PG8_LAS bf16x8*)(lds + PG8_SA(b, h) + aoff + m * 2048 + k * 1024); } while (0)
; #define PG8_LDB(dst, b, h) do { _Pragma("unroll") for (int n = 0; n < 2; ++n) _Pragma("unroll") for (int k = 0; k < 2; ++k) dst[n][k] = *(const PG8_LAS bf16x8*)(lds + PG8_SB(b, h) + boff + n * 2048 + k * 1024); } while (0)
; #define PG8_MMA(ai, bj, At, Bt) do { __builtin_amdgcn_s_setprio(1); _Pragma("unroll") for (int m = 0; m < 4; ++m) _Pragma("unroll") for (int n = 0; n < 2; ++n) _Pragma("unroll") for (int k = 0; k < 2; ++k) \
;         acc[ai][bj][m][n] = __builtin_amdgcn_mfma_f32_16x16x32_bf16(Bt[n][k], At[m][k], acc[ai][bj][m][n], 0, 0, 0); __builtin_amdgcn_s_setprio(0); } while (0)
; #define PG8_WAIT_V(n) asm volatile("s_waitcnt vmcnt(" #n ")" ::: "memory")
; #define PG8_WAIT_L(n) asm volatile("s_waitcnt lgkmcnt(" #n ")" ::: "memory")
; #define PG8_BAR __builtin_amdgcn_s_barrier()
; #define PG8_SCHED __builtin_amdgcn_sched_barrier(0)
; template <class Epi>
; __device__ __forceinline__ void gemm_phase(PG8_LAS unsigned char* lds, PG8_LAS unsigned char* xl, const Gemm g, const Sched& S, const Epi& E, const int wid) {
;     ...
;             PG8_WAIT_V(8); PG8_WAIT_L(0); PG8_BAR; if (do1) { PG8_MMA(1, 0, At, B0); PG8_MMA(1, 1, At, B1); } PG8_BAR; PG8_SCHED;
;             PG8_LDB(B0, 1, 0); PG8_LDB(B1, 1, 1); PG8_SCHED; PG8_LDA(At, 1, 0); PG8_STAGE(PG8_SA(0, 1), a2 + hstepA, voffA);
;             PG8_WAIT_V(8); PG8_WAIT_L(0); PG8_BAR; if (do0) { PG8_MMA(0, 0, At, B0); PG8_MMA(0, 1, At, B1); } PG8_BAR; PG8_SCHED;
	v_mfma_f32_16x16x32_bf16 v[60:63], v[144:147], v[176:179], v[60:63]
	v_mfma_f32_16x16x32_bf16 v[56:59], v[152:155], v[176:179], v[56:59]
	v_mfma_f32_16x16x32_bf16 v[52:55], v[144:147], v[184:187], v[52:55]
	v_mfma_f32_16x16x32_bf16 v[44:47], v[152:155], v[184:187], v[44:47]
	v_mfma_f32_16x16x32_bf16 v[36:39], v[144:147], v[210:213], v[36:39]
	v_mfma_f32_16x16x32_bf16 v[28:31], v[152:155], v[210:213], v[28:31]
	v_mfma_f32_16x16x32_bf16 v[20:23], v[144:147], v[218:221], v[20:23]
	v_mfma_f32_16x16x32_bf16 v[12:15], v[152:155], v[218:221], v[12:15]
	v_mfma_f32_16x16x32_bf16 v[60:63], v[148:151], v[180:183], v[60:63]
	v_mfma_f32_16x16x32_bf16 v[56:59], v[156:159], v[180:183], v[56:59]
	v_mfma_f32_16x16x32_bf16 v[52:55], v[148:151], v[188:191], v[52:55]
	v_mfma_f32_16x16x32_bf16 v[44:47], v[156:159], v[188:191], v[44:47]
	v_mfma_f32_16x16x32_bf16 v[36:39], v[148:151], v[214:217], v[36:39]
	v_mfma_f32_16x16x32_bf16 v[28:31], v[156:159], v[214:217], v[28:31]
	v_mfma_f32_16x16x32_bf16 v[20:23], v[148:151], v[222:225], v[20:23]
	v_mfma_f32_16x16x32_bf16 v[12:15], v[156:159], v[222:225], v[12:15]
	s_setprio 0
	s_setprio 1
	v_mfma_f32_16x16x32_bf16 v[48:51], v[160:163], v[176:179], v[48:51]
	v_mfma_f32_16x16x32_bf16 v[40:43], v[168:171], v[176:179], v[40:43]
	v_mfma_f32_16x16x32_bf16 v[32:35], v[160:163], v[184:187], v[32:35]
	v_mfma_f32_16x16x32_bf16 v[24:27], v[168:171], v[184:187], v[24:27]
	v_mfma_f32_16x16x32_bf16 v[16:19], v[160:163], v[210:213], v[16:19]
	v_mfma_f32_16x16x32_bf16 v[8:11], v[168:171], v[210:213], v[8:11]
	v_mfma_f32_16x16x32_bf16 v[4:7], v[160:163], v[218:221], v[4:7]
	v_mfma_f32_16x16x32_bf16 v[0:3], v[168:171], v[218:221], v[0:3]
	v_mfma_f32_16x16x32_bf16 v[48:51], v[164:167], v[180:183], v[48:51]
	v_mfma_f32_16x16x32_bf16 v[40:43], v[172:175], v[180:183], v[40:43]
	v_mfma_f32_16x16x32_bf16 v[32:35], v[164:167], v[188:191], v[32:35]
	v_mfma_f32_16x16x32_bf16 v[24:27], v[172:175], v[188:191], v[24:27]
	v_mfma_f32_16x16x32_bf16 v[16:19], v[164:167], v[214:217], v[16:19]
	v_mfma_f32_16x16x32_bf16 v[8:11], v[172:175], v[214:217], v[8:11]
	v_mfma_f32_16x16x32_bf16 v[4:7], v[164:167], v[222:225], v[4:7]
	v_mfma_f32_16x16x32_bf16 v[0:3], v[172:175], v[222:225], v[0:3]
	s_barrier
	s_setprio 0
	s_add_i32 s54, 0, 0x18000
	s_add_i32 s55, 0, 0x1c000
	ds_read_b128 v[144:147], v229 offset:32768
	ds_read_b128 v[148:151], v229 offset:33792
	ds_read_b128 v[152:155], v229 offset:34816
	ds_read_b128 v[156:159], v229 offset:35840
	ds_read_b128 v[160:163], v229 offset:49152
	ds_read_b128 v[164:167], v229 offset:50176
	ds_read_b128 v[168:171], v229 offset:51200
	ds_read_b128 v[172:175], v229 offset:52224
	s_add_u32 s50, s58, 0x80000
	s_addc_u32 s51, s59, 0
	s_mov_b32 m0, s69
	ds_read_b128 v[176:179], v143 offset:32768
	ds_read_b128 v[180:183], v143 offset:33792
	ds_read_b128 v[184:187], v143 offset:34816
	ds_read_b128 v[188:191], v143 offset:35840
	ds_read_b128 v[210:213], v143 offset:36864
	ds_read_b128 v[214:217], v143 offset:37888
	ds_read_b128 v[218:221], v143 offset:38912
	ds_read_b128 v[222:225], v143 offset:39936
	global_load_lds_dwordx4 v134, s[50:51]
	s_mov_b32 m0, s70
	s_nop 0
	global_load_lds_dwordx4 v130, s[50:51]
	s_waitcnt vmcnt(8)
	s_waitcnt lgkmcnt(0)
	s_setprio 1
	s_barrier
	v_mfma_f32_16x16x32_bf16 v[124:127], v[144:147], v[176:179], v[124:127]
	v_mfma_f32_16x16x32_bf16 v[120:123], v[152:155], v[176:179], v[120:123]
	v_mfma_f32_16x16x32_bf16 v[116:119], v[144:147], v[184:187], v[116:119]
	v_mfma_f32_16x16x32_bf16 v[108:111], v[152:155], v[184:187], v[108:111]
	v_mfma_f32_16x16x32_bf16 v[100:103], v[144:147], v[210:213], v[100:103]
	v_mfma_f32_16x16x32_bf16 v[92:95], v[152:155], v[210:213], v[92:95]
	v_mfma_f32_16x16x32_bf16 v[84:87], v[144:147], v[218:221], v[84:87]
	v_mfma_f32_16x16x32_bf16 v[76:79], v[152:155], v[218:221], v[76:79]
	v_mfma_f32_16x16x32_bf16 v[124:127], v[148:151], v[180:183], v[124:127]
	v_mfma_f32_16x16x32_bf16 v[120:123], v[156:159], v[180:183], v[120:123]
	v_mfma_f32_16x16x32_bf16 v[116:119], v[148:151], v[188:191], v[116:119]
	v_mfma_f32_16x16x32_bf16 v[108:111], v[156:159], v[188:191], v[108:111]
	v_mfma_f32_16x16x32_bf16 v[100:103], v[148:151], v[214:217], v[100:103]
	v_mfma_f32_16x16x32_bf16 v[92:95], v[156:159], v[214:217], v[92:95]
	v_mfma_f32_16x16x32_bf16 v[84:87], v[148:151], v[222:225], v[84:87]
	v_mfma_f32_16x16x32_bf16 v[76:79], v[156:159], v[222:225], v[76:79]
	s_setprio 0
	s_setprio 1
	v_mfma_f32_16x16x32_bf16 v[112:115], v[160:163], v[176:179], v[112:115]
	v_mfma_f32_16x16x32_bf16 v[104:107], v[168:171], v[176:179], v[104:107]
	v_mfma_f32_16x16x32_bf16 v[96:99], v[160:163], v[184:187], v[96:99]
	v_mfma_f32_16x16x32_bf16 v[88:91], v[168:171], v[184:187], v[88:91]
	v_mfma_f32_16x16x32_bf16 v[80:83], v[160:163], v[210:213], v[80:83]
	v_mfma_f32_16x16x32_bf16 v[72:75], v[168:171], v[210:213], v[72:75]
	v_mfma_f32_16x16x32_bf16 v[68:71], v[160:163], v[218:221], v[68:71]
	v_mfma_f32_16x16x32_bf16 v[64:67], v[168:171], v[218:221], v[64:67]
	v_mfma_f32_16x16x32_bf16 v[112:115], v[164:167], v[180:183], v[112:115]
	v_mfma_f32_16x16x32_bf16 v[104:107], v[172:175], v[180:183], v[104:107]
	v_mfma_f32_16x16x32_bf16 v[96:99], v[164:167], v[188:191], v[96:99]
	v_mfma_f32_16x16x32_bf16 v[88:91], v[172:175], v[188:191], v[88:91]
	v_mfma_f32_16x16x32_bf16 v[80:83], v[164:167], v[214:217], v[80:83]
	v_mfma_f32_16x16x32_bf16 v[72:75], v[172:175], v[214:217], v[72:75]
	v_mfma_f32_16x16x32_bf16 v[68:71], v[164:167], v[222:225], v[68:71]
	v_mfma_f32_16x16x32_bf16 v[64:67], v[172:175], v[222:225], v[64:67]
	s_barrier
; #define PG8_STAGE(bufoff, gbase, voff) do { _Pragma("unroll") for (int _i = 0; _i < 2; ++_i) \
;         __builtin_amdgcn_global_load_lds((const unsigned*)((const char*)(gbase) + (voff)[_i]), (PG8_LAS unsigned*)(lds + (bufoff) + ldsw + _i * 8192), 16, 0, 0); } while (0)
; #define PG8_LDA(dst, b, h) do { _Pragma("unroll") for (int m = 0; m < 4; ++m) _Pragma("unroll") for (int k = 0; k < 2; ++k) dst[m][k] = *(const PG8_LAS bf16x8*)(lds + PG8_SA(b, h) + aoff + m * 2048 + k * 1024); } while (0)
; #define PG8_MMA(ai, bj, At, Bt) do { __builtin_amdgcn_s_setprio(1); _Pragma("unroll") for (int m = 0; m < 4; ++m) _Pragma("unroll") for (int n = 0; n < 2; ++n) _Pragma("unroll") for (int k = 0; k < 2; ++k) \
;         acc[ai][bj][m][n] = __builtin_amdgcn_mfma_f32_16x16x32_bf16(Bt[n][k], At[m][k], acc[ai][bj][m][n], 0, 0, 0); __builtin_amdgcn_s_setprio(0); } while (0)
; #define PG8_WAIT_V(n) asm volatile("s_waitcnt vmcnt(" #n ")" ::: "memory")
; #define PG8_WAIT_L(n) asm volatile("s_waitcnt lgkmcnt(" #n ")" ::: "memory")
; #define PG8_BAR __builtin_amdgcn_s_barrier()
; #define PG8_SCHED __builtin_amdgcn_sched_barrier(0)
; template <class Epi>
; __device__ __forceinline__ void gemm_phase(PG8_LAS unsigned char* lds, PG8_LAS unsigned char* xl, const Gemm g, const Sched& S, const Epi& E, const int wid) {
;     ...
;             PG8_LDA(At, 1, 1); PG8_STAGE(PG8_SB(1, 0), b3, voffB); PG8_STAGE(PG8_SB(1, 1), b3 + hstepB, voffB); PG8_STAGE(PG8_SA(1, 0), a3, voffA);
;             PG8_WAIT_V(8); PG8_WAIT_L(0); PG8_BAR; if (do1) { PG8_MMA(1, 0, At, B0); PG8_MMA(1, 1, At, B1); } PG8_BAR; PG8_SCHED;
;         }
	s_setprio 0
	s_add_i32 s50, s54, s29
	s_mov_b32 m0, s50
	ds_read_b128 v[176:179], v143 offset:49152
	ds_read_b128 v[180:183], v143 offset:50176
	ds_read_b128 v[184:187], v143 offset:51200
	ds_read_b128 v[188:191], v143 offset:52224
	ds_read_b128 v[210:213], v143 offset:53248
	ds_read_b128 v[214:217], v143 offset:54272
	ds_read_b128 v[218:221], v143 offset:55296
	ds_read_b128 v[222:225], v143 offset:56320
	global_load_lds_dwordx4 v227, s[56:57]
	s_add_i32 m0, s50, 0x2000
	s_add_u32 s50, s56, 0x80080
	global_load_lds_dwordx4 v141, s[56:57]
	s_addc_u32 s51, s57, 0
	s_add_i32 s54, s55, s29
	s_mov_b32 m0, s54
	s_nop 0
	global_load_lds_dwordx4 v132, s[50:51]
	s_add_i32 m0, s54, 0x2000
	s_nop 0
	global_load_lds_dwordx4 v128, s[50:51]
	s_mov_b32 m0, s77
	s_nop 0
	global_load_lds_dwordx4 v228, s[58:59]
	s_mov_b32 m0, s87
	s_nop 0
	global_load_lds_dwordx4 v226, s[58:59]
	s_waitcnt vmcnt(8)
	s_waitcnt lgkmcnt(0)
	s_setprio 1
	s_barrier
	v_mfma_f32_16x16x32_bf16 v[60:63], v[144:147], v[176:179], v[60:63]
	v_mfma_f32_16x16x32_bf16 v[56:59], v[152:155], v[176:179], v[56:59]
	v_mfma_f32_16x16x32_bf16 v[52:55], v[144:147], v[184:187], v[52:55]
	v_mfma_f32_16x16x32_bf16 v[44:47], v[152:155], v[184:187], v[44:47]
	v_mfma_f32_16x16x32_bf16 v[36:39], v[144:147], v[210:213], v[36:39]
	v_mfma_f32_16x16x32_bf16 v[28:31], v[152:155], v[210:213], v[28:31]
	v_mfma_f32_16x16x32_bf16 v[20:23], v[144:147], v[218:221], v[20:23]
	v_mfma_f32_16x16x32_bf16 v[12:15], v[152:155], v[218:221], v[12:15]
	v_mfma_f32_16x16x32_bf16 v[60:63], v[148:151], v[180:183], v[60:63]
	v_mfma_f32_16x16x32_bf16 v[56:59], v[156:159], v[180:183], v[56:59]
	v_mfma_f32_16x16x32_bf16 v[52:55], v[148:151], v[188:191], v[52:55]
	v_mfma_f32_16x16x32_bf16 v[44:47], v[156:159], v[188:191], v[44:47]
	v_mfma_f32_16x16x32_bf16 v[36:39], v[148:151], v[214:217], v[36:39]
	v_mfma_f32_16x16x32_bf16 v[28:31], v[156:159], v[214:217], v[28:31]
	v_mfma_f32_16x16x32_bf16 v[20:23], v[148:151], v[222:225], v[20:23]
	v_mfma_f32_16x16x32_bf16 v[12:15], v[156:159], v[222:225], v[12:15]
	s_setprio 0
	s_setprio 1
	v_mfma_f32_16x16x32_bf16 v[48:51], v[160:163], v[176:179], v[48:51]
	v_mfma_f32_16x16x32_bf16 v[40:43], v[168:171], v[176:179], v[40:43]
	v_mfma_f32_16x16x32_bf16 v[32:35], v[160:163], v[184:187], v[32:35]
	v_mfma_f32_16x16x32_bf16 v[24:27], v[168:171], v[184:187], v[24:27]
	v_mfma_f32_16x16x32_bf16 v[16:19], v[160:163], v[210:213], v[16:19]
	v_mfma_f32_16x16x32_bf16 v[8:11], v[168:171], v[210:213], v[8:11]
	v_mfma_f32_16x16x32_bf16 v[4:7], v[160:163], v[218:221], v[4:7]
	v_mfma_f32_16x16x32_bf16 v[0:3], v[168:171], v[218:221], v[0:3]
	v_mfma_f32_16x16x32_bf16 v[48:51], v[164:167], v[180:183], v[48:51]
	v_mfma_f32_16x16x32_bf16 v[40:43], v[172:175], v[180:183], v[40:43]
	v_mfma_f32_16x16x32_bf16 v[32:35], v[164:167], v[188:191], v[32:35]
	v_mfma_f32_16x16x32_bf16 v[24:27], v[172:175], v[188:191], v[24:27]
	v_mfma_f32_16x16x32_bf16 v[16:19], v[164:167], v[214:217], v[16:19]
	v_mfma_f32_16x16x32_bf16 v[8:11], v[172:175], v[214:217], v[8:11]
	v_mfma_f32_16x16x32_bf16 v[4:7], v[164:167], v[222:225], v[4:7]
	v_mfma_f32_16x16x32_bf16 v[0:3], v[172:175], v[222:225], v[0:3]
	s_barrier
	s_setprio 0
	s_add_i32 s43, s43, 2
	s_add_u32 s13, s13, 0x100
	s_addc_u32 s21, s21, 0
	s_cmp_gt_u32 s43, 29
	s_mov_b64 s[50:51], s[52:53]
	s_cbranch_scc0 .LBB0_220
	s_and_b64 vcc, exec, s[14:15]
	s_cbranch_vccz .LBB0_223
	s_barrier

; #define PG8_STAGE(bufoff, gbase, voff) do { _Pragma("unroll") for (int _i = 0; _i < 2; ++_i) \
;         __builtin_amdgcn_global_load_lds((const unsigned*)((const char*)(gbase) + (voff)[_i]), (PG8_LAS unsigned*)(lds + (bufoff) + ldsw + _i * 8192), 16, 0, 0); } while (0)
; #define PG8_LDA(dst, b, h) do { _Pragma("unroll") for (int m = 0; m < 4; ++m) _Pragma("unroll") for (int k = 0; k < 2; ++k) dst[m][k] = *(const PG8_LAS bf16x8*)(lds + PG8_SA(b, h) + aoff + m * 2048 + k * 1024); } while (0)
; #define PG8_LDB(dst, b, h) do { _Pragma("unroll") for (int n = 0; n < 2; ++n) _Pragma("unroll") for (int k = 0; k < 2; ++k) dst[n][k] = *(const PG8_LAS bf16x8*)(lds + PG8_SB(b, h) + boff + n * 2048 + k * 1024); } while (0)
; #define PG8_MMA(ai, bj, At, Bt) do { __builtin_amdgcn_s_setprio(1); _Pragma("unroll") for (int m = 0; m < 4; ++m) _Pragma("unroll") for (int n = 0; n < 2; ++n) _Pragma("unroll") for (int k = 0; k < 2; ++k) \
;         acc[ai][bj][m][n] = __builtin_amdgcn_mfma_f32_16x16x32_bf16(Bt[n][k], At[m][k], acc[ai][bj][m][n], 0, 0, 0); __builtin_amdgcn_s_setprio(0); } while (0)
; #define PG8_WAIT_V(n) asm volatile("s_waitcnt vmcnt(" #n ")" ::: "memory")
; #define PG8_WAIT_L(n) asm volatile("s_waitcnt lgkmcnt(" #n ")" ::: "memory")
; #define PG8_BAR __builtin_amdgcn_s_barrier()
; #define PG8_SCHED __builtin_amdgcn_sched_barrier(0)
; template <class Epi>
; __device__ __forceinline__ void gemm_phase(PG8_LAS unsigned char* lds, PG8_LAS unsigned char* xl, const Gemm g, const Sched& S, const Epi& E, const int wid) {
;     ...
;             const char* a1 = cA + (size_t)(t + 1) * kstep + j1;
;             const char* a2 = last ? nA : cA + (size_t)(t + 2) * kstep + ja2; const char* b2 = last ? nB : cB + (size_t)(t + 2) * kstep + jb2;
;             const char* a3 = a2 + kstep; const char* b3 = b2 + kstep;
;             PG8_LDB(B0, 0, 0); PG8_LDB(B1, 0, 1); PG8_SCHED; PG8_LDA(At, 0, 0); PG8_STAGE(PG8_SA(1, 1), a1 + hstepA, voffA);
;             PG8_WAIT_V(8); PG8_WAIT_L(0); PG8_BAR; if (do0) { PG8_MMA(0, 0, At, B0); PG8_MMA(0, 1, At, B1); } PG8_BAR; PG8_SCHED;
;             PG8_LDA(At, 0, 1); PG8_STAGE(PG8_SB(0, 0), b2, voffB); PG8_STAGE(PG8_SB(0, 1), b2 + hstepB, voffB); PG8_STAGE(PG8_SA(0, 0), a2, voffA);
.Ldefbar_skip_1:
	v_add_u32_e32 v157, s22, v140
	v_add_u32_e32 v234, s22, v142
	v_add_u32_e32 v235, s22, v144
	v_add_u32_e32 v236, s22, v146
	v_add_u32_e32 v237, 0x10000, v158
.LBB0_238:
	s_add_u32 s30, s20, 0x100
	s_addc_u32 s31, s21, 0
	s_add_i32 s54, 0, 0x10000
	s_cmp_eq_u32 s62, 28
	s_cselect_b32 s47, s8, s31
	s_cselect_b32 s46, s9, s30
	s_cselect_b32 s45, s10, s57
	s_cselect_b32 s44, s11, s13
	s_add_i32 s55, 0, 0x14000
	ds_read_b128 v[18:21], v237 offset:0
	ds_read_b128 v[22:25], v237 offset:1024
	ds_read_b128 v[160:163], v237 offset:2048
	ds_read_b128 v[164:167], v237 offset:3072
	ds_read_b128 v[168:171], v237 offset:16384
	ds_read_b128 v[172:175], v237 offset:17408
	ds_read_b128 v[176:179], v237 offset:18432
	ds_read_b128 v[180:183], v237 offset:19456
	s_add_i32 m0, s77, 0xc000
	ds_read_b128 v[184:187], v159
	ds_read_b128 v[188:191], v159 offset:1024
	ds_read_b128 v[210:213], v159 offset:2048
	ds_read_b128 v[214:217], v159 offset:3072
	ds_read_b128 v[218:221], v159 offset:4096
	ds_read_b128 v[222:225], v159 offset:5120
	ds_read_b128 v[226:229], v159 offset:6144
	ds_read_b128 v[230:233], v159 offset:7168
	global_load_lds_dwordx4 v148, s[20:21]
	s_add_i32 m0, s77, 0xe000
	s_nop 0
	global_load_lds_dwordx4 v150, s[20:21]
	s_waitcnt vmcnt(8)
	s_waitcnt lgkmcnt(0)
	s_setprio 1
	s_barrier
	v_mfma_f32_16x16x32_bf16 v[136:139], v[18:21], v[184:187], v[136:139]
	v_mfma_f32_16x16x32_bf16 v[132:135], v[160:163], v[184:187], v[132:135]
	v_mfma_f32_16x16x32_bf16 v[120:123], v[18:21], v[210:213], v[120:123]
	v_mfma_f32_16x16x32_bf16 v[116:119], v[160:163], v[210:213], v[116:119]
	v_mfma_f32_16x16x32_bf16 v[104:107], v[18:21], v[218:221], v[104:107]
	v_mfma_f32_16x16x32_bf16 v[100:103], v[160:163], v[218:221], v[100:103]
	v_mfma_f32_16x16x32_bf16 v[86:89], v[18:21], v[226:229], v[86:89]
	v_mfma_f32_16x16x32_bf16 v[82:85], v[160:163], v[226:229], v[82:85]
	v_mfma_f32_16x16x32_bf16 v[136:139], v[22:25], v[188:191], v[136:139]
	v_mfma_f32_16x16x32_bf16 v[132:135], v[164:167], v[188:191], v[132:135]
	v_mfma_f32_16x16x32_bf16 v[120:123], v[22:25], v[214:217], v[120:123]
	v_mfma_f32_16x16x32_bf16 v[116:119], v[164:167], v[214:217], v[116:119]
	v_mfma_f32_16x16x32_bf16 v[104:107], v[22:25], v[222:225], v[104:107]
	v_mfma_f32_16x16x32_bf16 v[100:103], v[164:167], v[222:225], v[100:103]
	v_mfma_f32_16x16x32_bf16 v[86:89], v[22:25], v[230:233], v[86:89]
	v_mfma_f32_16x16x32_bf16 v[82:85], v[164:167], v[230:233], v[82:85]
	s_setprio 0
	s_setprio 1
	v_mfma_f32_16x16x32_bf16 v[128:131], v[168:171], v[184:187], v[128:131]
	v_mfma_f32_16x16x32_bf16 v[124:127], v[176:179], v[184:187], v[124:127]
	v_mfma_f32_16x16x32_bf16 v[112:115], v[168:171], v[210:213], v[112:115]
	v_mfma_f32_16x16x32_bf16 v[108:111], v[176:179], v[210:213], v[108:111]
	v_mfma_f32_16x16x32_bf16 v[96:99], v[168:171], v[218:221], v[96:99]
	v_mfma_f32_16x16x32_bf16 v[92:95], v[176:179], v[218:221], v[92:95]
	v_mfma_f32_16x16x32_bf16 v[78:81], v[168:171], v[226:229], v[78:81]
	v_mfma_f32_16x16x32_bf16 v[74:77], v[176:179], v[226:229], v[74:77]
	v_mfma_f32_16x16x32_bf16 v[128:131], v[172:175], v[188:191], v[128:131]
	v_mfma_f32_16x16x32_bf16 v[124:127], v[180:183], v[188:191], v[124:127]
	v_mfma_f32_16x16x32_bf16 v[112:115], v[172:175], v[214:217], v[112:115]
	v_mfma_f32_16x16x32_bf16 v[108:111], v[180:183], v[214:217], v[108:111]
	v_mfma_f32_16x16x32_bf16 v[96:99], v[172:175], v[222:225], v[96:99]
	v_mfma_f32_16x16x32_bf16 v[92:95], v[180:183], v[222:225], v[92:95]
	v_mfma_f32_16x16x32_bf16 v[78:81], v[172:175], v[230:233], v[78:81]
	v_mfma_f32_16x16x32_bf16 v[74:77], v[180:183], v[230:233], v[74:77]
	s_barrier
	s_setprio 0
	s_add_i32 s20, s54, s29
	s_mov_b32 m0, s20
	ds_read_b128 v[184:187], v159 offset:16384
	ds_read_b128 v[188:191], v159 offset:17408
	ds_read_b128 v[210:213], v159 offset:18432
	ds_read_b128 v[214:217], v159 offset:19456
	ds_read_b128 v[218:221], v159 offset:20480
	ds_read_b128 v[222:225], v159 offset:21504
	ds_read_b128 v[226:229], v159 offset:22528
	ds_read_b128 v[230:233], v159 offset:23552
	global_load_lds_dwordx4 v142, s[44:45]
	s_add_i32 m0, s20, 0x2000
	s_add_u32 s20, s44, 0x80000
	s_addc_u32 s21, s45, 0
	s_add_i32 s54, s55, s29
	global_load_lds_dwordx4 v146, s[44:45]
	s_mov_b32 m0, s54
	s_nop 0
	global_load_lds_dwordx4 v142, s[20:21]
	s_add_i32 m0, s54, 0x2000
	s_nop 0
	global_load_lds_dwordx4 v146, s[20:21]
	s_mov_b32 m0, s77
	s_nop 0
	global_load_lds_dwordx4 v140, s[46:47]
	s_mov_b32 m0, s49
	s_nop 0
	global_load_lds_dwordx4 v144, s[46:47]
	s_waitcnt vmcnt(8)
	s_waitcnt lgkmcnt(0)
	s_setprio 1
	s_barrier
; #define PG8_STAGE(bufoff, gbase, voff) do { _Pragma("unroll") for (int _i = 0; _i < 2; ++_i) \
;         __builtin_amdgcn_global_load_lds((const unsigned*)((const char*)(gbase) + (voff)[_i]), (PG8_LAS unsigned*)(lds + (bufoff) + ldsw + _i * 8192), 16, 0, 0); } while (0)
; #define PG8_LDA(dst, b, h) do { _Pragma("unroll") for (int m = 0; m < 4; ++m) _Pragma("unroll") for (int k = 0; k < 2; ++k) dst[m][k] = *(const PG8_LAS bf16x8*)(lds + PG8_SA(b, h) + aoff + m * 2048 + k * 1024); } while (0)
; #define PG8_LDB(dst, b, h) do { _Pragma("unroll") for (int n = 0; n < 2; ++n) _Pragma("unroll") for (int k = 0; k < 2; ++k) dst[n][k] = *(const PG8_LAS bf16x8*)(lds + PG8_SB(b, h) + boff + n * 2048 + k * 1024); } while (0)
; #define PG8_MMA(ai, bj, At, Bt) do { __builtin_amdgcn_s_setprio(1); _Pragma("unroll") for (int m = 0; m < 4; ++m) _Pragma("unroll") for (int n = 0; n < 2; ++n) _Pragma("unroll") for (int k = 0; k < 2; ++k) \
;         acc[ai][bj][m][n] = __builtin_amdgcn_mfma_f32_16x16x32_bf16(Bt[n][k], At[m][k], acc[ai][bj][m][n], 0, 0, 0); __builtin_amdgcn_s_setprio(0); } while (0)
; #define PG8_WAIT_V(n) asm volatile("s_waitcnt vmcnt(" #n ")" ::: "memory")
; #define PG8_WAIT_L(n) asm volatile("s_waitcnt lgkmcnt(" #n ")" ::: "memory")
; #define PG8_BAR __builtin_amdgcn_s_barrier()
; #define PG8_SCHED __builtin_amdgcn_sched_barrier(0)
; template <class Epi>
; __device__ __forceinline__ void gemm_phase(PG8_LAS unsigned char* lds, PG8_LAS unsigned char* xl, const Gemm g, const Sched& S, const Epi& E, const int wid) {
;     ...
;             PG8_WAIT_V(8); PG8_WAIT_L(0); PG8_BAR; if (do1) { PG8_MMA(1, 0, At, B0); PG8_MMA(1, 1, At, B1); } PG8_BAR; PG8_SCHED;
;             PG8_LDB(B0, 1, 0); PG8_LDB(B1, 1, 1); PG8_SCHED; PG8_LDA(At, 1, 0); PG8_STAGE(PG8_SA(0, 1), a2 + hstepA, voffA);
;             PG8_WAIT_V(8); PG8_WAIT_L(0); PG8_BAR; if (do0) { PG8_MMA(0, 0, At, B0); PG8_MMA(0, 1, At, B1); } PG8_BAR; PG8_SCHED;
	v_mfma_f32_16x16x32_bf16 v[70:73], v[18:21], v[184:187], v[70:73]
	v_mfma_f32_16x16x32_bf16 v[66:69], v[160:163], v[184:187], v[66:69]
	v_mfma_f32_16x16x32_bf16 v[54:57], v[18:21], v[210:213], v[54:57]
	v_mfma_f32_16x16x32_bf16 v[50:53], v[160:163], v[210:213], v[50:53]
	v_mfma_f32_16x16x32_bf16 v[38:41], v[18:21], v[218:221], v[38:41]
	v_mfma_f32_16x16x32_bf16 v[34:37], v[160:163], v[218:221], v[34:37]
	v_mfma_f32_16x16x32_bf16 v[12:15], v[18:21], v[226:229], v[12:15]
	v_mfma_f32_16x16x32_bf16 v[8:11], v[160:163], v[226:229], v[8:11]
	v_mfma_f32_16x16x32_bf16 v[70:73], v[22:25], v[188:191], v[70:73]
	v_mfma_f32_16x16x32_bf16 v[66:69], v[164:167], v[188:191], v[66:69]
	v_mfma_f32_16x16x32_bf16 v[54:57], v[22:25], v[214:217], v[54:57]
	v_mfma_f32_16x16x32_bf16 v[50:53], v[164:167], v[214:217], v[50:53]
	v_mfma_f32_16x16x32_bf16 v[38:41], v[22:25], v[222:225], v[38:41]
	v_mfma_f32_16x16x32_bf16 v[34:37], v[164:167], v[222:225], v[34:37]
	v_mfma_f32_16x16x32_bf16 v[12:15], v[22:25], v[230:233], v[12:15]
	v_mfma_f32_16x16x32_bf16 v[8:11], v[164:167], v[230:233], v[8:11]
	s_setprio 0
	s_setprio 1
	v_mfma_f32_16x16x32_bf16 v[46:49], v[168:171], v[210:213], v[46:49]
	v_mfma_f32_16x16x32_bf16 v[42:45], v[176:179], v[210:213], v[42:45]
	v_mfma_f32_16x16x32_bf16 v[30:33], v[168:171], v[218:221], v[30:33]
	v_mfma_f32_16x16x32_bf16 v[26:29], v[176:179], v[218:221], v[26:29]
	v_mfma_f32_16x16x32_bf16 v[4:7], v[168:171], v[226:229], v[4:7]
	v_mfma_f32_16x16x32_bf16 v[0:3], v[176:179], v[226:229], v[0:3]
	v_mfma_f32_16x16x32_bf16 v[18:21], v[168:171], v[184:187], v[62:65]
	v_mfma_f32_16x16x32_bf16 v[22:25], v[176:179], v[184:187], v[58:61]
	v_mfma_f32_16x16x32_bf16 v[46:49], v[172:175], v[214:217], v[46:49]
	v_mfma_f32_16x16x32_bf16 v[42:45], v[180:183], v[214:217], v[42:45]
	v_mfma_f32_16x16x32_bf16 v[30:33], v[172:175], v[222:225], v[30:33]
	v_mfma_f32_16x16x32_bf16 v[26:29], v[180:183], v[222:225], v[26:29]
	v_mfma_f32_16x16x32_bf16 v[4:7], v[172:175], v[230:233], v[4:7]
	v_mfma_f32_16x16x32_bf16 v[0:3], v[180:183], v[230:233], v[0:3]
	v_mfma_f32_16x16x32_bf16 v[18:21], v[172:175], v[188:191], v[18:21]
	v_mfma_f32_16x16x32_bf16 v[22:25], v[180:183], v[188:191], v[22:25]
	s_barrier
	s_setprio 0
	s_add_i32 s54, 0, 0x18000
	s_add_i32 s55, 0, 0x1c000
	ds_read_b128 v[58:61], v237 offset:32768
	ds_read_b128 v[62:65], v237 offset:33792
	ds_read_b128 v[160:163], v237 offset:34816
	ds_read_b128 v[164:167], v237 offset:35840
	ds_read_b128 v[168:171], v237 offset:49152
	ds_read_b128 v[172:175], v237 offset:50176
	ds_read_b128 v[176:179], v237 offset:51200
	ds_read_b128 v[180:183], v237 offset:52224
	s_add_u32 s20, s46, 0x80000
	s_addc_u32 s21, s47, 0
	s_mov_b32 m0, s87
	ds_read_b128 v[184:187], v159 offset:32768
	ds_read_b128 v[188:191], v159 offset:33792
	ds_read_b128 v[210:213], v159 offset:34816
	ds_read_b128 v[214:217], v159 offset:35840
	ds_read_b128 v[218:221], v159 offset:36864
	ds_read_b128 v[222:225], v159 offset:37888
	ds_read_b128 v[226:229], v159 offset:38912
	ds_read_b128 v[230:233], v159 offset:39936
	global_load_lds_dwordx4 v140, s[20:21]
	s_mov_b32 m0, s88
	s_nop 0
	global_load_lds_dwordx4 v144, s[20:21]
	s_waitcnt vmcnt(8)
	s_waitcnt lgkmcnt(0)
	s_setprio 1
	s_barrier
	v_mfma_f32_16x16x32_bf16 v[136:139], v[58:61], v[184:187], v[136:139]
	v_mfma_f32_16x16x32_bf16 v[132:135], v[160:163], v[184:187], v[132:135]
	v_mfma_f32_16x16x32_bf16 v[120:123], v[58:61], v[210:213], v[120:123]
	v_mfma_f32_16x16x32_bf16 v[116:119], v[160:163], v[210:213], v[116:119]
	v_mfma_f32_16x16x32_bf16 v[104:107], v[58:61], v[218:221], v[104:107]
	v_mfma_f32_16x16x32_bf16 v[100:103], v[160:163], v[218:221], v[100:103]
	v_mfma_f32_16x16x32_bf16 v[86:89], v[58:61], v[226:229], v[86:89]
	v_mfma_f32_16x16x32_bf16 v[82:85], v[160:163], v[226:229], v[82:85]
	v_mfma_f32_16x16x32_bf16 v[136:139], v[62:65], v[188:191], v[136:139]
	v_mfma_f32_16x16x32_bf16 v[132:135], v[164:167], v[188:191], v[132:135]
	v_mfma_f32_16x16x32_bf16 v[120:123], v[62:65], v[214:217], v[120:123]
	v_mfma_f32_16x16x32_bf16 v[116:119], v[164:167], v[214:217], v[116:119]
	v_mfma_f32_16x16x32_bf16 v[104:107], v[62:65], v[222:225], v[104:107]
	v_mfma_f32_16x16x32_bf16 v[100:103], v[164:167], v[222:225], v[100:103]
	v_mfma_f32_16x16x32_bf16 v[86:89], v[62:65], v[230:233], v[86:89]
	v_mfma_f32_16x16x32_bf16 v[82:85], v[164:167], v[230:233], v[82:85]
	s_setprio 0
	s_setprio 1
	v_mfma_f32_16x16x32_bf16 v[128:131], v[168:171], v[184:187], v[128:131]
	v_mfma_f32_16x16x32_bf16 v[124:127], v[176:179], v[184:187], v[124:127]
	v_mfma_f32_16x16x32_bf16 v[112:115], v[168:171], v[210:213], v[112:115]
	v_mfma_f32_16x16x32_bf16 v[108:111], v[176:179], v[210:213], v[108:111]
	v_mfma_f32_16x16x32_bf16 v[96:99], v[168:171], v[218:221], v[96:99]
	v_mfma_f32_16x16x32_bf16 v[92:95], v[176:179], v[218:221], v[92:95]
	v_mfma_f32_16x16x32_bf16 v[78:81], v[168:171], v[226:229], v[78:81]
	v_mfma_f32_16x16x32_bf16 v[74:77], v[176:179], v[226:229], v[74:77]
	v_mfma_f32_16x16x32_bf16 v[128:131], v[172:175], v[188:191], v[128:131]
	v_mfma_f32_16x16x32_bf16 v[124:127], v[180:183], v[188:191], v[124:127]
	v_mfma_f32_16x16x32_bf16 v[112:115], v[172:175], v[214:217], v[112:115]
	v_mfma_f32_16x16x32_bf16 v[108:111], v[180:183], v[214:217], v[108:111]
	v_mfma_f32_16x16x32_bf16 v[96:99], v[172:175], v[222:225], v[96:99]
	v_mfma_f32_16x16x32_bf16 v[92:95], v[180:183], v[222:225], v[92:95]
	v_mfma_f32_16x16x32_bf16 v[78:81], v[172:175], v[230:233], v[78:81]
	v_mfma_f32_16x16x32_bf16 v[74:77], v[180:183], v[230:233], v[74:77]
	s_barrier
; #define PG8_STAGE(bufoff, gbase, voff) do { _Pragma("unroll") for (int _i = 0; _i < 2; ++_i) \
;         __builtin_amdgcn_global_load_lds((const unsigned*)((const char*)(gbase) + (voff)[_i]), (PG8_LAS unsigned*)(lds + (bufoff) + ldsw + _i * 8192), 16, 0, 0); } while (0)
; #define PG8_LDA(dst, b, h) do { _Pragma("unroll") for (int m = 0; m < 4; ++m) _Pragma("unroll") for (int k = 0; k < 2; ++k) dst[m][k] = *(const PG8_LAS bf16x8*)(lds + PG8_SA(b, h) + aoff + m * 2048 + k * 1024); } while (0)
; #define PG8_MMA(ai, bj, At, Bt) do { __builtin_amdgcn_s_setprio(1); _Pragma("unroll") for (int m = 0; m < 4; ++m) _Pragma("unroll") for (int n = 0; n < 2; ++n) _Pragma("unroll") for (int k = 0; k < 2; ++k) \
;         acc[ai][bj][m][n] = __builtin_amdgcn_mfma_f32_16x16x32_bf16(Bt[n][k], At[m][k], acc[ai][bj][m][n], 0, 0, 0); __builtin_amdgcn_s_setprio(0); } while (0)
; #define PG8_WAIT_V(n) asm volatile("s_waitcnt vmcnt(" #n ")" ::: "memory")
; #define PG8_WAIT_L(n) asm volatile("s_waitcnt lgkmcnt(" #n ")" ::: "memory")
; #define PG8_BAR __builtin_amdgcn_s_barrier()
; #define PG8_SCHED __builtin_amdgcn_sched_barrier(0)
; template <class Epi>
; __device__ __forceinline__ void gemm_phase(PG8_LAS unsigned char* lds, PG8_LAS unsigned char* xl, const Gemm g, const Sched& S, const Epi& E, const int wid) {
;     ...
;             PG8_LDA(At, 1, 1); PG8_STAGE(PG8_SB(1, 0), b3, voffB); PG8_STAGE(PG8_SB(1, 1), b3 + hstepB, voffB); PG8_STAGE(PG8_SA(1, 0), a3, voffA);
;             PG8_WAIT_V(8); PG8_WAIT_L(0); PG8_BAR; if (do1) { PG8_MMA(1, 0, At, B0); PG8_MMA(1, 1, At, B1); } PG8_BAR; PG8_SCHED;
;         }
	s_setprio 0
	s_add_i32 s20, s54, s29
	s_mov_b32 m0, s20
	ds_read_b128 v[184:187], v159 offset:49152
	ds_read_b128 v[188:191], v159 offset:50176
	ds_read_b128 v[210:213], v159 offset:51200
	ds_read_b128 v[214:217], v159 offset:52224
	ds_read_b128 v[218:221], v159 offset:53248
	ds_read_b128 v[222:225], v159 offset:54272
	ds_read_b128 v[226:229], v159 offset:55296
	ds_read_b128 v[230:233], v159 offset:56320
	global_load_lds_dwordx4 v234, s[44:45]
	s_add_i32 m0, s20, 0x2000
	s_add_u32 s20, s44, 0x80080
	global_load_lds_dwordx4 v236, s[44:45]
	s_addc_u32 s21, s45, 0
	s_add_i32 s44, s55, s29
	s_mov_b32 m0, s44
	s_nop 0
	global_load_lds_dwordx4 v142, s[20:21]
	s_add_i32 m0, s44, 0x2000
	s_nop 0
	global_load_lds_dwordx4 v146, s[20:21]
	s_mov_b32 m0, s91
	s_nop 0
	global_load_lds_dwordx4 v157, s[46:47]
	s_mov_b32 m0, s92
	s_nop 0
	global_load_lds_dwordx4 v235, s[46:47]
	s_waitcnt vmcnt(8)
	s_waitcnt lgkmcnt(0)
	s_setprio 1
	s_barrier
	v_mfma_f32_16x16x32_bf16 v[70:73], v[58:61], v[184:187], v[70:73]
	v_mfma_f32_16x16x32_bf16 v[66:69], v[160:163], v[184:187], v[66:69]
	v_mfma_f32_16x16x32_bf16 v[54:57], v[58:61], v[210:213], v[54:57]
	v_mfma_f32_16x16x32_bf16 v[50:53], v[160:163], v[210:213], v[50:53]
	v_mfma_f32_16x16x32_bf16 v[38:41], v[58:61], v[218:221], v[38:41]
	v_mfma_f32_16x16x32_bf16 v[34:37], v[160:163], v[218:221], v[34:37]
	v_mfma_f32_16x16x32_bf16 v[12:15], v[58:61], v[226:229], v[12:15]
	v_mfma_f32_16x16x32_bf16 v[8:11], v[160:163], v[226:229], v[8:11]
	v_mfma_f32_16x16x32_bf16 v[70:73], v[62:65], v[188:191], v[70:73]
	v_mfma_f32_16x16x32_bf16 v[66:69], v[164:167], v[188:191], v[66:69]
	v_mfma_f32_16x16x32_bf16 v[54:57], v[62:65], v[214:217], v[54:57]
	v_mfma_f32_16x16x32_bf16 v[50:53], v[164:167], v[214:217], v[50:53]
	v_mfma_f32_16x16x32_bf16 v[38:41], v[62:65], v[222:225], v[38:41]
	v_mfma_f32_16x16x32_bf16 v[34:37], v[164:167], v[222:225], v[34:37]
	v_mfma_f32_16x16x32_bf16 v[12:15], v[62:65], v[230:233], v[12:15]
	v_mfma_f32_16x16x32_bf16 v[8:11], v[164:167], v[230:233], v[8:11]
	s_setprio 0
	s_setprio 1
	v_mfma_f32_16x16x32_bf16 v[18:21], v[168:171], v[184:187], v[18:21]
	v_mfma_f32_16x16x32_bf16 v[62:65], v[172:175], v[188:191], v[18:21]
	v_mfma_f32_16x16x32_bf16 v[18:21], v[176:179], v[184:187], v[22:25]
	v_mfma_f32_16x16x32_bf16 v[58:61], v[180:183], v[188:191], v[18:21]
	v_mfma_f32_16x16x32_bf16 v[18:21], v[168:171], v[210:213], v[46:49]
	v_mfma_f32_16x16x32_bf16 v[46:49], v[172:175], v[214:217], v[18:21]
	v_mfma_f32_16x16x32_bf16 v[18:21], v[176:179], v[210:213], v[42:45]
	v_mfma_f32_16x16x32_bf16 v[42:45], v[180:183], v[214:217], v[18:21]
	v_mfma_f32_16x16x32_bf16 v[18:21], v[168:171], v[218:221], v[30:33]
	v_mfma_f32_16x16x32_bf16 v[30:33], v[172:175], v[222:225], v[18:21]
	v_mfma_f32_16x16x32_bf16 v[18:21], v[176:179], v[218:221], v[26:29]
	v_mfma_f32_16x16x32_bf16 v[4:7], v[168:171], v[226:229], v[4:7]
	v_mfma_f32_16x16x32_bf16 v[0:3], v[176:179], v[226:229], v[0:3]
	v_mfma_f32_16x16x32_bf16 v[26:29], v[180:183], v[222:225], v[18:21]
	v_mfma_f32_16x16x32_bf16 v[4:7], v[172:175], v[230:233], v[4:7]
	v_mfma_f32_16x16x32_bf16 v[0:3], v[180:183], v[230:233], v[0:3]
	s_barrier
	s_setprio 0
	s_add_i32 s62, s62, 2
	s_add_u32 s13, s13, 0x100
	s_addc_u32 s57, s57, 0
	s_cmp_gt_u32 s62, 29
	s_mov_b64 s[20:21], s[30:31]
	s_cbranch_scc0 .LBB0_238
	s_and_b64 vcc, exec, s[14:15]
	s_cbranch_vccz .LBB0_241
	s_barrier

; #define PG8_STAGE(bufoff, gbase, voff) do { _Pragma("unroll") for (int _i = 0; _i < 2; ++_i) \
;         __builtin_amdgcn_global_load_lds((const unsigned*)((const char*)(gbase) + (voff)[_i]), (PG8_LAS unsigned*)(lds + (bufoff) + ldsw + _i * 8192), 16, 0, 0); } while (0)
; #define PG8_LDA(dst, b, h) do { _Pragma("unroll") for (int m = 0; m < 4; ++m) _Pragma("unroll") for (int k = 0; k < 2; ++k) dst[m][k] = *(const PG8_LAS bf16x8*)(lds + PG8_SA(b, h) + aoff + m * 2048 + k * 1024); } while (0)
; #define PG8_LDB(dst, b, h) do { _Pragma("unroll") for (int n = 0; n < 2; ++n) _Pragma("unroll") for (int k = 0; k < 2; ++k) dst[n][k] = *(const PG8_LAS bf16x8*)(lds + PG8_SB(b, h) + boff + n * 2048 + k * 1024); } while (0)
; #define PG8_MMA(ai, bj, At, Bt) do { __builtin_amdgcn_s_setprio(1); _Pragma("unroll") for (int m = 0; m < 4; ++m) _Pragma("unroll") for (int n = 0; n < 2; ++n) _Pragma("unroll") for (int k = 0; k < 2; ++k) \
;         acc[ai][bj][m][n] = __builtin_amdgcn_mfma_f32_16x16x32_bf16(Bt[n][k], At[m][k], acc[ai][bj][m][n], 0, 0, 0); __builtin_amdgcn_s_setprio(0); } while (0)
; #define PG8_WAIT_V(n) asm volatile("s_waitcnt vmcnt(" #n ")" ::: "memory")
; #define PG8_WAIT_L(n) asm volatile("s_waitcnt lgkmcnt(" #n ")" ::: "memory")
; #define PG8_BAR __builtin_amdgcn_s_barrier()
; #define PG8_SCHED __builtin_amdgcn_sched_barrier(0)
; template <class Epi>
; __device__ __forceinline__ void gemm_phase(PG8_LAS unsigned char* lds, PG8_LAS unsigned char* xl, const Gemm g, const Sched& S, const Epi& E, const int wid) {
;     ...
;             const char* a1 = cA + (size_t)(t + 1) * kstep + j1;
;             const char* a2 = last ? nA : cA + (size_t)(t + 2) * kstep + ja2; const char* b2 = last ? nB : cB + (size_t)(t + 2) * kstep + jb2;
;             const char* a3 = a2 + kstep; const char* b3 = b2 + kstep;
;             PG8_LDB(B0, 0, 0); PG8_LDB(B1, 0, 1); PG8_SCHED; PG8_LDA(At, 0, 0); PG8_STAGE(PG8_SA(1, 1), a1 + hstepA, voffA);
;             PG8_WAIT_V(8); PG8_WAIT_L(0); PG8_BAR; if (do0) { PG8_MMA(0, 0, At, B0); PG8_MMA(0, 1, At, B1); } PG8_BAR; PG8_SCHED;
;             PG8_LDA(At, 0, 1); PG8_STAGE(PG8_SB(0, 0), b2, voffB); PG8_STAGE(PG8_SB(0, 1), b2 + hstepB, voffB); PG8_STAGE(PG8_SA(0, 0), a2, voffA);
.Ldefbar_skip_2:
	v_add_u32_e32 v190, s22, v128
	v_add_u32_e32 v191, s22, v130
	v_add_u32_e32 v226, s22, v132
	v_add_u32_e32 v227, s22, v134
	v_add_u32_e32 v228, 0x10000, v140
.LBB0_408:
	s_add_u32 s76, s60, 0x100
	s_addc_u32 s77, s61, 0
	s_add_i32 s11, 0, 0x10000
	s_cmp_eq_u32 s10, 4
	s_cselect_b32 s41, s47, s77
	s_cselect_b32 s40, s46, s76
	s_cselect_b32 vcc_hi, s59, s9
	s_cselect_b32 vcc_lo, s58, s8
	s_add_i32 s21, 0, 0x14000
	ds_read_b128 v[142:145], v228 offset:0
	ds_read_b128 v[146:149], v228 offset:1024
	ds_read_b128 v[150:153], v228 offset:2048
	ds_read_b128 v[154:157], v228 offset:3072
	ds_read_b128 v[158:161], v228 offset:16384
	ds_read_b128 v[162:165], v228 offset:17408
	ds_read_b128 v[166:169], v228 offset:18432
	ds_read_b128 v[170:173], v228 offset:19456
	s_add_i32 m0, s13, 0xc000
	ds_read_b128 v[174:177], v141
	ds_read_b128 v[178:181], v141 offset:1024
	ds_read_b128 v[182:185], v141 offset:2048
	ds_read_b128 v[186:189], v141 offset:3072
	ds_read_b128 v[210:213], v141 offset:4096
	ds_read_b128 v[214:217], v141 offset:5120
	ds_read_b128 v[218:221], v141 offset:6144
	ds_read_b128 v[222:225], v141 offset:7168
	global_load_lds_dwordx4 v136, s[60:61]
	s_add_i32 m0, s13, 0xe000
	s_nop 0
	global_load_lds_dwordx4 v138, s[60:61]
	s_waitcnt vmcnt(8)
	s_waitcnt lgkmcnt(0)
	s_setprio 1
	s_barrier
	v_mfma_f32_16x16x32_bf16 v[124:127], v[142:145], v[174:177], v[124:127]
	v_mfma_f32_16x16x32_bf16 v[120:123], v[150:153], v[174:177], v[120:123]
	v_mfma_f32_16x16x32_bf16 v[116:119], v[142:145], v[182:185], v[116:119]
	v_mfma_f32_16x16x32_bf16 v[108:111], v[150:153], v[182:185], v[108:111]
	v_mfma_f32_16x16x32_bf16 v[100:103], v[142:145], v[210:213], v[100:103]
	v_mfma_f32_16x16x32_bf16 v[92:95], v[150:153], v[210:213], v[92:95]
	v_mfma_f32_16x16x32_bf16 v[84:87], v[142:145], v[218:221], v[84:87]
	v_mfma_f32_16x16x32_bf16 v[76:79], v[150:153], v[218:221], v[76:79]
	v_mfma_f32_16x16x32_bf16 v[124:127], v[146:149], v[178:181], v[124:127]
	v_mfma_f32_16x16x32_bf16 v[120:123], v[154:157], v[178:181], v[120:123]
	v_mfma_f32_16x16x32_bf16 v[116:119], v[146:149], v[186:189], v[116:119]
	v_mfma_f32_16x16x32_bf16 v[108:111], v[154:157], v[186:189], v[108:111]
	v_mfma_f32_16x16x32_bf16 v[100:103], v[146:149], v[214:217], v[100:103]
	v_mfma_f32_16x16x32_bf16 v[92:95], v[154:157], v[214:217], v[92:95]
	v_mfma_f32_16x16x32_bf16 v[84:87], v[146:149], v[222:225], v[84:87]
	v_mfma_f32_16x16x32_bf16 v[76:79], v[154:157], v[222:225], v[76:79]
	s_setprio 0
	s_setprio 1
	v_mfma_f32_16x16x32_bf16 v[112:115], v[158:161], v[174:177], v[112:115]
	v_mfma_f32_16x16x32_bf16 v[104:107], v[166:169], v[174:177], v[104:107]
	v_mfma_f32_16x16x32_bf16 v[96:99], v[158:161], v[182:185], v[96:99]
	v_mfma_f32_16x16x32_bf16 v[88:91], v[166:169], v[182:185], v[88:91]
	v_mfma_f32_16x16x32_bf16 v[80:83], v[158:161], v[210:213], v[80:83]
	v_mfma_f32_16x16x32_bf16 v[72:75], v[166:169], v[210:213], v[72:75]
	v_mfma_f32_16x16x32_bf16 v[68:71], v[158:161], v[218:221], v[68:71]
	v_mfma_f32_16x16x32_bf16 v[64:67], v[166:169], v[218:221], v[64:67]
	v_mfma_f32_16x16x32_bf16 v[112:115], v[162:165], v[178:181], v[112:115]
	v_mfma_f32_16x16x32_bf16 v[104:107], v[170:173], v[178:181], v[104:107]
	v_mfma_f32_16x16x32_bf16 v[96:99], v[162:165], v[186:189], v[96:99]
	v_mfma_f32_16x16x32_bf16 v[88:91], v[170:173], v[186:189], v[88:91]
	v_mfma_f32_16x16x32_bf16 v[80:83], v[162:165], v[214:217], v[80:83]
	v_mfma_f32_16x16x32_bf16 v[72:75], v[170:173], v[214:217], v[72:75]
	v_mfma_f32_16x16x32_bf16 v[68:71], v[162:165], v[222:225], v[68:71]
	v_mfma_f32_16x16x32_bf16 v[64:67], v[170:173], v[222:225], v[64:67]
	s_barrier
	s_setprio 0
	s_add_i32 s11, s11, s29
	s_mov_b32 m0, s11
	ds_read_b128 v[174:177], v141 offset:16384
	ds_read_b128 v[178:181], v141 offset:17408
	ds_read_b128 v[182:185], v141 offset:18432
	ds_read_b128 v[186:189], v141 offset:19456
	ds_read_b128 v[210:213], v141 offset:20480
	ds_read_b128 v[214:217], v141 offset:21504
	ds_read_b128 v[218:221], v141 offset:22528
	ds_read_b128 v[222:225], v141 offset:23552
	global_load_lds_dwordx4 v132, vcc
	s_add_i32 m0, s11, 0x2000
	s_add_u32 s54, vcc_lo, 0x80000
	s_addc_u32 s55, vcc_hi, 0
	s_add_i32 s11, s21, s29
	global_load_lds_dwordx4 v128, vcc
	s_mov_b32 m0, s11
	s_nop 0
	global_load_lds_dwordx4 v132, s[54:55]
	s_add_i32 m0, s11, 0x2000
	s_nop 0
	global_load_lds_dwordx4 v128, s[54:55]
	s_mov_b32 m0, s13
	s_nop 0
	global_load_lds_dwordx4 v134, s[40:41]
	s_mov_b32 m0, s67
	s_nop 0
	global_load_lds_dwordx4 v130, s[40:41]
	s_waitcnt vmcnt(8)
	s_waitcnt lgkmcnt(0)
	s_setprio 1
	s_barrier
; #define PG8_STAGE(bufoff, gbase, voff) do { _Pragma("unroll") for (int _i = 0; _i < 2; ++_i) \
;         __builtin_amdgcn_global_load_lds((const unsigned*)((const char*)(gbase) + (voff)[_i]), (PG8_LAS unsigned*)(lds + (bufoff) + ldsw + _i * 8192), 16, 0, 0); } while (0)
; #define PG8_LDA(dst, b, h) do { _Pragma("unroll") for (int m = 0; m < 4; ++m) _Pragma("unroll") for (int k = 0; k < 2; ++k) dst[m][k] = *(const PG8_LAS bf16x8*)(lds + PG8_SA(b, h) + aoff + m * 2048 + k * 1024); } while (0)
; #define PG8_LDB(dst, b, h) do { _Pragma("unroll") for (int n = 0; n < 2; ++n) _Pragma("unroll") for (int k = 0; k < 2; ++k) dst[n][k] = *(const PG8_LAS bf16x8*)(lds + PG8_SB(b, h) + boff + n * 2048 + k * 1024); } while (0)
; #define PG8_MMA(ai, bj, At, Bt) do { __builtin_amdgcn_s_setprio(1); _Pragma("unroll") for (int m = 0; m < 4; ++m) _Pragma("unroll") for (int n = 0; n < 2; ++n) _Pragma("unroll") for (int k = 0; k < 2; ++k) \
;         acc[ai][bj][m][n] = __builtin_amdgcn_mfma_f32_16x16x32_bf16(Bt[n][k], At[m][k], acc[ai][bj][m][n], 0, 0, 0); __builtin_amdgcn_s_setprio(0); } while (0)
; #define PG8_WAIT_V(n) asm volatile("s_waitcnt vmcnt(" #n ")" ::: "memory")
; #define PG8_WAIT_L(n) asm volatile("s_waitcnt lgkmcnt(" #n ")" ::: "memory")
; #define PG8_BAR __builtin_amdgcn_s_barrier()
; #define PG8_SCHED __builtin_amdgcn_sched_barrier(0)
; template <class Epi>
; __device__ __forceinline__ void gemm_phase(PG8_LAS unsigned char* lds, PG8_LAS unsigned char* xl, const Gemm g, const Sched& S, const Epi& E, const int wid) {
;     ...
;             PG8_WAIT_V(8); PG8_WAIT_L(0); PG8_BAR; if (do1) { PG8_MMA(1, 0, At, B0); PG8_MMA(1, 1, At, B1); } PG8_BAR; PG8_SCHED;
;             PG8_LDB(B0, 1, 0); PG8_LDB(B1, 1, 1); PG8_SCHED; PG8_LDA(At, 1, 0); PG8_STAGE(PG8_SA(0, 1), a2 + hstepA, voffA);
;             PG8_WAIT_V(8); PG8_WAIT_L(0); PG8_BAR; if (do0) { PG8_MMA(0, 0, At, B0); PG8_MMA(0, 1, At, B1); } PG8_BAR; PG8_SCHED;
	v_mfma_f32_16x16x32_bf16 v[60:63], v[142:145], v[174:177], v[60:63]
	v_mfma_f32_16x16x32_bf16 v[56:59], v[150:153], v[174:177], v[56:59]
	v_mfma_f32_16x16x32_bf16 v[52:55], v[142:145], v[182:185], v[52:55]
	v_mfma_f32_16x16x32_bf16 v[44:47], v[150:153], v[182:185], v[44:47]
	v_mfma_f32_16x16x32_bf16 v[36:39], v[142:145], v[210:213], v[36:39]
	v_mfma_f32_16x16x32_bf16 v[28:31], v[150:153], v[210:213], v[28:31]
	v_mfma_f32_16x16x32_bf16 v[20:23], v[142:145], v[218:221], v[20:23]
	v_mfma_f32_16x16x32_bf16 v[12:15], v[150:153], v[218:221], v[12:15]
	v_mfma_f32_16x16x32_bf16 v[60:63], v[146:149], v[178:181], v[60:63]
	v_mfma_f32_16x16x32_bf16 v[56:59], v[154:157], v[178:181], v[56:59]
	v_mfma_f32_16x16x32_bf16 v[52:55], v[146:149], v[186:189], v[52:55]
	v_mfma_f32_16x16x32_bf16 v[44:47], v[154:157], v[186:189], v[44:47]
	v_mfma_f32_16x16x32_bf16 v[36:39], v[146:149], v[214:217], v[36:39]
	v_mfma_f32_16x16x32_bf16 v[28:31], v[154:157], v[214:217], v[28:31]
	v_mfma_f32_16x16x32_bf16 v[20:23], v[146:149], v[222:225], v[20:23]
	v_mfma_f32_16x16x32_bf16 v[12:15], v[154:157], v[222:225], v[12:15]
	s_setprio 0
	s_setprio 1
	v_mfma_f32_16x16x32_bf16 v[48:51], v[158:161], v[174:177], v[48:51]
	v_mfma_f32_16x16x32_bf16 v[40:43], v[166:169], v[174:177], v[40:43]
	v_mfma_f32_16x16x32_bf16 v[32:35], v[158:161], v[182:185], v[32:35]
	v_mfma_f32_16x16x32_bf16 v[24:27], v[166:169], v[182:185], v[24:27]
	v_mfma_f32_16x16x32_bf16 v[16:19], v[158:161], v[210:213], v[16:19]
	v_mfma_f32_16x16x32_bf16 v[8:11], v[166:169], v[210:213], v[8:11]
	v_mfma_f32_16x16x32_bf16 v[4:7], v[158:161], v[218:221], v[4:7]
	v_mfma_f32_16x16x32_bf16 v[0:3], v[166:169], v[218:221], v[0:3]
	v_mfma_f32_16x16x32_bf16 v[48:51], v[162:165], v[178:181], v[48:51]
	v_mfma_f32_16x16x32_bf16 v[40:43], v[170:173], v[178:181], v[40:43]
	v_mfma_f32_16x16x32_bf16 v[32:35], v[162:165], v[186:189], v[32:35]
	v_mfma_f32_16x16x32_bf16 v[24:27], v[170:173], v[186:189], v[24:27]
	v_mfma_f32_16x16x32_bf16 v[16:19], v[162:165], v[214:217], v[16:19]
	v_mfma_f32_16x16x32_bf16 v[8:11], v[170:173], v[214:217], v[8:11]
	v_mfma_f32_16x16x32_bf16 v[4:7], v[162:165], v[222:225], v[4:7]
	v_mfma_f32_16x16x32_bf16 v[0:3], v[170:173], v[222:225], v[0:3]
	s_barrier
	s_setprio 0
	s_add_i32 s11, 0, 0x18000
	s_add_i32 s21, 0, 0x1c000
	ds_read_b128 v[142:145], v228 offset:32768
	ds_read_b128 v[146:149], v228 offset:33792
	ds_read_b128 v[150:153], v228 offset:34816
	ds_read_b128 v[154:157], v228 offset:35840
	ds_read_b128 v[158:161], v228 offset:49152
	ds_read_b128 v[162:165], v228 offset:50176
	ds_read_b128 v[166:169], v228 offset:51200
	ds_read_b128 v[170:173], v228 offset:52224
	s_add_u32 s100, s40, 0x100000
	s_addc_u32 s101, s41, 0
	s_mov_b32 m0, s68
	ds_read_b128 v[174:177], v141 offset:32768
	ds_read_b128 v[178:181], v141 offset:33792
	ds_read_b128 v[182:185], v141 offset:34816
	ds_read_b128 v[186:189], v141 offset:35840
	ds_read_b128 v[210:213], v141 offset:36864
	ds_read_b128 v[214:217], v141 offset:37888
	ds_read_b128 v[218:221], v141 offset:38912
	ds_read_b128 v[222:225], v141 offset:39936
	global_load_lds_dwordx4 v134, s[100:101]
	s_mov_b32 m0, s69
	s_nop 0
	global_load_lds_dwordx4 v130, s[100:101]
	s_waitcnt vmcnt(8)
	s_waitcnt lgkmcnt(0)
	s_setprio 1
	s_barrier
	v_mfma_f32_16x16x32_bf16 v[124:127], v[142:145], v[174:177], v[124:127]
	v_mfma_f32_16x16x32_bf16 v[120:123], v[150:153], v[174:177], v[120:123]
	v_mfma_f32_16x16x32_bf16 v[116:119], v[142:145], v[182:185], v[116:119]
	v_mfma_f32_16x16x32_bf16 v[108:111], v[150:153], v[182:185], v[108:111]
	v_mfma_f32_16x16x32_bf16 v[100:103], v[142:145], v[210:213], v[100:103]
	v_mfma_f32_16x16x32_bf16 v[92:95], v[150:153], v[210:213], v[92:95]
	v_mfma_f32_16x16x32_bf16 v[84:87], v[142:145], v[218:221], v[84:87]
	v_mfma_f32_16x16x32_bf16 v[76:79], v[150:153], v[218:221], v[76:79]
	v_mfma_f32_16x16x32_bf16 v[124:127], v[146:149], v[178:181], v[124:127]
	v_mfma_f32_16x16x32_bf16 v[120:123], v[154:157], v[178:181], v[120:123]
	v_mfma_f32_16x16x32_bf16 v[116:119], v[146:149], v[186:189], v[116:119]
	v_mfma_f32_16x16x32_bf16 v[108:111], v[154:157], v[186:189], v[108:111]
	v_mfma_f32_16x16x32_bf16 v[100:103], v[146:149], v[214:217], v[100:103]
	v_mfma_f32_16x16x32_bf16 v[92:95], v[154:157], v[214:217], v[92:95]
	v_mfma_f32_16x16x32_bf16 v[84:87], v[146:149], v[222:225], v[84:87]
	v_mfma_f32_16x16x32_bf16 v[76:79], v[154:157], v[222:225], v[76:79]
	s_setprio 0
	s_setprio 1
	v_mfma_f32_16x16x32_bf16 v[112:115], v[158:161], v[174:177], v[112:115]
	v_mfma_f32_16x16x32_bf16 v[104:107], v[166:169], v[174:177], v[104:107]
	v_mfma_f32_16x16x32_bf16 v[96:99], v[158:161], v[182:185], v[96:99]
	v_mfma_f32_16x16x32_bf16 v[88:91], v[166:169], v[182:185], v[88:91]
	v_mfma_f32_16x16x32_bf16 v[80:83], v[158:161], v[210:213], v[80:83]
	v_mfma_f32_16x16x32_bf16 v[72:75], v[166:169], v[210:213], v[72:75]
	v_mfma_f32_16x16x32_bf16 v[68:71], v[158:161], v[218:221], v[68:71]
	v_mfma_f32_16x16x32_bf16 v[64:67], v[166:169], v[218:221], v[64:67]
	v_mfma_f32_16x16x32_bf16 v[112:115], v[162:165], v[178:181], v[112:115]
	v_mfma_f32_16x16x32_bf16 v[104:107], v[170:173], v[178:181], v[104:107]
	v_mfma_f32_16x16x32_bf16 v[96:99], v[162:165], v[186:189], v[96:99]
	v_mfma_f32_16x16x32_bf16 v[88:91], v[170:173], v[186:189], v[88:91]
	v_mfma_f32_16x16x32_bf16 v[80:83], v[162:165], v[214:217], v[80:83]
	v_mfma_f32_16x16x32_bf16 v[72:75], v[170:173], v[214:217], v[72:75]
	v_mfma_f32_16x16x32_bf16 v[68:71], v[162:165], v[222:225], v[68:71]
	v_mfma_f32_16x16x32_bf16 v[64:67], v[170:173], v[222:225], v[64:67]
	s_barrier
; #define PG8_STAGE(bufoff, gbase, voff) do { _Pragma("unroll") for (int _i = 0; _i < 2; ++_i) \
;         __builtin_amdgcn_global_load_lds((const unsigned*)((const char*)(gbase) + (voff)[_i]), (PG8_LAS unsigned*)(lds + (bufoff) + ldsw + _i * 8192), 16, 0, 0); } while (0)
; #define PG8_LDA(dst, b, h) do { _Pragma("unroll") for (int m = 0; m < 4; ++m) _Pragma("unroll") for (int k = 0; k < 2; ++k) dst[m][k] = *(const PG8_LAS bf16x8*)(lds + PG8_SA(b, h) + aoff + m * 2048 + k * 1024); } while (0)
; #define PG8_MMA(ai, bj, At, Bt) do { __builtin_amdgcn_s_setprio(1); _Pragma("unroll") for (int m = 0; m < 4; ++m) _Pragma("unroll") for (int n = 0; n < 2; ++n) _Pragma("unroll") for (int k = 0; k < 2; ++k) \
;         acc[ai][bj][m][n] = __builtin_amdgcn_mfma_f32_16x16x32_bf16(Bt[n][k], At[m][k], acc[ai][bj][m][n], 0, 0, 0); __builtin_amdgcn_s_setprio(0); } while (0)
; #define PG8_WAIT_V(n) asm volatile("s_waitcnt vmcnt(" #n ")" ::: "memory")
; #define PG8_WAIT_L(n) asm volatile("s_waitcnt lgkmcnt(" #n ")" ::: "memory")
; #define PG8_BAR __builtin_amdgcn_s_barrier()
; #define PG8_SCHED __builtin_amdgcn_sched_barrier(0)
; template <class Epi>
; __device__ __forceinline__ void gemm_phase(PG8_LAS unsigned char* lds, PG8_LAS unsigned char* xl, const Gemm g, const Sched& S, const Epi& E, const int wid) {
;     ...
;             PG8_LDA(At, 1, 1); PG8_STAGE(PG8_SB(1, 0), b3, voffB); PG8_STAGE(PG8_SB(1, 1), b3 + hstepB, voffB); PG8_STAGE(PG8_SA(1, 0), a3, voffA);
;             PG8_WAIT_V(8); PG8_WAIT_L(0); PG8_BAR; if (do1) { PG8_MMA(1, 0, At, B0); PG8_MMA(1, 1, At, B1); } PG8_BAR; PG8_SCHED;
;         }
	s_setprio 0
	s_add_i32 s11, s11, s29
	s_mov_b32 m0, s11
	ds_read_b128 v[174:177], v141 offset:49152
	ds_read_b128 v[178:181], v141 offset:50176
	ds_read_b128 v[182:185], v141 offset:51200
	ds_read_b128 v[186:189], v141 offset:52224
	ds_read_b128 v[210:213], v141 offset:53248
	ds_read_b128 v[214:217], v141 offset:54272
	ds_read_b128 v[218:221], v141 offset:55296
	ds_read_b128 v[222:225], v141 offset:56320
	global_load_lds_dwordx4 v226, vcc
	s_add_i32 m0, s11, 0x2000
	s_add_u32 s100, vcc_lo, 0x80080
	global_load_lds_dwordx4 v190, vcc
	s_addc_u32 s101, vcc_hi, 0
	s_add_i32 s11, s21, s29
	s_mov_b32 m0, s11
	s_nop 0
	global_load_lds_dwordx4 v132, s[100:101]
	s_add_i32 m0, s11, 0x2000
	s_nop 0
	global_load_lds_dwordx4 v128, s[100:101]
	s_mov_b32 m0, s88
	s_nop 0
	global_load_lds_dwordx4 v227, s[40:41]
	s_mov_b32 m0, s89
	s_nop 0
	global_load_lds_dwordx4 v191, s[40:41]
	s_waitcnt vmcnt(8)
	s_waitcnt lgkmcnt(0)
	s_setprio 1
	s_barrier
	v_mfma_f32_16x16x32_bf16 v[60:63], v[142:145], v[174:177], v[60:63]
	v_mfma_f32_16x16x32_bf16 v[56:59], v[150:153], v[174:177], v[56:59]
	v_mfma_f32_16x16x32_bf16 v[52:55], v[142:145], v[182:185], v[52:55]
	v_mfma_f32_16x16x32_bf16 v[44:47], v[150:153], v[182:185], v[44:47]
	v_mfma_f32_16x16x32_bf16 v[36:39], v[142:145], v[210:213], v[36:39]
	v_mfma_f32_16x16x32_bf16 v[28:31], v[150:153], v[210:213], v[28:31]
	v_mfma_f32_16x16x32_bf16 v[20:23], v[142:145], v[218:221], v[20:23]
	v_mfma_f32_16x16x32_bf16 v[12:15], v[150:153], v[218:221], v[12:15]
	v_mfma_f32_16x16x32_bf16 v[60:63], v[146:149], v[178:181], v[60:63]
	v_mfma_f32_16x16x32_bf16 v[56:59], v[154:157], v[178:181], v[56:59]
	v_mfma_f32_16x16x32_bf16 v[52:55], v[146:149], v[186:189], v[52:55]
	v_mfma_f32_16x16x32_bf16 v[44:47], v[154:157], v[186:189], v[44:47]
	v_mfma_f32_16x16x32_bf16 v[36:39], v[146:149], v[214:217], v[36:39]
	v_mfma_f32_16x16x32_bf16 v[28:31], v[154:157], v[214:217], v[28:31]
	v_mfma_f32_16x16x32_bf16 v[20:23], v[146:149], v[222:225], v[20:23]
	v_mfma_f32_16x16x32_bf16 v[12:15], v[154:157], v[222:225], v[12:15]
	s_setprio 0
	s_setprio 1
	v_mfma_f32_16x16x32_bf16 v[48:51], v[158:161], v[174:177], v[48:51]
	v_mfma_f32_16x16x32_bf16 v[40:43], v[166:169], v[174:177], v[40:43]
	v_mfma_f32_16x16x32_bf16 v[32:35], v[158:161], v[182:185], v[32:35]
	v_mfma_f32_16x16x32_bf16 v[24:27], v[166:169], v[182:185], v[24:27]
	v_mfma_f32_16x16x32_bf16 v[16:19], v[158:161], v[210:213], v[16:19]
	v_mfma_f32_16x16x32_bf16 v[8:11], v[166:169], v[210:213], v[8:11]
	v_mfma_f32_16x16x32_bf16 v[4:7], v[158:161], v[218:221], v[4:7]
	v_mfma_f32_16x16x32_bf16 v[0:3], v[166:169], v[218:221], v[0:3]
	v_mfma_f32_16x16x32_bf16 v[48:51], v[162:165], v[178:181], v[48:51]
	v_mfma_f32_16x16x32_bf16 v[40:43], v[170:173], v[178:181], v[40:43]
	v_mfma_f32_16x16x32_bf16 v[32:35], v[162:165], v[186:189], v[32:35]
	v_mfma_f32_16x16x32_bf16 v[24:27], v[170:173], v[186:189], v[24:27]
	v_mfma_f32_16x16x32_bf16 v[16:19], v[162:165], v[214:217], v[16:19]
	v_mfma_f32_16x16x32_bf16 v[8:11], v[170:173], v[214:217], v[8:11]
	v_mfma_f32_16x16x32_bf16 v[4:7], v[162:165], v[222:225], v[4:7]
	v_mfma_f32_16x16x32_bf16 v[0:3], v[170:173], v[222:225], v[0:3]
	s_barrier
	s_setprio 0
	s_add_i32 s10, s10, 2
	s_add_u32 s8, s8, 0x100
	s_addc_u32 s9, s9, 0
	s_cmp_gt_u32 s10, 5
	s_mov_b64 s[60:61], s[76:77]
	s_cbranch_scc0 .LBB0_408
	s_mov_b32 s100, 0
	s_and_b64 vcc, exec, s[14:15]
	s_cbranch_vccz .LBB0_411
	s_barrier

; #define PG8_STAGE(bufoff, gbase, voff) do { _Pragma("unroll") for (int _i = 0; _i < 2; ++_i) \
;         __builtin_amdgcn_global_load_lds((const unsigned*)((const char*)(gbase) + (voff)[_i]), (PG8_LAS unsigned*)(lds + (bufoff) + ldsw + _i * 8192), 16, 0, 0); } while (0)
; #define PG8_LDA(dst, b, h) do { _Pragma("unroll") for (int m = 0; m < 4; ++m) _Pragma("unroll") for (int k = 0; k < 2; ++k) dst[m][k] = *(const PG8_LAS bf16x8*)(lds + PG8_SA(b, h) + aoff + m * 2048 + k * 1024); } while (0)
; #define PG8_LDB(dst, b, h) do { _Pragma("unroll") for (int n = 0; n < 2; ++n) _Pragma("unroll") for (int k = 0; k < 2; ++k) dst[n][k] = *(const PG8_LAS bf16x8*)(lds + PG8_SB(b, h) + boff + n * 2048 + k * 1024); } while (0)
; #define PG8_MMA(ai, bj, At, Bt) do { __builtin_amdgcn_s_setprio(1); _Pragma("unroll") for (int m = 0; m < 4; ++m) _Pragma("unroll") for (int n = 0; n < 2; ++n) _Pragma("unroll") for (int k = 0; k < 2; ++k) \
;         acc[ai][bj][m][n] = __builtin_amdgcn_mfma_f32_16x16x32_bf16(Bt[n][k], At[m][k], acc[ai][bj][m][n], 0, 0, 0); __builtin_amdgcn_s_setprio(0); } while (0)
; #define PG8_WAIT_V(n) asm volatile("s_waitcnt vmcnt(" #n ")" ::: "memory")
; #define PG8_WAIT_L(n) asm volatile("s_waitcnt lgkmcnt(" #n ")" ::: "memory")
; #define PG8_BAR __builtin_amdgcn_s_barrier()
; #define PG8_SCHED __builtin_amdgcn_sched_barrier(0)
; template <class Epi>
; __device__ __forceinline__ void gemm_phase(PG8_LAS unsigned char* lds, PG8_LAS unsigned char* xl, const Gemm g, const Sched& S, const Epi& E, const int wid) {
;     ...
;             const char* a1 = cA + (size_t)(t + 1) * kstep + j1;
;             const char* a2 = last ? nA : cA + (size_t)(t + 2) * kstep + ja2; const char* b2 = last ? nB : cB + (size_t)(t + 2) * kstep + jb2;
;             const char* a3 = a2 + kstep; const char* b3 = b2 + kstep;
;             PG8_LDB(B0, 0, 0); PG8_LDB(B1, 0, 1); PG8_SCHED; PG8_LDA(At, 0, 0); PG8_STAGE(PG8_SA(1, 1), a1 + hstepA, voffA);
;             PG8_WAIT_V(8); PG8_WAIT_L(0); PG8_BAR; if (do0) { PG8_MMA(0, 0, At, B0); PG8_MMA(0, 1, At, B1); } PG8_BAR; PG8_SCHED;
;             PG8_LDA(At, 0, 1); PG8_STAGE(PG8_SB(0, 0), b2, voffB); PG8_STAGE(PG8_SB(0, 1), b2 + hstepB, voffB); PG8_STAGE(PG8_SA(0, 0), a2, voffA);
;             PG8_WAIT_V(8); PG8_WAIT_L(0); PG8_BAR; if (do1) { PG8_MMA(1, 0, At, B0); PG8_MMA(1, 1, At, B1); } PG8_BAR; PG8_SCHED;
.LBB0_428:
	s_add_u32 s60, s58, 0x100
	s_addc_u32 s61, s59, 0
	s_add_i32 s11, 0, 0x10000
	s_cmp_eq_u32 s10, 4
	s_cselect_b32 s41, s47, s61
	s_cselect_b32 s40, s46, s60
	s_cselect_b32 s77, s57, s9
	s_cselect_b32 s76, s56, s8
	s_add_i32 s21, 0, 0x14000
	ds_read_b128 v[142:145], v228 offset:0
	ds_read_b128 v[146:149], v228 offset:1024
	ds_read_b128 v[150:153], v228 offset:2048
	ds_read_b128 v[154:157], v228 offset:3072
	ds_read_b128 v[158:161], v228 offset:16384
	ds_read_b128 v[162:165], v228 offset:17408
	ds_read_b128 v[166:169], v228 offset:18432
	ds_read_b128 v[170:173], v228 offset:19456
	s_add_i32 m0, s13, 0xc000
	ds_read_b128 v[174:177], v141
	ds_read_b128 v[178:181], v141 offset:1024
	ds_read_b128 v[182:185], v141 offset:2048
	ds_read_b128 v[186:189], v141 offset:3072
	ds_read_b128 v[210:213], v141 offset:4096
	ds_read_b128 v[214:217], v141 offset:5120
	ds_read_b128 v[218:221], v141 offset:6144
	ds_read_b128 v[222:225], v141 offset:7168
	global_load_lds_dwordx4 v136, s[58:59]
	s_add_i32 m0, s13, 0xe000
	s_nop 0
	global_load_lds_dwordx4 v138, s[58:59]
	s_waitcnt vmcnt(8)
	s_waitcnt lgkmcnt(0)
	s_setprio 1
	s_barrier
	v_mfma_f32_16x16x32_bf16 v[124:127], v[142:145], v[174:177], v[124:127]
	v_mfma_f32_16x16x32_bf16 v[120:123], v[150:153], v[174:177], v[120:123]
	v_mfma_f32_16x16x32_bf16 v[116:119], v[142:145], v[182:185], v[116:119]
	v_mfma_f32_16x16x32_bf16 v[108:111], v[150:153], v[182:185], v[108:111]
	v_mfma_f32_16x16x32_bf16 v[100:103], v[142:145], v[210:213], v[100:103]
	v_mfma_f32_16x16x32_bf16 v[92:95], v[150:153], v[210:213], v[92:95]
	v_mfma_f32_16x16x32_bf16 v[84:87], v[142:145], v[218:221], v[84:87]
	v_mfma_f32_16x16x32_bf16 v[76:79], v[150:153], v[218:221], v[76:79]
	v_mfma_f32_16x16x32_bf16 v[124:127], v[146:149], v[178:181], v[124:127]
	v_mfma_f32_16x16x32_bf16 v[120:123], v[154:157], v[178:181], v[120:123]
	v_mfma_f32_16x16x32_bf16 v[116:119], v[146:149], v[186:189], v[116:119]
	v_mfma_f32_16x16x32_bf16 v[108:111], v[154:157], v[186:189], v[108:111]
	v_mfma_f32_16x16x32_bf16 v[100:103], v[146:149], v[214:217], v[100:103]
	v_mfma_f32_16x16x32_bf16 v[92:95], v[154:157], v[214:217], v[92:95]
	v_mfma_f32_16x16x32_bf16 v[84:87], v[146:149], v[222:225], v[84:87]
	v_mfma_f32_16x16x32_bf16 v[76:79], v[154:157], v[222:225], v[76:79]
	s_setprio 0
	s_setprio 1
	v_mfma_f32_16x16x32_bf16 v[112:115], v[158:161], v[174:177], v[112:115]
	v_mfma_f32_16x16x32_bf16 v[104:107], v[166:169], v[174:177], v[104:107]
	v_mfma_f32_16x16x32_bf16 v[96:99], v[158:161], v[182:185], v[96:99]
	v_mfma_f32_16x16x32_bf16 v[88:91], v[166:169], v[182:185], v[88:91]
	v_mfma_f32_16x16x32_bf16 v[80:83], v[158:161], v[210:213], v[80:83]
	v_mfma_f32_16x16x32_bf16 v[72:75], v[166:169], v[210:213], v[72:75]
	v_mfma_f32_16x16x32_bf16 v[68:71], v[158:161], v[218:221], v[68:71]
	v_mfma_f32_16x16x32_bf16 v[64:67], v[166:169], v[218:221], v[64:67]
	v_mfma_f32_16x16x32_bf16 v[112:115], v[162:165], v[178:181], v[112:115]
	v_mfma_f32_16x16x32_bf16 v[104:107], v[170:173], v[178:181], v[104:107]
	v_mfma_f32_16x16x32_bf16 v[96:99], v[162:165], v[186:189], v[96:99]
	v_mfma_f32_16x16x32_bf16 v[88:91], v[170:173], v[186:189], v[88:91]
	v_mfma_f32_16x16x32_bf16 v[80:83], v[162:165], v[214:217], v[80:83]
	v_mfma_f32_16x16x32_bf16 v[72:75], v[170:173], v[214:217], v[72:75]
	v_mfma_f32_16x16x32_bf16 v[68:71], v[162:165], v[222:225], v[68:71]
	v_mfma_f32_16x16x32_bf16 v[64:67], v[170:173], v[222:225], v[64:67]
	s_barrier
	s_setprio 0
	s_add_i32 s11, s11, s29
	s_mov_b32 m0, s11
	ds_read_b128 v[174:177], v141 offset:16384
	ds_read_b128 v[178:181], v141 offset:17408
	ds_read_b128 v[182:185], v141 offset:18432
	ds_read_b128 v[186:189], v141 offset:19456
	ds_read_b128 v[210:213], v141 offset:20480
	ds_read_b128 v[214:217], v141 offset:21504
	ds_read_b128 v[218:221], v141 offset:22528
	ds_read_b128 v[222:225], v141 offset:23552
	global_load_lds_dwordx4 v132, s[76:77]
	s_add_i32 m0, s11, 0x2000
	s_add_u32 s54, s76, 0x100000
	s_addc_u32 s55, s77, 0
	s_add_i32 s11, s21, s29
	global_load_lds_dwordx4 v128, s[76:77]
	s_mov_b32 m0, s11
	s_nop 0
	global_load_lds_dwordx4 v132, s[54:55]
	s_add_i32 m0, s11, 0x2000
	s_nop 0
	global_load_lds_dwordx4 v128, s[54:55]
	s_mov_b32 m0, s13
	s_nop 0
	global_load_lds_dwordx4 v134, s[40:41]
	s_mov_b32 m0, s69
	s_nop 0
	global_load_lds_dwordx4 v130, s[40:41]
	s_waitcnt vmcnt(8)
	s_waitcnt lgkmcnt(0)
	s_setprio 1
	s_barrier
	v_mfma_f32_16x16x32_bf16 v[60:63], v[142:145], v[174:177], v[60:63]
	v_mfma_f32_16x16x32_bf16 v[56:59], v[150:153], v[174:177], v[56:59]
	v_mfma_f32_16x16x32_bf16 v[52:55], v[142:145], v[182:185], v[52:55]
	v_mfma_f32_16x16x32_bf16 v[44:47], v[150:153], v[182:185], v[44:47]
	v_mfma_f32_16x16x32_bf16 v[36:39], v[142:145], v[210:213], v[36:39]
	v_mfma_f32_16x16x32_bf16 v[28:31], v[150:153], v[210:213], v[28:31]
	v_mfma_f32_16x16x32_bf16 v[20:23], v[142:145], v[218:221], v[20:23]
	v_mfma_f32_16x16x32_bf16 v[12:15], v[150:153], v[218:221], v[12:15]
	v_mfma_f32_16x16x32_bf16 v[60:63], v[146:149], v[178:181], v[60:63]
	v_mfma_f32_16x16x32_bf16 v[56:59], v[154:157], v[178:181], v[56:59]
	v_mfma_f32_16x16x32_bf16 v[52:55], v[146:149], v[186:189], v[52:55]
	v_mfma_f32_16x16x32_bf16 v[44:47], v[154:157], v[186:189], v[44:47]
	v_mfma_f32_16x16x32_bf16 v[36:39], v[146:149], v[214:217], v[36:39]
	v_mfma_f32_16x16x32_bf16 v[28:31], v[154:157], v[214:217], v[28:31]
	v_mfma_f32_16x16x32_bf16 v[20:23], v[146:149], v[222:225], v[20:23]
	v_mfma_f32_16x16x32_bf16 v[12:15], v[154:157], v[222:225], v[12:15]
	s_setprio 0
	s_setprio 1
	v_mfma_f32_16x16x32_bf16 v[48:51], v[158:161], v[174:177], v[48:51]
	v_mfma_f32_16x16x32_bf16 v[40:43], v[166:169], v[174:177], v[40:43]
	v_mfma_f32_16x16x32_bf16 v[32:35], v[158:161], v[182:185], v[32:35]
	v_mfma_f32_16x16x32_bf16 v[24:27], v[166:169], v[182:185], v[24:27]
	v_mfma_f32_16x16x32_bf16 v[16:19], v[158:161], v[210:213], v[16:19]
	v_mfma_f32_16x16x32_bf16 v[8:11], v[166:169], v[210:213], v[8:11]
	v_mfma_f32_16x16x32_bf16 v[4:7], v[158:161], v[218:221], v[4:7]
	v_mfma_f32_16x16x32_bf16 v[0:3], v[166:169], v[218:221], v[0:3]
	v_mfma_f32_16x16x32_bf16 v[48:51], v[162:165], v[178:181], v[48:51]
	v_mfma_f32_16x16x32_bf16 v[40:43], v[170:173], v[178:181], v[40:43]
	v_mfma_f32_16x16x32_bf16 v[32:35], v[162:165], v[186:189], v[32:35]
	v_mfma_f32_16x16x32_bf16 v[24:27], v[170:173], v[186:189], v[24:27]
	v_mfma_f32_16x16x32_bf16 v[16:19], v[162:165], v[214:217], v[16:19]
	v_mfma_f32_16x16x32_bf16 v[8:11], v[170:173], v[214:217], v[8:11]
	v_mfma_f32_16x16x32_bf16 v[4:7], v[162:165], v[222:225], v[4:7]
	v_mfma_f32_16x16x32_bf16 v[0:3], v[170:173], v[222:225], v[0:3]
	s_barrier
; #define PG8_STAGE(bufoff, gbase, voff) do { _Pragma("unroll") for (int _i = 0; _i < 2; ++_i) \
;         __builtin_amdgcn_global_load_lds((const unsigned*)((const char*)(gbase) + (voff)[_i]), (PG8_LAS unsigned*)(lds + (bufoff) + ldsw + _i * 8192), 16, 0, 0); } while (0)
; #define PG8_LDA(dst, b, h) do { _Pragma("unroll") for (int m = 0; m < 4; ++m) _Pragma("unroll") for (int k = 0; k < 2; ++k) dst[m][k] = *(const PG8_LAS bf16x8*)(lds + PG8_SA(b, h) + aoff + m * 2048 + k * 1024); } while (0)
; #define PG8_LDB(dst, b, h) do { _Pragma("unroll") for (int n = 0; n < 2; ++n) _Pragma("unroll") for (int k = 0; k < 2; ++k) dst[n][k] = *(const PG8_LAS bf16x8*)(lds + PG8_SB(b, h) + boff + n * 2048 + k * 1024); } while (0)
; #define PG8_MMA(ai, bj, At, Bt) do { __builtin_amdgcn_s_setprio(1); _Pragma("unroll") for (int m = 0; m < 4; ++m) _Pragma("unroll") for (int n = 0; n < 2; ++n) _Pragma("unroll") for (int k = 0; k < 2; ++k) \
;         acc[ai][bj][m][n] = __builtin_amdgcn_mfma_f32_16x16x32_bf16(Bt[n][k], At[m][k], acc[ai][bj][m][n], 0, 0, 0); __builtin_amdgcn_s_setprio(0); } while (0)
; #define PG8_WAIT_V(n) asm volatile("s_waitcnt vmcnt(" #n ")" ::: "memory")
; #define PG8_WAIT_L(n) asm volatile("s_waitcnt lgkmcnt(" #n ")" ::: "memory")
; #define PG8_BAR __builtin_amdgcn_s_barrier()
; #define PG8_SCHED __builtin_amdgcn_sched_barrier(0)
; template <class Epi>
; __device__ __forceinline__ void gemm_phase(PG8_LAS unsigned char* lds, PG8_LAS unsigned char* xl, const Gemm g, const Sched& S, const Epi& E, const int wid) {
;     ...
;             PG8_LDB(B0, 1, 0); PG8_LDB(B1, 1, 1); PG8_SCHED; PG8_LDA(At, 1, 0); PG8_STAGE(PG8_SA(0, 1), a2 + hstepA, voffA);
;             PG8_WAIT_V(8); PG8_WAIT_L(0); PG8_BAR; if (do0) { PG8_MMA(0, 0, At, B0); PG8_MMA(0, 1, At, B1); } PG8_BAR; PG8_SCHED;
;             PG8_LDA(At, 1, 1); PG8_STAGE(PG8_SB(1, 0), b3, voffB); PG8_STAGE(PG8_SB(1, 1), b3 + hstepB, voffB); PG8_STAGE(PG8_SA(1, 0), a3, voffA);
;             PG8_WAIT_V(8); PG8_WAIT_L(0); PG8_BAR; if (do1) { PG8_MMA(1, 0, At, B0); PG8_MMA(1, 1, At, B1); } PG8_BAR; PG8_SCHED;
;         }
	s_setprio 0
	s_add_i32 s11, 0, 0x18000
	s_add_i32 s21, 0, 0x1c000
	ds_read_b128 v[142:145], v228 offset:32768
	ds_read_b128 v[146:149], v228 offset:33792
	ds_read_b128 v[150:153], v228 offset:34816
	ds_read_b128 v[154:157], v228 offset:35840
	ds_read_b128 v[158:161], v228 offset:49152
	ds_read_b128 v[162:165], v228 offset:50176
	ds_read_b128 v[166:169], v228 offset:51200
	ds_read_b128 v[170:173], v228 offset:52224
	s_add_u32 s100, s40, 0x80000
	s_addc_u32 s101, s41, 0
	s_mov_b32 m0, s70
	ds_read_b128 v[174:177], v141 offset:32768
	ds_read_b128 v[178:181], v141 offset:33792
	ds_read_b128 v[182:185], v141 offset:34816
	ds_read_b128 v[186:189], v141 offset:35840
	ds_read_b128 v[210:213], v141 offset:36864
	ds_read_b128 v[214:217], v141 offset:37888
	ds_read_b128 v[218:221], v141 offset:38912
	ds_read_b128 v[222:225], v141 offset:39936
	global_load_lds_dwordx4 v134, s[100:101]
	s_mov_b32 m0, s71
	s_nop 0
	global_load_lds_dwordx4 v130, s[100:101]
	s_waitcnt vmcnt(8)
	s_waitcnt lgkmcnt(0)
	s_setprio 1
	s_barrier
	v_mfma_f32_16x16x32_bf16 v[124:127], v[142:145], v[174:177], v[124:127]
	v_mfma_f32_16x16x32_bf16 v[120:123], v[150:153], v[174:177], v[120:123]
	v_mfma_f32_16x16x32_bf16 v[116:119], v[142:145], v[182:185], v[116:119]
	v_mfma_f32_16x16x32_bf16 v[108:111], v[150:153], v[182:185], v[108:111]
	v_mfma_f32_16x16x32_bf16 v[100:103], v[142:145], v[210:213], v[100:103]
	v_mfma_f32_16x16x32_bf16 v[92:95], v[150:153], v[210:213], v[92:95]
	v_mfma_f32_16x16x32_bf16 v[84:87], v[142:145], v[218:221], v[84:87]
	v_mfma_f32_16x16x32_bf16 v[76:79], v[150:153], v[218:221], v[76:79]
	v_mfma_f32_16x16x32_bf16 v[124:127], v[146:149], v[178:181], v[124:127]
	v_mfma_f32_16x16x32_bf16 v[120:123], v[154:157], v[178:181], v[120:123]
	v_mfma_f32_16x16x32_bf16 v[116:119], v[146:149], v[186:189], v[116:119]
	v_mfma_f32_16x16x32_bf16 v[108:111], v[154:157], v[186:189], v[108:111]
	v_mfma_f32_16x16x32_bf16 v[100:103], v[146:149], v[214:217], v[100:103]
	v_mfma_f32_16x16x32_bf16 v[92:95], v[154:157], v[214:217], v[92:95]
	v_mfma_f32_16x16x32_bf16 v[84:87], v[146:149], v[222:225], v[84:87]
	v_mfma_f32_16x16x32_bf16 v[76:79], v[154:157], v[222:225], v[76:79]
	s_setprio 0
	s_setprio 1
	v_mfma_f32_16x16x32_bf16 v[112:115], v[158:161], v[174:177], v[112:115]
	v_mfma_f32_16x16x32_bf16 v[104:107], v[166:169], v[174:177], v[104:107]
	v_mfma_f32_16x16x32_bf16 v[96:99], v[158:161], v[182:185], v[96:99]
	v_mfma_f32_16x16x32_bf16 v[88:91], v[166:169], v[182:185], v[88:91]
	v_mfma_f32_16x16x32_bf16 v[80:83], v[158:161], v[210:213], v[80:83]
	v_mfma_f32_16x16x32_bf16 v[72:75], v[166:169], v[210:213], v[72:75]
	v_mfma_f32_16x16x32_bf16 v[68:71], v[158:161], v[218:221], v[68:71]
	v_mfma_f32_16x16x32_bf16 v[64:67], v[166:169], v[218:221], v[64:67]
	v_mfma_f32_16x16x32_bf16 v[112:115], v[162:165], v[178:181], v[112:115]
	v_mfma_f32_16x16x32_bf16 v[104:107], v[170:173], v[178:181], v[104:107]
	v_mfma_f32_16x16x32_bf16 v[96:99], v[162:165], v[186:189], v[96:99]
	v_mfma_f32_16x16x32_bf16 v[88:91], v[170:173], v[186:189], v[88:91]
	v_mfma_f32_16x16x32_bf16 v[80:83], v[162:165], v[214:217], v[80:83]
	v_mfma_f32_16x16x32_bf16 v[72:75], v[170:173], v[214:217], v[72:75]
	v_mfma_f32_16x16x32_bf16 v[68:71], v[162:165], v[222:225], v[68:71]
	v_mfma_f32_16x16x32_bf16 v[64:67], v[170:173], v[222:225], v[64:67]
	s_barrier
	s_setprio 0
	s_add_i32 s11, s11, s29
	s_mov_b32 m0, s11
	ds_read_b128 v[174:177], v141 offset:49152
	ds_read_b128 v[178:181], v141 offset:50176
	ds_read_b128 v[182:185], v141 offset:51200
	ds_read_b128 v[186:189], v141 offset:52224
	ds_read_b128 v[210:213], v141 offset:53248
	ds_read_b128 v[214:217], v141 offset:54272
	ds_read_b128 v[218:221], v141 offset:55296
	ds_read_b128 v[222:225], v141 offset:56320
	global_load_lds_dwordx4 v226, s[76:77]
	s_add_i32 m0, s11, 0x2000
	s_add_u32 s100, s76, 0x100080
	global_load_lds_dwordx4 v190, s[76:77]
	s_addc_u32 s101, s77, 0
	s_add_i32 s11, s21, s29
	s_mov_b32 m0, s11
	s_nop 0
	global_load_lds_dwordx4 v132, s[100:101]
	s_add_i32 m0, s11, 0x2000
	s_nop 0
	global_load_lds_dwordx4 v128, s[100:101]
	s_mov_b32 m0, s90
	s_nop 0
	global_load_lds_dwordx4 v227, s[40:41]
	s_mov_b32 m0, s91
	s_nop 0
	global_load_lds_dwordx4 v191, s[40:41]
	s_waitcnt vmcnt(8)
	s_waitcnt lgkmcnt(0)
	s_setprio 1
	s_barrier
	v_mfma_f32_16x16x32_bf16 v[60:63], v[142:145], v[174:177], v[60:63]
	v_mfma_f32_16x16x32_bf16 v[56:59], v[150:153], v[174:177], v[56:59]
	v_mfma_f32_16x16x32_bf16 v[52:55], v[142:145], v[182:185], v[52:55]
	v_mfma_f32_16x16x32_bf16 v[44:47], v[150:153], v[182:185], v[44:47]
	v_mfma_f32_16x16x32_bf16 v[36:39], v[142:145], v[210:213], v[36:39]
	v_mfma_f32_16x16x32_bf16 v[28:31], v[150:153], v[210:213], v[28:31]
	v_mfma_f32_16x16x32_bf16 v[20:23], v[142:145], v[218:221], v[20:23]
	v_mfma_f32_16x16x32_bf16 v[12:15], v[150:153], v[218:221], v[12:15]
	v_mfma_f32_16x16x32_bf16 v[60:63], v[146:149], v[178:181], v[60:63]
	v_mfma_f32_16x16x32_bf16 v[56:59], v[154:157], v[178:181], v[56:59]
	v_mfma_f32_16x16x32_bf16 v[52:55], v[146:149], v[186:189], v[52:55]
	v_mfma_f32_16x16x32_bf16 v[44:47], v[154:157], v[186:189], v[44:47]
	v_mfma_f32_16x16x32_bf16 v[36:39], v[146:149], v[214:217], v[36:39]
	v_mfma_f32_16x16x32_bf16 v[28:31], v[154:157], v[214:217], v[28:31]
	v_mfma_f32_16x16x32_bf16 v[20:23], v[146:149], v[222:225], v[20:23]
	v_mfma_f32_16x16x32_bf16 v[12:15], v[154:157], v[222:225], v[12:15]
	s_setprio 0
	s_setprio 1
	v_mfma_f32_16x16x32_bf16 v[48:51], v[158:161], v[174:177], v[48:51]
	v_mfma_f32_16x16x32_bf16 v[40:43], v[166:169], v[174:177], v[40:43]
	v_mfma_f32_16x16x32_bf16 v[32:35], v[158:161], v[182:185], v[32:35]
	v_mfma_f32_16x16x32_bf16 v[24:27], v[166:169], v[182:185], v[24:27]
	v_mfma_f32_16x16x32_bf16 v[16:19], v[158:161], v[210:213], v[16:19]
	v_mfma_f32_16x16x32_bf16 v[8:11], v[166:169], v[210:213], v[8:11]
	v_mfma_f32_16x16x32_bf16 v[4:7], v[158:161], v[218:221], v[4:7]
	v_mfma_f32_16x16x32_bf16 v[0:3], v[166:169], v[218:221], v[0:3]
	v_mfma_f32_16x16x32_bf16 v[48:51], v[162:165], v[178:181], v[48:51]
	v_mfma_f32_16x16x32_bf16 v[40:43], v[170:173], v[178:181], v[40:43]
	v_mfma_f32_16x16x32_bf16 v[32:35], v[162:165], v[186:189], v[32:35]
	v_mfma_f32_16x16x32_bf16 v[24:27], v[170:173], v[186:189], v[24:27]
	v_mfma_f32_16x16x32_bf16 v[16:19], v[162:165], v[214:217], v[16:19]
	v_mfma_f32_16x16x32_bf16 v[8:11], v[170:173], v[214:217], v[8:11]
	v_mfma_f32_16x16x32_bf16 v[4:7], v[162:165], v[222:225], v[4:7]
	v_mfma_f32_16x16x32_bf16 v[0:3], v[170:173], v[222:225], v[0:3]
	s_barrier
	s_setprio 0
	s_add_i32 s10, s10, 2
	s_add_u32 s8, s8, 0x100
	s_addc_u32 s9, s9, 0
	s_cmp_gt_u32 s10, 5
	s_mov_b64 s[58:59], s[60:61]
	s_cbranch_scc0 .LBB0_428
	s_mov_b32 s100, 0
	s_and_b64 vcc, exec, s[14:15]
	s_cbranch_vccz .LBB0_431
	s_barrier

; #define PG8_STAGE(bufoff, gbase, voff) do { _Pragma("unroll") for (int _i = 0; _i < 2; ++_i) \
;         __builtin_amdgcn_global_load_lds((const unsigned*)((const char*)(gbase) + (voff)[_i]), (PG8_LAS unsigned*)(lds + (bufoff) + ldsw + _i * 8192), 16, 0, 0); } while (0)
; #define PG8_LDA(dst, b, h) do { _Pragma("unroll") for (int m = 0; m < 4; ++m) _Pragma("unroll") for (int k = 0; k < 2; ++k) dst[m][k] = *(const PG8_LAS bf16x8*)(lds + PG8_SA(b, h) + aoff + m * 2048 + k * 1024); } while (0)
; #define PG8_LDB(dst, b, h) do { _Pragma("unroll") for (int n = 0; n < 2; ++n) _Pragma("unroll") for (int k = 0; k < 2; ++k) dst[n][k] = *(const PG8_LAS bf16x8*)(lds + PG8_SB(b, h) + boff + n * 2048 + k * 1024); } while (0)
; #define PG8_MMA(ai, bj, At, Bt) do { __builtin_amdgcn_s_setprio(1); _Pragma("unroll") for (int m = 0; m < 4; ++m) _Pragma("unroll") for (int n = 0; n < 2; ++n) _Pragma("unroll") for (int k = 0; k < 2; ++k) \
;         acc[ai][bj][m][n] = __builtin_amdgcn_mfma_f32_16x16x32_bf16(Bt[n][k], At[m][k], acc[ai][bj][m][n], 0, 0, 0); __builtin_amdgcn_s_setprio(0); } while (0)
; #define PG8_WAIT_V(n) asm volatile("s_waitcnt vmcnt(" #n ")" ::: "memory")
; #define PG8_WAIT_L(n) asm volatile("s_waitcnt lgkmcnt(" #n ")" ::: "memory")
; #define PG8_BAR __builtin_amdgcn_s_barrier()
; #define PG8_SCHED __builtin_amdgcn_sched_barrier(0)
; template <class Epi>
; __device__ __forceinline__ void gemm_phase(PG8_LAS unsigned char* lds, PG8_LAS unsigned char* xl, const Gemm g, const Sched& S, const Epi& E, const int wid) {
;     ...
;             const char* a1 = cA + (size_t)(t + 1) * kstep + j1;
;             const char* a2 = last ? nA : cA + (size_t)(t + 2) * kstep + ja2; const char* b2 = last ? nB : cB + (size_t)(t + 2) * kstep + jb2;
;             const char* a3 = a2 + kstep; const char* b3 = b2 + kstep;
;             PG8_LDB(B0, 0, 0); PG8_LDB(B1, 0, 1); PG8_SCHED; PG8_LDA(At, 0, 0); PG8_STAGE(PG8_SA(1, 1), a1 + hstepA, voffA);
;             PG8_WAIT_V(8); PG8_WAIT_L(0); PG8_BAR; if (do0) { PG8_MMA(0, 0, At, B0); PG8_MMA(0, 1, At, B1); } PG8_BAR; PG8_SCHED;
;             PG8_LDA(At, 0, 1); PG8_STAGE(PG8_SB(0, 0), b2, voffB); PG8_STAGE(PG8_SB(0, 1), b2 + hstepB, voffB); PG8_STAGE(PG8_SA(0, 0), a2, voffA);
.Ldefbar_skip_4:
	v_add_u32_e32 v157, s22, v140
	v_add_u32_e32 v204, s22, v142
	v_add_u32_e32 v205, s22, v144
	v_add_u32_e32 v234, s22, v146
	v_add_u32_e32 v235, 0x10000, v158
.LBB0_527:
	s_add_u32 s20, s12, 0x100
	s_addc_u32 s21, s13, 0
	s_add_i32 s54, 0, 0x10000
	s_cmp_eq_u32 s66, 28
	s_cselect_b32 s53, s8, s21
	s_cselect_b32 s52, s9, s20
	s_cselect_b32 s51, s10, s62
	s_cselect_b32 s50, s11, s59
	s_add_i32 s55, 0, 0x14000
	ds_read_b128 v[22:25], v235 offset:0
	ds_read_b128 v[26:29], v235 offset:1024
	ds_read_b128 v[160:163], v235 offset:2048
	ds_read_b128 v[164:167], v235 offset:3072
	ds_read_b128 v[168:171], v235 offset:16384
	ds_read_b128 v[172:175], v235 offset:17408
	ds_read_b128 v[176:179], v235 offset:18432
	ds_read_b128 v[180:183], v235 offset:19456
	s_add_i32 m0, s45, 0xc000
	ds_read_b128 v[184:187], v159
	ds_read_b128 v[188:191], v159 offset:1024
	ds_read_b128 v[210:213], v159 offset:2048
	ds_read_b128 v[214:217], v159 offset:3072
	ds_read_b128 v[218:221], v159 offset:4096
	ds_read_b128 v[222:225], v159 offset:5120
	ds_read_b128 v[226:229], v159 offset:6144
	ds_read_b128 v[230:233], v159 offset:7168
	global_load_lds_dwordx4 v148, s[12:13]
	s_add_i32 m0, s45, 0xe000
	s_nop 0
	global_load_lds_dwordx4 v150, s[12:13]
	s_waitcnt vmcnt(8)
	s_waitcnt lgkmcnt(0)
	s_setprio 1
	s_barrier
	v_mfma_f32_16x16x32_bf16 v[136:139], v[22:25], v[184:187], v[136:139]
	v_mfma_f32_16x16x32_bf16 v[132:135], v[160:163], v[184:187], v[132:135]
	v_mfma_f32_16x16x32_bf16 v[120:123], v[22:25], v[210:213], v[120:123]
	v_mfma_f32_16x16x32_bf16 v[116:119], v[160:163], v[210:213], v[116:119]
	v_mfma_f32_16x16x32_bf16 v[104:107], v[22:25], v[218:221], v[104:107]
	v_mfma_f32_16x16x32_bf16 v[100:103], v[160:163], v[218:221], v[100:103]
	v_mfma_f32_16x16x32_bf16 v[86:89], v[22:25], v[226:229], v[86:89]
	v_mfma_f32_16x16x32_bf16 v[82:85], v[160:163], v[226:229], v[82:85]
	v_mfma_f32_16x16x32_bf16 v[136:139], v[26:29], v[188:191], v[136:139]
	v_mfma_f32_16x16x32_bf16 v[132:135], v[164:167], v[188:191], v[132:135]
	v_mfma_f32_16x16x32_bf16 v[120:123], v[26:29], v[214:217], v[120:123]
	v_mfma_f32_16x16x32_bf16 v[116:119], v[164:167], v[214:217], v[116:119]
	v_mfma_f32_16x16x32_bf16 v[104:107], v[26:29], v[222:225], v[104:107]
	v_mfma_f32_16x16x32_bf16 v[100:103], v[164:167], v[222:225], v[100:103]
	v_mfma_f32_16x16x32_bf16 v[86:89], v[26:29], v[230:233], v[86:89]
	v_mfma_f32_16x16x32_bf16 v[82:85], v[164:167], v[230:233], v[82:85]
	s_setprio 0
	s_setprio 1
	v_mfma_f32_16x16x32_bf16 v[128:131], v[168:171], v[184:187], v[128:131]
	v_mfma_f32_16x16x32_bf16 v[124:127], v[176:179], v[184:187], v[124:127]
	v_mfma_f32_16x16x32_bf16 v[112:115], v[168:171], v[210:213], v[112:115]
	v_mfma_f32_16x16x32_bf16 v[108:111], v[176:179], v[210:213], v[108:111]
	v_mfma_f32_16x16x32_bf16 v[96:99], v[168:171], v[218:221], v[96:99]
	v_mfma_f32_16x16x32_bf16 v[92:95], v[176:179], v[218:221], v[92:95]
	v_mfma_f32_16x16x32_bf16 v[78:81], v[168:171], v[226:229], v[78:81]
	v_mfma_f32_16x16x32_bf16 v[74:77], v[176:179], v[226:229], v[74:77]
	v_mfma_f32_16x16x32_bf16 v[128:131], v[172:175], v[188:191], v[128:131]
	v_mfma_f32_16x16x32_bf16 v[124:127], v[180:183], v[188:191], v[124:127]
	v_mfma_f32_16x16x32_bf16 v[112:115], v[172:175], v[214:217], v[112:115]
	v_mfma_f32_16x16x32_bf16 v[108:111], v[180:183], v[214:217], v[108:111]
	v_mfma_f32_16x16x32_bf16 v[96:99], v[172:175], v[222:225], v[96:99]
	v_mfma_f32_16x16x32_bf16 v[92:95], v[180:183], v[222:225], v[92:95]
	v_mfma_f32_16x16x32_bf16 v[78:81], v[172:175], v[230:233], v[78:81]
	v_mfma_f32_16x16x32_bf16 v[74:77], v[180:183], v[230:233], v[74:77]
	s_barrier
	s_setprio 0
	s_add_i32 s12, s54, s29
	s_mov_b32 m0, s12
	ds_read_b128 v[184:187], v159 offset:16384
	ds_read_b128 v[188:191], v159 offset:17408
	ds_read_b128 v[210:213], v159 offset:18432
	ds_read_b128 v[214:217], v159 offset:19456
	ds_read_b128 v[218:221], v159 offset:20480
	ds_read_b128 v[222:225], v159 offset:21504
	ds_read_b128 v[226:229], v159 offset:22528
	ds_read_b128 v[230:233], v159 offset:23552
	global_load_lds_dwordx4 v142, s[50:51]
	s_add_i32 m0, s12, 0x2000
	s_add_u32 s12, s50, 0x80000
	s_addc_u32 s13, s51, 0
	s_add_i32 s54, s55, s29
	global_load_lds_dwordx4 v146, s[50:51]
	s_mov_b32 m0, s54
	s_nop 0
	global_load_lds_dwordx4 v142, s[12:13]
	s_add_i32 m0, s54, 0x2000
	s_nop 0
	global_load_lds_dwordx4 v146, s[12:13]
	s_mov_b32 m0, s45
	s_nop 0
	global_load_lds_dwordx4 v140, s[52:53]
	s_mov_b32 m0, s41
	s_nop 0
	global_load_lds_dwordx4 v144, s[52:53]
	s_waitcnt vmcnt(8)
	s_waitcnt lgkmcnt(0)
	s_setprio 1
	s_barrier
; #define PG8_STAGE(bufoff, gbase, voff) do { _Pragma("unroll") for (int _i = 0; _i < 2; ++_i) \
;         __builtin_amdgcn_global_load_lds((const unsigned*)((const char*)(gbase) + (voff)[_i]), (PG8_LAS unsigned*)(lds + (bufoff) + ldsw + _i * 8192), 16, 0, 0); } while (0)
; #define PG8_LDA(dst, b, h) do { _Pragma("unroll") for (int m = 0; m < 4; ++m) _Pragma("unroll") for (int k = 0; k < 2; ++k) dst[m][k] = *(const PG8_LAS bf16x8*)(lds + PG8_SA(b, h) + aoff + m * 2048 + k * 1024); } while (0)
; #define PG8_LDB(dst, b, h) do { _Pragma("unroll") for (int n = 0; n < 2; ++n) _Pragma("unroll") for (int k = 0; k < 2; ++k) dst[n][k] = *(const PG8_LAS bf16x8*)(lds + PG8_SB(b, h) + boff + n * 2048 + k * 1024); } while (0)
; #define PG8_MMA(ai, bj, At, Bt) do { __builtin_amdgcn_s_setprio(1); _Pragma("unroll") for (int m = 0; m < 4; ++m) _Pragma("unroll") for (int n = 0; n < 2; ++n) _Pragma("unroll") for (int k = 0; k < 2; ++k) \
;         acc[ai][bj][m][n] = __builtin_amdgcn_mfma_f32_16x16x32_bf16(Bt[n][k], At[m][k], acc[ai][bj][m][n], 0, 0, 0); __builtin_amdgcn_s_setprio(0); } while (0)
; #define PG8_WAIT_V(n) asm volatile("s_waitcnt vmcnt(" #n ")" ::: "memory")
; #define PG8_WAIT_L(n) asm volatile("s_waitcnt lgkmcnt(" #n ")" ::: "memory")
; #define PG8_BAR __builtin_amdgcn_s_barrier()
; #define PG8_SCHED __builtin_amdgcn_sched_barrier(0)
; template <class Epi>
; __device__ __forceinline__ void gemm_phase(PG8_LAS unsigned char* lds, PG8_LAS unsigned char* xl, const Gemm g, const Sched& S, const Epi& E, const int wid) {
;     ...
;             PG8_WAIT_V(8); PG8_WAIT_L(0); PG8_BAR; if (do1) { PG8_MMA(1, 0, At, B0); PG8_MMA(1, 1, At, B1); } PG8_BAR; PG8_SCHED;
;             PG8_LDB(B0, 1, 0); PG8_LDB(B1, 1, 1); PG8_SCHED; PG8_LDA(At, 1, 0); PG8_STAGE(PG8_SA(0, 1), a2 + hstepA, voffA);
;             PG8_WAIT_V(8); PG8_WAIT_L(0); PG8_BAR; if (do0) { PG8_MMA(0, 0, At, B0); PG8_MMA(0, 1, At, B1); } PG8_BAR; PG8_SCHED;
	v_mfma_f32_16x16x32_bf16 v[70:73], v[22:25], v[184:187], v[70:73]
	v_mfma_f32_16x16x32_bf16 v[66:69], v[160:163], v[184:187], v[66:69]
	v_mfma_f32_16x16x32_bf16 v[54:57], v[22:25], v[210:213], v[54:57]
	v_mfma_f32_16x16x32_bf16 v[50:53], v[160:163], v[210:213], v[50:53]
	v_mfma_f32_16x16x32_bf16 v[38:41], v[22:25], v[218:221], v[38:41]
	v_mfma_f32_16x16x32_bf16 v[34:37], v[160:163], v[218:221], v[34:37]
	v_mfma_f32_16x16x32_bf16 v[12:15], v[22:25], v[226:229], v[12:15]
	v_mfma_f32_16x16x32_bf16 v[8:11], v[160:163], v[226:229], v[8:11]
	v_mfma_f32_16x16x32_bf16 v[70:73], v[26:29], v[188:191], v[70:73]
	v_mfma_f32_16x16x32_bf16 v[66:69], v[164:167], v[188:191], v[66:69]
	v_mfma_f32_16x16x32_bf16 v[54:57], v[26:29], v[214:217], v[54:57]
	v_mfma_f32_16x16x32_bf16 v[50:53], v[164:167], v[214:217], v[50:53]
	v_mfma_f32_16x16x32_bf16 v[38:41], v[26:29], v[222:225], v[38:41]
	v_mfma_f32_16x16x32_bf16 v[34:37], v[164:167], v[222:225], v[34:37]
	v_mfma_f32_16x16x32_bf16 v[12:15], v[26:29], v[230:233], v[12:15]
	v_mfma_f32_16x16x32_bf16 v[8:11], v[164:167], v[230:233], v[8:11]
	s_setprio 0
	s_setprio 1
	v_mfma_f32_16x16x32_bf16 v[46:49], v[168:171], v[210:213], v[46:49]
	v_mfma_f32_16x16x32_bf16 v[42:45], v[176:179], v[210:213], v[42:45]
	v_mfma_f32_16x16x32_bf16 v[30:33], v[168:171], v[218:221], v[30:33]
	v_mfma_f32_16x16x32_bf16 v[18:21], v[176:179], v[218:221], v[18:21]
	v_mfma_f32_16x16x32_bf16 v[4:7], v[168:171], v[226:229], v[4:7]
	v_mfma_f32_16x16x32_bf16 v[0:3], v[176:179], v[226:229], v[0:3]
	v_mfma_f32_16x16x32_bf16 v[22:25], v[168:171], v[184:187], v[62:65]
	v_mfma_f32_16x16x32_bf16 v[26:29], v[176:179], v[184:187], v[58:61]
	v_mfma_f32_16x16x32_bf16 v[46:49], v[172:175], v[214:217], v[46:49]
	v_mfma_f32_16x16x32_bf16 v[42:45], v[180:183], v[214:217], v[42:45]
	v_mfma_f32_16x16x32_bf16 v[30:33], v[172:175], v[222:225], v[30:33]
	v_mfma_f32_16x16x32_bf16 v[18:21], v[180:183], v[222:225], v[18:21]
	v_mfma_f32_16x16x32_bf16 v[4:7], v[172:175], v[230:233], v[4:7]
	v_mfma_f32_16x16x32_bf16 v[0:3], v[180:183], v[230:233], v[0:3]
	v_mfma_f32_16x16x32_bf16 v[22:25], v[172:175], v[188:191], v[22:25]
	v_mfma_f32_16x16x32_bf16 v[26:29], v[180:183], v[188:191], v[26:29]
	s_barrier
	s_setprio 0
	s_add_i32 s54, 0, 0x18000
	s_add_i32 s55, 0, 0x1c000
	ds_read_b128 v[58:61], v235 offset:32768
	ds_read_b128 v[62:65], v235 offset:33792
	ds_read_b128 v[160:163], v235 offset:34816
	ds_read_b128 v[164:167], v235 offset:35840
	ds_read_b128 v[168:171], v235 offset:49152
	ds_read_b128 v[172:175], v235 offset:50176
	ds_read_b128 v[176:179], v235 offset:51200
	ds_read_b128 v[180:183], v235 offset:52224
	s_add_u32 s12, s52, 0x80000
	s_addc_u32 s13, s53, 0
	s_mov_b32 m0, s88
	ds_read_b128 v[184:187], v159 offset:32768
	ds_read_b128 v[188:191], v159 offset:33792
	ds_read_b128 v[210:213], v159 offset:34816
	ds_read_b128 v[214:217], v159 offset:35840
	ds_read_b128 v[218:221], v159 offset:36864
	ds_read_b128 v[222:225], v159 offset:37888
	ds_read_b128 v[226:229], v159 offset:38912
	ds_read_b128 v[230:233], v159 offset:39936
	global_load_lds_dwordx4 v140, s[12:13]
	s_mov_b32 m0, s89
	s_nop 0
	global_load_lds_dwordx4 v144, s[12:13]
	s_waitcnt vmcnt(8)
	s_waitcnt lgkmcnt(0)
	s_setprio 1
	s_barrier
	v_mfma_f32_16x16x32_bf16 v[136:139], v[58:61], v[184:187], v[136:139]
	v_mfma_f32_16x16x32_bf16 v[132:135], v[160:163], v[184:187], v[132:135]
	v_mfma_f32_16x16x32_bf16 v[120:123], v[58:61], v[210:213], v[120:123]
	v_mfma_f32_16x16x32_bf16 v[116:119], v[160:163], v[210:213], v[116:119]
	v_mfma_f32_16x16x32_bf16 v[104:107], v[58:61], v[218:221], v[104:107]
	v_mfma_f32_16x16x32_bf16 v[100:103], v[160:163], v[218:221], v[100:103]
	v_mfma_f32_16x16x32_bf16 v[86:89], v[58:61], v[226:229], v[86:89]
	v_mfma_f32_16x16x32_bf16 v[82:85], v[160:163], v[226:229], v[82:85]
	v_mfma_f32_16x16x32_bf16 v[136:139], v[62:65], v[188:191], v[136:139]
	v_mfma_f32_16x16x32_bf16 v[132:135], v[164:167], v[188:191], v[132:135]
	v_mfma_f32_16x16x32_bf16 v[120:123], v[62:65], v[214:217], v[120:123]
	v_mfma_f32_16x16x32_bf16 v[116:119], v[164:167], v[214:217], v[116:119]
	v_mfma_f32_16x16x32_bf16 v[104:107], v[62:65], v[222:225], v[104:107]
	v_mfma_f32_16x16x32_bf16 v[100:103], v[164:167], v[222:225], v[100:103]
	v_mfma_f32_16x16x32_bf16 v[86:89], v[62:65], v[230:233], v[86:89]
	v_mfma_f32_16x16x32_bf16 v[82:85], v[164:167], v[230:233], v[82:85]
	s_setprio 0
	s_setprio 1
	v_mfma_f32_16x16x32_bf16 v[128:131], v[168:171], v[184:187], v[128:131]
	v_mfma_f32_16x16x32_bf16 v[124:127], v[176:179], v[184:187], v[124:127]
	v_mfma_f32_16x16x32_bf16 v[112:115], v[168:171], v[210:213], v[112:115]
	v_mfma_f32_16x16x32_bf16 v[108:111], v[176:179], v[210:213], v[108:111]
	v_mfma_f32_16x16x32_bf16 v[96:99], v[168:171], v[218:221], v[96:99]
	v_mfma_f32_16x16x32_bf16 v[92:95], v[176:179], v[218:221], v[92:95]
	v_mfma_f32_16x16x32_bf16 v[78:81], v[168:171], v[226:229], v[78:81]
	v_mfma_f32_16x16x32_bf16 v[74:77], v[176:179], v[226:229], v[74:77]
	v_mfma_f32_16x16x32_bf16 v[128:131], v[172:175], v[188:191], v[128:131]
	v_mfma_f32_16x16x32_bf16 v[124:127], v[180:183], v[188:191], v[124:127]
	v_mfma_f32_16x16x32_bf16 v[112:115], v[172:175], v[214:217], v[112:115]
	v_mfma_f32_16x16x32_bf16 v[108:111], v[180:183], v[214:217], v[108:111]
	v_mfma_f32_16x16x32_bf16 v[96:99], v[172:175], v[222:225], v[96:99]
	v_mfma_f32_16x16x32_bf16 v[92:95], v[180:183], v[222:225], v[92:95]
	v_mfma_f32_16x16x32_bf16 v[78:81], v[172:175], v[230:233], v[78:81]
	v_mfma_f32_16x16x32_bf16 v[74:77], v[180:183], v[230:233], v[74:77]
	s_barrier
; #define PG8_STAGE(bufoff, gbase, voff) do { _Pragma("unroll") for (int _i = 0; _i < 2; ++_i) \
;         __builtin_amdgcn_global_load_lds((const unsigned*)((const char*)(gbase) + (voff)[_i]), (PG8_LAS unsigned*)(lds + (bufoff) + ldsw + _i * 8192), 16, 0, 0); } while (0)
; #define PG8_LDA(dst, b, h) do { _Pragma("unroll") for (int m = 0; m < 4; ++m) _Pragma("unroll") for (int k = 0; k < 2; ++k) dst[m][k] = *(const PG8_LAS bf16x8*)(lds + PG8_SA(b, h) + aoff + m * 2048 + k * 1024); } while (0)
; #define PG8_MMA(ai, bj, At, Bt) do { __builtin_amdgcn_s_setprio(1); _Pragma("unroll") for (int m = 0; m < 4; ++m) _Pragma("unroll") for (int n = 0; n < 2; ++n) _Pragma("unroll") for (int k = 0; k < 2; ++k) \
;         acc[ai][bj][m][n] = __builtin_amdgcn_mfma_f32_16x16x32_bf16(Bt[n][k], At[m][k], acc[ai][bj][m][n], 0, 0, 0); __builtin_amdgcn_s_setprio(0); } while (0)
; #define PG8_WAIT_V(n) asm volatile("s_waitcnt vmcnt(" #n ")" ::: "memory")
; #define PG8_WAIT_L(n) asm volatile("s_waitcnt lgkmcnt(" #n ")" ::: "memory")
; #define PG8_BAR __builtin_amdgcn_s_barrier()
; #define PG8_SCHED __builtin_amdgcn_sched_barrier(0)
; template <class Epi>
; __device__ __forceinline__ void gemm_phase(PG8_LAS unsigned char* lds, PG8_LAS unsigned char* xl, const Gemm g, const Sched& S, const Epi& E, const int wid) {
;     ...
;             PG8_LDA(At, 1, 1); PG8_STAGE(PG8_SB(1, 0), b3, voffB); PG8_STAGE(PG8_SB(1, 1), b3 + hstepB, voffB); PG8_STAGE(PG8_SA(1, 0), a3, voffA);
;             PG8_WAIT_V(8); PG8_WAIT_L(0); PG8_BAR; if (do1) { PG8_MMA(1, 0, At, B0); PG8_MMA(1, 1, At, B1); } PG8_BAR; PG8_SCHED;
;         }
	s_setprio 0
	s_add_i32 s12, s54, s29
	s_mov_b32 m0, s12
	ds_read_b128 v[184:187], v159 offset:49152
	ds_read_b128 v[188:191], v159 offset:50176
	ds_read_b128 v[210:213], v159 offset:51200
	ds_read_b128 v[214:217], v159 offset:52224
	ds_read_b128 v[218:221], v159 offset:53248
	ds_read_b128 v[222:225], v159 offset:54272
	ds_read_b128 v[226:229], v159 offset:55296
	ds_read_b128 v[230:233], v159 offset:56320
	global_load_lds_dwordx4 v204, s[50:51]
	s_add_i32 m0, s12, 0x2000
	s_add_u32 s12, s50, 0x80080
	global_load_lds_dwordx4 v234, s[50:51]
	s_addc_u32 s13, s51, 0
	s_add_i32 s50, s55, s29
	s_mov_b32 m0, s50
	s_nop 0
	global_load_lds_dwordx4 v142, s[12:13]
	s_add_i32 m0, s50, 0x2000
	s_nop 0
	global_load_lds_dwordx4 v146, s[12:13]
	s_mov_b32 m0, s90
	s_nop 0
	global_load_lds_dwordx4 v157, s[52:53]
	s_mov_b32 m0, s91
	s_nop 0
	global_load_lds_dwordx4 v205, s[52:53]
	s_waitcnt vmcnt(8)
	s_waitcnt lgkmcnt(0)
	s_setprio 1
	s_barrier
	v_mfma_f32_16x16x32_bf16 v[70:73], v[58:61], v[184:187], v[70:73]
	v_mfma_f32_16x16x32_bf16 v[66:69], v[160:163], v[184:187], v[66:69]
	v_mfma_f32_16x16x32_bf16 v[54:57], v[58:61], v[210:213], v[54:57]
	v_mfma_f32_16x16x32_bf16 v[50:53], v[160:163], v[210:213], v[50:53]
	v_mfma_f32_16x16x32_bf16 v[38:41], v[58:61], v[218:221], v[38:41]
	v_mfma_f32_16x16x32_bf16 v[34:37], v[160:163], v[218:221], v[34:37]
	v_mfma_f32_16x16x32_bf16 v[12:15], v[58:61], v[226:229], v[12:15]
	v_mfma_f32_16x16x32_bf16 v[8:11], v[160:163], v[226:229], v[8:11]
	v_mfma_f32_16x16x32_bf16 v[70:73], v[62:65], v[188:191], v[70:73]
	v_mfma_f32_16x16x32_bf16 v[66:69], v[164:167], v[188:191], v[66:69]
	v_mfma_f32_16x16x32_bf16 v[54:57], v[62:65], v[214:217], v[54:57]
	v_mfma_f32_16x16x32_bf16 v[50:53], v[164:167], v[214:217], v[50:53]
	v_mfma_f32_16x16x32_bf16 v[38:41], v[62:65], v[222:225], v[38:41]
	v_mfma_f32_16x16x32_bf16 v[34:37], v[164:167], v[222:225], v[34:37]
	v_mfma_f32_16x16x32_bf16 v[12:15], v[62:65], v[230:233], v[12:15]
	v_mfma_f32_16x16x32_bf16 v[8:11], v[164:167], v[230:233], v[8:11]
	s_setprio 0
	s_setprio 1
	v_mfma_f32_16x16x32_bf16 v[22:25], v[168:171], v[184:187], v[22:25]
	v_mfma_f32_16x16x32_bf16 v[62:65], v[172:175], v[188:191], v[22:25]
	v_mfma_f32_16x16x32_bf16 v[22:25], v[176:179], v[184:187], v[26:29]
	v_mfma_f32_16x16x32_bf16 v[58:61], v[180:183], v[188:191], v[22:25]
	v_mfma_f32_16x16x32_bf16 v[22:25], v[168:171], v[210:213], v[46:49]
	v_mfma_f32_16x16x32_bf16 v[46:49], v[172:175], v[214:217], v[22:25]
	v_mfma_f32_16x16x32_bf16 v[22:25], v[176:179], v[210:213], v[42:45]
	v_mfma_f32_16x16x32_bf16 v[42:45], v[180:183], v[214:217], v[22:25]
	v_mfma_f32_16x16x32_bf16 v[22:25], v[168:171], v[218:221], v[30:33]
	v_mfma_f32_16x16x32_bf16 v[18:21], v[176:179], v[218:221], v[18:21]
	v_mfma_f32_16x16x32_bf16 v[4:7], v[168:171], v[226:229], v[4:7]
	v_mfma_f32_16x16x32_bf16 v[0:3], v[176:179], v[226:229], v[0:3]
	v_mfma_f32_16x16x32_bf16 v[30:33], v[172:175], v[222:225], v[22:25]
	v_mfma_f32_16x16x32_bf16 v[18:21], v[180:183], v[222:225], v[18:21]
	v_mfma_f32_16x16x32_bf16 v[4:7], v[172:175], v[230:233], v[4:7]
	v_mfma_f32_16x16x32_bf16 v[0:3], v[180:183], v[230:233], v[0:3]
	s_barrier
	s_setprio 0
	s_add_i32 s66, s66, 2
	s_add_u32 s59, s59, 0x100
	s_addc_u32 s62, s62, 0
	s_cmp_gt_u32 s66, 29
	s_mov_b64 s[12:13], s[20:21]
	s_cbranch_scc0 .LBB0_527
	s_and_b64 vcc, exec, s[14:15]
	s_cbranch_vccz .LBB0_530
	s_barrier

; #define PG8_STAGE(bufoff, gbase, voff) do { _Pragma("unroll") for (int _i = 0; _i < 2; ++_i) \
;         __builtin_amdgcn_global_load_lds((const unsigned*)((const char*)(gbase) + (voff)[_i]), (PG8_LAS unsigned*)(lds + (bufoff) + ldsw + _i * 8192), 16, 0, 0); } while (0)
; #define PG8_LDA(dst, b, h) do { _Pragma("unroll") for (int m = 0; m < 4; ++m) _Pragma("unroll") for (int k = 0; k < 2; ++k) dst[m][k] = *(const PG8_LAS bf16x8*)(lds + PG8_SA(b, h) + aoff + m * 2048 + k * 1024); } while (0)
; #define PG8_LDB(dst, b, h) do { _Pragma("unroll") for (int n = 0; n < 2; ++n) _Pragma("unroll") for (int k = 0; k < 2; ++k) dst[n][k] = *(const PG8_LAS bf16x8*)(lds + PG8_SB(b, h) + boff + n * 2048 + k * 1024); } while (0)
; #define PG8_MMA(ai, bj, At, Bt) do { __builtin_amdgcn_s_setprio(1); _Pragma("unroll") for (int m = 0; m < 4; ++m) _Pragma("unroll") for (int n = 0; n < 2; ++n) _Pragma("unroll") for (int k = 0; k < 2; ++k) \
;         acc[ai][bj][m][n] = __builtin_amdgcn_mfma_f32_16x16x32_bf16(Bt[n][k], At[m][k], acc[ai][bj][m][n], 0, 0, 0); __builtin_amdgcn_s_setprio(0); } while (0)
; #define PG8_WAIT_V(n) asm volatile("s_waitcnt vmcnt(" #n ")" ::: "memory")
; #define PG8_WAIT_L(n) asm volatile("s_waitcnt lgkmcnt(" #n ")" ::: "memory")
; #define PG8_BAR __builtin_amdgcn_s_barrier()
; #define PG8_SCHED __builtin_amdgcn_sched_barrier(0)
; template <class Epi>
; __device__ __forceinline__ void gemm_phase(PG8_LAS unsigned char* lds, PG8_LAS unsigned char* xl, const Gemm g, const Sched& S, const Epi& E, const int wid) {
;     ...
;             const char* a1 = cA + (size_t)(t + 1) * kstep + j1;
;             const char* a2 = last ? nA : cA + (size_t)(t + 2) * kstep + ja2; const char* b2 = last ? nB : cB + (size_t)(t + 2) * kstep + jb2;
;             const char* a3 = a2 + kstep; const char* b3 = b2 + kstep;
;             PG8_LDB(B0, 0, 0); PG8_LDB(B1, 0, 1); PG8_SCHED; PG8_LDA(At, 0, 0); PG8_STAGE(PG8_SA(1, 1), a1 + hstepA, voffA);
;             PG8_WAIT_V(8); PG8_WAIT_L(0); PG8_BAR; if (do0) { PG8_MMA(0, 0, At, B0); PG8_MMA(0, 1, At, B1); } PG8_BAR; PG8_SCHED;
;             PG8_LDA(At, 0, 1); PG8_STAGE(PG8_SB(0, 0), b2, voffB); PG8_STAGE(PG8_SB(0, 1), b2 + hstepB, voffB); PG8_STAGE(PG8_SA(0, 0), a2, voffA);
.Ldefbar_skip_6:
	v_add_u32_e32 v204, s22, v188
	v_add_u32_e32 v205, s22, v190
	v_add_u32_e32 v218, s22, v210
	v_add_u32_e32 v219, s22, v212
	v_add_u32_e32 v226, 0x10000, v195
.LBB0_765:
	s_add_u32 s21, s42, 0xffd40080
	s_addc_u32 s31, s43, -1
	s_add_i32 s54, 0, 0x10000
	s_cmp_eq_u32 s13, 28
	s_cselect_b32 s49, s37, s31
	s_cselect_b32 s48, s36, s21
	s_cselect_b32 s45, s8, s11
	s_cselect_b32 s44, s9, s10
	s_add_i32 s21, 0, 0x14000
	ds_read_b128 v[120:123], v226 offset:0
	ds_read_b128 v[124:127], v226 offset:1024
	ds_read_b128 v[128:131], v226 offset:2048
	ds_read_b128 v[136:139], v226 offset:3072
	ds_read_b128 v[144:147], v226 offset:16384
	ds_read_b128 v[148:151], v226 offset:17408
	ds_read_b128 v[152:155], v226 offset:18432
	ds_read_b128 v[156:159], v226 offset:19456
	s_add_i32 m0, s53, 0xc000
	ds_read_b128 v[160:163], v220
	ds_read_b128 v[164:167], v220 offset:1024
	ds_read_b128 v[168:171], v220 offset:2048
	ds_read_b128 v[172:175], v220 offset:3072
	ds_read_b128 v[176:179], v220 offset:4096
	ds_read_b128 v[180:183], v220 offset:5120
	ds_read_b128 v[184:187], v220 offset:6144
	ds_read_b128 v[222:225], v220 offset:7168
	global_load_lds_dwordx4 v214, s[42:43]
	s_add_i32 m0, s53, 0xe000
	s_nop 0
	global_load_lds_dwordx4 v216, s[42:43]
	s_waitcnt vmcnt(8)
	s_waitcnt lgkmcnt(0)
	s_setprio 1
	s_barrier
	v_mfma_f32_16x16x32_bf16 v[140:143], v[120:123], v[160:163], v[140:143]
	v_mfma_f32_16x16x32_bf16 v[132:135], v[128:131], v[160:163], v[132:135]
	v_mfma_f32_16x16x32_bf16 v[108:111], v[120:123], v[168:171], v[108:111]
	v_mfma_f32_16x16x32_bf16 v[104:107], v[128:131], v[168:171], v[104:107]
	v_mfma_f32_16x16x32_bf16 v[92:95], v[120:123], v[176:179], v[92:95]
	v_mfma_f32_16x16x32_bf16 v[88:91], v[128:131], v[176:179], v[88:91]
	v_mfma_f32_16x16x32_bf16 v[76:79], v[120:123], v[184:187], v[76:79]
	v_mfma_f32_16x16x32_bf16 v[72:75], v[128:131], v[184:187], v[72:75]
	v_mfma_f32_16x16x32_bf16 v[140:143], v[124:127], v[164:167], v[140:143]
	v_mfma_f32_16x16x32_bf16 v[132:135], v[136:139], v[164:167], v[132:135]
	v_mfma_f32_16x16x32_bf16 v[108:111], v[124:127], v[172:175], v[108:111]
	v_mfma_f32_16x16x32_bf16 v[104:107], v[136:139], v[172:175], v[104:107]
	v_mfma_f32_16x16x32_bf16 v[92:95], v[124:127], v[180:183], v[92:95]
	v_mfma_f32_16x16x32_bf16 v[88:91], v[136:139], v[180:183], v[88:91]
	v_mfma_f32_16x16x32_bf16 v[76:79], v[124:127], v[222:225], v[76:79]
	v_mfma_f32_16x16x32_bf16 v[72:75], v[136:139], v[222:225], v[72:75]
	s_setprio 0
	s_setprio 1
	v_mfma_f32_16x16x32_bf16 v[116:119], v[144:147], v[160:163], v[116:119]
	v_mfma_f32_16x16x32_bf16 v[112:115], v[152:155], v[160:163], v[112:115]
	v_mfma_f32_16x16x32_bf16 v[100:103], v[144:147], v[168:171], v[100:103]
	v_mfma_f32_16x16x32_bf16 v[96:99], v[152:155], v[168:171], v[96:99]
	v_mfma_f32_16x16x32_bf16 v[84:87], v[144:147], v[176:179], v[84:87]
	v_mfma_f32_16x16x32_bf16 v[80:83], v[152:155], v[176:179], v[80:83]
	v_mfma_f32_16x16x32_bf16 v[68:71], v[144:147], v[184:187], v[68:71]
	v_mfma_f32_16x16x32_bf16 v[64:67], v[152:155], v[184:187], v[64:67]
	v_mfma_f32_16x16x32_bf16 v[116:119], v[148:151], v[164:167], v[116:119]
	v_mfma_f32_16x16x32_bf16 v[112:115], v[156:159], v[164:167], v[112:115]
	v_mfma_f32_16x16x32_bf16 v[100:103], v[148:151], v[172:175], v[100:103]
	v_mfma_f32_16x16x32_bf16 v[96:99], v[156:159], v[172:175], v[96:99]
	v_mfma_f32_16x16x32_bf16 v[84:87], v[148:151], v[180:183], v[84:87]
	v_mfma_f32_16x16x32_bf16 v[80:83], v[156:159], v[180:183], v[80:83]
	v_mfma_f32_16x16x32_bf16 v[68:71], v[148:151], v[222:225], v[68:71]
	v_mfma_f32_16x16x32_bf16 v[64:67], v[156:159], v[222:225], v[64:67]
	s_barrier
	s_setprio 0
	s_add_i32 s31, s54, s29
	s_mov_b32 m0, s31
	ds_read_b128 v[160:163], v220 offset:16384
	ds_read_b128 v[164:167], v220 offset:17408
	ds_read_b128 v[168:171], v220 offset:18432
	ds_read_b128 v[172:175], v220 offset:19456
	ds_read_b128 v[176:179], v220 offset:20480
	ds_read_b128 v[180:183], v220 offset:21504
	ds_read_b128 v[184:187], v220 offset:22528
	ds_read_b128 v[222:225], v220 offset:23552
	global_load_lds_dwordx4 v190, s[44:45]
	s_add_i32 m0, s31, 0x2000
	s_add_u32 s54, s44, 0x80000
	s_addc_u32 s55, s45, 0
	s_add_i32 s21, s21, s29
	global_load_lds_dwordx4 v212, s[44:45]
	s_mov_b32 m0, s21
	s_nop 0
	global_load_lds_dwordx4 v190, s[54:55]
	s_add_i32 m0, s21, 0x2000
	s_nop 0
	global_load_lds_dwordx4 v212, s[54:55]
	s_mov_b32 m0, s53
	s_nop 0
	global_load_lds_dwordx4 v188, s[48:49]
	s_mov_b32 m0, s56
	s_nop 0
	global_load_lds_dwordx4 v210, s[48:49]
	s_waitcnt vmcnt(8)
	s_waitcnt lgkmcnt(0)
	s_setprio 1
	s_barrier
; #define PG8_STAGE(bufoff, gbase, voff) do { _Pragma("unroll") for (int _i = 0; _i < 2; ++_i) \
;         __builtin_amdgcn_global_load_lds((const unsigned*)((const char*)(gbase) + (voff)[_i]), (PG8_LAS unsigned*)(lds + (bufoff) + ldsw + _i * 8192), 16, 0, 0); } while (0)
; #define PG8_LDA(dst, b, h) do { _Pragma("unroll") for (int m = 0; m < 4; ++m) _Pragma("unroll") for (int k = 0; k < 2; ++k) dst[m][k] = *(const PG8_LAS bf16x8*)(lds + PG8_SA(b, h) + aoff + m * 2048 + k * 1024); } while (0)
; #define PG8_LDB(dst, b, h) do { _Pragma("unroll") for (int n = 0; n < 2; ++n) _Pragma("unroll") for (int k = 0; k < 2; ++k) dst[n][k] = *(const PG8_LAS bf16x8*)(lds + PG8_SB(b, h) + boff + n * 2048 + k * 1024); } while (0)
; #define PG8_MMA(ai, bj, At, Bt) do { __builtin_amdgcn_s_setprio(1); _Pragma("unroll") for (int m = 0; m < 4; ++m) _Pragma("unroll") for (int n = 0; n < 2; ++n) _Pragma("unroll") for (int k = 0; k < 2; ++k) \
;         acc[ai][bj][m][n] = __builtin_amdgcn_mfma_f32_16x16x32_bf16(Bt[n][k], At[m][k], acc[ai][bj][m][n], 0, 0, 0); __builtin_amdgcn_s_setprio(0); } while (0)
; #define PG8_WAIT_V(n) asm volatile("s_waitcnt vmcnt(" #n ")" ::: "memory")
; #define PG8_WAIT_L(n) asm volatile("s_waitcnt lgkmcnt(" #n ")" ::: "memory")
; #define PG8_BAR __builtin_amdgcn_s_barrier()
; #define PG8_SCHED __builtin_amdgcn_sched_barrier(0)
; template <class Epi>
; __device__ __forceinline__ void gemm_phase(PG8_LAS unsigned char* lds, PG8_LAS unsigned char* xl, const Gemm g, const Sched& S, const Epi& E, const int wid) {
;     ...
;             PG8_WAIT_V(8); PG8_WAIT_L(0); PG8_BAR; if (do1) { PG8_MMA(1, 0, At, B0); PG8_MMA(1, 1, At, B1); } PG8_BAR; PG8_SCHED;
;             PG8_LDB(B0, 1, 0); PG8_LDB(B1, 1, 1); PG8_SCHED; PG8_LDA(At, 1, 0); PG8_STAGE(PG8_SA(0, 1), a2 + hstepA, voffA);
;             PG8_WAIT_V(8); PG8_WAIT_L(0); PG8_BAR; if (do0) { PG8_MMA(0, 0, At, B0); PG8_MMA(0, 1, At, B1); } PG8_BAR; PG8_SCHED;
	v_mfma_f32_16x16x32_bf16 v[60:63], v[120:123], v[160:163], v[60:63]
	v_mfma_f32_16x16x32_bf16 v[56:59], v[128:131], v[160:163], v[56:59]
	v_mfma_f32_16x16x32_bf16 v[44:47], v[120:123], v[168:171], v[44:47]
	v_mfma_f32_16x16x32_bf16 v[40:43], v[128:131], v[168:171], v[40:43]
	v_mfma_f32_16x16x32_bf16 v[28:31], v[120:123], v[176:179], v[28:31]
	v_mfma_f32_16x16x32_bf16 v[24:27], v[128:131], v[176:179], v[24:27]
	v_mfma_f32_16x16x32_bf16 v[12:15], v[120:123], v[184:187], v[12:15]
	v_mfma_f32_16x16x32_bf16 v[8:11], v[128:131], v[184:187], v[8:11]
	v_mfma_f32_16x16x32_bf16 v[60:63], v[124:127], v[164:167], v[60:63]
	v_mfma_f32_16x16x32_bf16 v[56:59], v[136:139], v[164:167], v[56:59]
	v_mfma_f32_16x16x32_bf16 v[44:47], v[124:127], v[172:175], v[44:47]
	v_mfma_f32_16x16x32_bf16 v[40:43], v[136:139], v[172:175], v[40:43]
	v_mfma_f32_16x16x32_bf16 v[28:31], v[124:127], v[180:183], v[28:31]
	v_mfma_f32_16x16x32_bf16 v[24:27], v[136:139], v[180:183], v[24:27]
	v_mfma_f32_16x16x32_bf16 v[12:15], v[124:127], v[222:225], v[12:15]
	v_mfma_f32_16x16x32_bf16 v[8:11], v[136:139], v[222:225], v[8:11]
	s_setprio 0
	s_setprio 1
	v_mfma_f32_16x16x32_bf16 v[52:55], v[144:147], v[160:163], v[52:55]
	v_mfma_f32_16x16x32_bf16 v[48:51], v[152:155], v[160:163], v[48:51]
	v_mfma_f32_16x16x32_bf16 v[36:39], v[144:147], v[168:171], v[36:39]
	v_mfma_f32_16x16x32_bf16 v[32:35], v[152:155], v[168:171], v[32:35]
	v_mfma_f32_16x16x32_bf16 v[20:23], v[144:147], v[176:179], v[20:23]
	v_mfma_f32_16x16x32_bf16 v[16:19], v[152:155], v[176:179], v[16:19]
	v_mfma_f32_16x16x32_bf16 v[4:7], v[144:147], v[184:187], v[4:7]
	v_mfma_f32_16x16x32_bf16 v[0:3], v[152:155], v[184:187], v[0:3]
	v_mfma_f32_16x16x32_bf16 v[52:55], v[148:151], v[164:167], v[52:55]
	v_mfma_f32_16x16x32_bf16 v[48:51], v[156:159], v[164:167], v[48:51]
	v_mfma_f32_16x16x32_bf16 v[36:39], v[148:151], v[172:175], v[36:39]
	v_mfma_f32_16x16x32_bf16 v[32:35], v[156:159], v[172:175], v[32:35]
	v_mfma_f32_16x16x32_bf16 v[20:23], v[148:151], v[180:183], v[20:23]
	v_mfma_f32_16x16x32_bf16 v[16:19], v[156:159], v[180:183], v[16:19]
	v_mfma_f32_16x16x32_bf16 v[4:7], v[148:151], v[222:225], v[4:7]
	v_mfma_f32_16x16x32_bf16 v[0:3], v[156:159], v[222:225], v[0:3]
	s_barrier
	s_setprio 0
	s_add_i32 s21, 0, 0x18000
	s_add_i32 s31, 0, 0x1c000
	ds_read_b128 v[120:123], v226 offset:32768
	ds_read_b128 v[124:127], v226 offset:33792
	ds_read_b128 v[128:131], v226 offset:34816
	ds_read_b128 v[136:139], v226 offset:35840
	ds_read_b128 v[144:147], v226 offset:49152
	ds_read_b128 v[148:151], v226 offset:50176
	ds_read_b128 v[152:155], v226 offset:51200
	ds_read_b128 v[156:159], v226 offset:52224
	s_add_u32 s100, s48, 0x2c0000
	s_addc_u32 s101, s49, 0
	s_mov_b32 m0, s57
	ds_read_b128 v[160:163], v220 offset:32768
	ds_read_b128 v[164:167], v220 offset:33792
	ds_read_b128 v[168:171], v220 offset:34816
	ds_read_b128 v[172:175], v220 offset:35840
	ds_read_b128 v[176:179], v220 offset:36864
	ds_read_b128 v[180:183], v220 offset:37888
	ds_read_b128 v[184:187], v220 offset:38912
	ds_read_b128 v[222:225], v220 offset:39936
	global_load_lds_dwordx4 v188, s[100:101]
	s_mov_b32 m0, s58
	s_nop 0
	global_load_lds_dwordx4 v210, s[100:101]
	s_waitcnt vmcnt(8)
	s_waitcnt lgkmcnt(0)
	s_setprio 1
	s_barrier
	v_mfma_f32_16x16x32_bf16 v[140:143], v[120:123], v[160:163], v[140:143]
	v_mfma_f32_16x16x32_bf16 v[132:135], v[128:131], v[160:163], v[132:135]
	v_mfma_f32_16x16x32_bf16 v[108:111], v[120:123], v[168:171], v[108:111]
	v_mfma_f32_16x16x32_bf16 v[104:107], v[128:131], v[168:171], v[104:107]
	v_mfma_f32_16x16x32_bf16 v[92:95], v[120:123], v[176:179], v[92:95]
	v_mfma_f32_16x16x32_bf16 v[88:91], v[128:131], v[176:179], v[88:91]
	v_mfma_f32_16x16x32_bf16 v[76:79], v[120:123], v[184:187], v[76:79]
	v_mfma_f32_16x16x32_bf16 v[72:75], v[128:131], v[184:187], v[72:75]
	v_mfma_f32_16x16x32_bf16 v[140:143], v[124:127], v[164:167], v[140:143]
	v_mfma_f32_16x16x32_bf16 v[132:135], v[136:139], v[164:167], v[132:135]
	v_mfma_f32_16x16x32_bf16 v[108:111], v[124:127], v[172:175], v[108:111]
	v_mfma_f32_16x16x32_bf16 v[104:107], v[136:139], v[172:175], v[104:107]
	v_mfma_f32_16x16x32_bf16 v[92:95], v[124:127], v[180:183], v[92:95]
	v_mfma_f32_16x16x32_bf16 v[88:91], v[136:139], v[180:183], v[88:91]
	v_mfma_f32_16x16x32_bf16 v[76:79], v[124:127], v[222:225], v[76:79]
	v_mfma_f32_16x16x32_bf16 v[72:75], v[136:139], v[222:225], v[72:75]
	s_setprio 0
	s_setprio 1
	v_mfma_f32_16x16x32_bf16 v[116:119], v[144:147], v[160:163], v[116:119]
	v_mfma_f32_16x16x32_bf16 v[112:115], v[152:155], v[160:163], v[112:115]
	v_mfma_f32_16x16x32_bf16 v[100:103], v[144:147], v[168:171], v[100:103]
	v_mfma_f32_16x16x32_bf16 v[96:99], v[152:155], v[168:171], v[96:99]
	v_mfma_f32_16x16x32_bf16 v[84:87], v[144:147], v[176:179], v[84:87]
	v_mfma_f32_16x16x32_bf16 v[80:83], v[152:155], v[176:179], v[80:83]
	v_mfma_f32_16x16x32_bf16 v[68:71], v[144:147], v[184:187], v[68:71]
	v_mfma_f32_16x16x32_bf16 v[64:67], v[152:155], v[184:187], v[64:67]
	v_mfma_f32_16x16x32_bf16 v[116:119], v[148:151], v[164:167], v[116:119]
	v_mfma_f32_16x16x32_bf16 v[112:115], v[156:159], v[164:167], v[112:115]
	v_mfma_f32_16x16x32_bf16 v[100:103], v[148:151], v[172:175], v[100:103]
	v_mfma_f32_16x16x32_bf16 v[96:99], v[156:159], v[172:175], v[96:99]
	v_mfma_f32_16x16x32_bf16 v[84:87], v[148:151], v[180:183], v[84:87]
	v_mfma_f32_16x16x32_bf16 v[80:83], v[156:159], v[180:183], v[80:83]
	v_mfma_f32_16x16x32_bf16 v[68:71], v[148:151], v[222:225], v[68:71]
	v_mfma_f32_16x16x32_bf16 v[64:67], v[156:159], v[222:225], v[64:67]
	s_barrier
; #define PG8_STAGE(bufoff, gbase, voff) do { _Pragma("unroll") for (int _i = 0; _i < 2; ++_i) \
;         __builtin_amdgcn_global_load_lds((const unsigned*)((const char*)(gbase) + (voff)[_i]), (PG8_LAS unsigned*)(lds + (bufoff) + ldsw + _i * 8192), 16, 0, 0); } while (0)
; #define PG8_LDA(dst, b, h) do { _Pragma("unroll") for (int m = 0; m < 4; ++m) _Pragma("unroll") for (int k = 0; k < 2; ++k) dst[m][k] = *(const PG8_LAS bf16x8*)(lds + PG8_SA(b, h) + aoff + m * 2048 + k * 1024); } while (0)
; #define PG8_MMA(ai, bj, At, Bt) do { __builtin_amdgcn_s_setprio(1); _Pragma("unroll") for (int m = 0; m < 4; ++m) _Pragma("unroll") for (int n = 0; n < 2; ++n) _Pragma("unroll") for (int k = 0; k < 2; ++k) \
;         acc[ai][bj][m][n] = __builtin_amdgcn_mfma_f32_16x16x32_bf16(Bt[n][k], At[m][k], acc[ai][bj][m][n], 0, 0, 0); __builtin_amdgcn_s_setprio(0); } while (0)
; #define PG8_WAIT_V(n) asm volatile("s_waitcnt vmcnt(" #n ")" ::: "memory")
; #define PG8_WAIT_L(n) asm volatile("s_waitcnt lgkmcnt(" #n ")" ::: "memory")
; #define PG8_BAR __builtin_amdgcn_s_barrier()
; #define PG8_SCHED __builtin_amdgcn_sched_barrier(0)
; template <class Epi>
; __device__ __forceinline__ void gemm_phase(PG8_LAS unsigned char* lds, PG8_LAS unsigned char* xl, const Gemm g, const Sched& S, const Epi& E, const int wid) {
;     ...
;             PG8_LDA(At, 1, 1); PG8_STAGE(PG8_SB(1, 0), b3, voffB); PG8_STAGE(PG8_SB(1, 1), b3 + hstepB, voffB); PG8_STAGE(PG8_SA(1, 0), a3, voffA);
;             PG8_WAIT_V(8); PG8_WAIT_L(0); PG8_BAR; if (do1) { PG8_MMA(1, 0, At, B0); PG8_MMA(1, 1, At, B1); } PG8_BAR; PG8_SCHED;
;         }
	s_setprio 0
	s_add_i32 s21, s21, s29
	s_mov_b32 m0, s21
	ds_read_b128 v[160:163], v220 offset:49152
	ds_read_b128 v[164:167], v220 offset:50176
	ds_read_b128 v[168:171], v220 offset:51200
	ds_read_b128 v[172:175], v220 offset:52224
	ds_read_b128 v[176:179], v220 offset:53248
	ds_read_b128 v[180:183], v220 offset:54272
	ds_read_b128 v[184:187], v220 offset:55296
	ds_read_b128 v[222:225], v220 offset:56320
	global_load_lds_dwordx4 v205, s[44:45]
	s_add_i32 m0, s21, 0x2000
	s_add_u32 s100, s44, 0x80080
	global_load_lds_dwordx4 v219, s[44:45]
	s_addc_u32 s101, s45, 0
	s_add_i32 s21, s31, s29
	s_mov_b32 m0, s21
	s_nop 0
	global_load_lds_dwordx4 v190, s[100:101]
	s_add_i32 m0, s21, 0x2000
	s_nop 0
	global_load_lds_dwordx4 v212, s[100:101]
	s_mov_b32 m0, s66
	s_nop 0
	global_load_lds_dwordx4 v204, s[48:49]
	s_mov_b32 m0, s67
	s_nop 0
	global_load_lds_dwordx4 v218, s[48:49]
	s_waitcnt vmcnt(8)
	s_waitcnt lgkmcnt(0)
	s_setprio 1
	s_barrier
	v_mfma_f32_16x16x32_bf16 v[60:63], v[120:123], v[160:163], v[60:63]
	v_mfma_f32_16x16x32_bf16 v[56:59], v[128:131], v[160:163], v[56:59]
	v_mfma_f32_16x16x32_bf16 v[44:47], v[120:123], v[168:171], v[44:47]
	v_mfma_f32_16x16x32_bf16 v[40:43], v[128:131], v[168:171], v[40:43]
	v_mfma_f32_16x16x32_bf16 v[28:31], v[120:123], v[176:179], v[28:31]
	v_mfma_f32_16x16x32_bf16 v[24:27], v[128:131], v[176:179], v[24:27]
	v_mfma_f32_16x16x32_bf16 v[12:15], v[120:123], v[184:187], v[12:15]
	v_mfma_f32_16x16x32_bf16 v[8:11], v[128:131], v[184:187], v[8:11]
	v_mfma_f32_16x16x32_bf16 v[60:63], v[124:127], v[164:167], v[60:63]
	v_mfma_f32_16x16x32_bf16 v[56:59], v[136:139], v[164:167], v[56:59]
	v_mfma_f32_16x16x32_bf16 v[44:47], v[124:127], v[172:175], v[44:47]
	v_mfma_f32_16x16x32_bf16 v[40:43], v[136:139], v[172:175], v[40:43]
	v_mfma_f32_16x16x32_bf16 v[28:31], v[124:127], v[180:183], v[28:31]
	v_mfma_f32_16x16x32_bf16 v[24:27], v[136:139], v[180:183], v[24:27]
	v_mfma_f32_16x16x32_bf16 v[12:15], v[124:127], v[222:225], v[12:15]
	v_mfma_f32_16x16x32_bf16 v[8:11], v[136:139], v[222:225], v[8:11]
	s_setprio 0
	s_setprio 1
	v_mfma_f32_16x16x32_bf16 v[52:55], v[144:147], v[160:163], v[52:55]
	v_mfma_f32_16x16x32_bf16 v[48:51], v[152:155], v[160:163], v[48:51]
	v_mfma_f32_16x16x32_bf16 v[36:39], v[144:147], v[168:171], v[36:39]
	v_mfma_f32_16x16x32_bf16 v[32:35], v[152:155], v[168:171], v[32:35]
	v_mfma_f32_16x16x32_bf16 v[20:23], v[144:147], v[176:179], v[20:23]
	v_mfma_f32_16x16x32_bf16 v[16:19], v[152:155], v[176:179], v[16:19]
	v_mfma_f32_16x16x32_bf16 v[4:7], v[144:147], v[184:187], v[4:7]
	v_mfma_f32_16x16x32_bf16 v[0:3], v[152:155], v[184:187], v[0:3]
	v_mfma_f32_16x16x32_bf16 v[52:55], v[148:151], v[164:167], v[52:55]
	v_mfma_f32_16x16x32_bf16 v[48:51], v[156:159], v[164:167], v[48:51]
	v_mfma_f32_16x16x32_bf16 v[36:39], v[148:151], v[172:175], v[36:39]
	v_mfma_f32_16x16x32_bf16 v[32:35], v[156:159], v[172:175], v[32:35]
	v_mfma_f32_16x16x32_bf16 v[20:23], v[148:151], v[180:183], v[20:23]
	v_mfma_f32_16x16x32_bf16 v[16:19], v[156:159], v[180:183], v[16:19]
	v_mfma_f32_16x16x32_bf16 v[4:7], v[148:151], v[222:225], v[4:7]
	v_mfma_f32_16x16x32_bf16 v[0:3], v[156:159], v[222:225], v[0:3]
	s_barrier
	s_setprio 0
	s_add_i32 s13, s13, 2
	s_add_u32 s42, s42, 0x100
	s_addc_u32 s43, s43, 0
	s_add_u32 s10, s10, 0x100
	s_addc_u32 s11, s11, 0
	s_cmp_gt_u32 s13, 29
	s_cbranch_scc0 .LBB0_765
	s_mov_b32 s100, 0
	s_and_b64 vcc, exec, s[14:15]
	s_cbranch_vccz .LBB0_768
	s_barrier

; #define PG8_STAGE(bufoff, gbase, voff) do { _Pragma("unroll") for (int _i = 0; _i < 2; ++_i) \
;         __builtin_amdgcn_global_load_lds((const unsigned*)((const char*)(gbase) + (voff)[_i]), (PG8_LAS unsigned*)(lds + (bufoff) + ldsw + _i * 8192), 16, 0, 0); } while (0)
; #define PG8_LDA(dst, b, h) do { _Pragma("unroll") for (int m = 0; m < 4; ++m) _Pragma("unroll") for (int k = 0; k < 2; ++k) dst[m][k] = *(const PG8_LAS bf16x8*)(lds + PG8_SA(b, h) + aoff + m * 2048 + k * 1024); } while (0)
; #define PG8_LDB(dst, b, h) do { _Pragma("unroll") for (int n = 0; n < 2; ++n) _Pragma("unroll") for (int k = 0; k < 2; ++k) dst[n][k] = *(const PG8_LAS bf16x8*)(lds + PG8_SB(b, h) + boff + n * 2048 + k * 1024); } while (0)
; #define PG8_MMA(ai, bj, At, Bt) do { __builtin_amdgcn_s_setprio(1); _Pragma("unroll") for (int m = 0; m < 4; ++m) _Pragma("unroll") for (int n = 0; n < 2; ++n) _Pragma("unroll") for (int k = 0; k < 2; ++k) \
;         acc[ai][bj][m][n] = __builtin_amdgcn_mfma_f32_16x16x32_bf16(Bt[n][k], At[m][k], acc[ai][bj][m][n], 0, 0, 0); __builtin_amdgcn_s_setprio(0); } while (0)
; #define PG8_WAIT_V(n) asm volatile("s_waitcnt vmcnt(" #n ")" ::: "memory")
; #define PG8_WAIT_L(n) asm volatile("s_waitcnt lgkmcnt(" #n ")" ::: "memory")
; #define PG8_BAR __builtin_amdgcn_s_barrier()
; #define PG8_SCHED __builtin_amdgcn_sched_barrier(0)
; template <class Epi>
; __device__ __forceinline__ void gemm_phase(PG8_LAS unsigned char* lds, PG8_LAS unsigned char* xl, const Gemm g, const Sched& S, const Epi& E, const int wid) {
;     ...
;             const char* a1 = cA + (size_t)(t + 1) * kstep + j1;
;             const char* a2 = last ? nA : cA + (size_t)(t + 2) * kstep + ja2; const char* b2 = last ? nB : cB + (size_t)(t + 2) * kstep + jb2;
;             const char* a3 = a2 + kstep; const char* b3 = b2 + kstep;
;             PG8_LDB(B0, 0, 0); PG8_LDB(B1, 0, 1); PG8_SCHED; PG8_LDA(At, 0, 0); PG8_STAGE(PG8_SA(1, 1), a1 + hstepA, voffA);
;             PG8_WAIT_V(8); PG8_WAIT_L(0); PG8_BAR; if (do0) { PG8_MMA(0, 0, At, B0); PG8_MMA(0, 1, At, B1); } PG8_BAR; PG8_SCHED;
;             PG8_LDA(At, 0, 1); PG8_STAGE(PG8_SB(0, 0), b2, voffB); PG8_STAGE(PG8_SB(0, 1), b2 + hstepB, voffB); PG8_STAGE(PG8_SA(0, 0), a2, voffA);
.Ldefbar_skip_7:
	v_add_u32_e32 v204, s22, v184
	v_add_u32_e32 v205, s22, v186
	v_add_u32_e32 v214, s22, v188
	v_add_u32_e32 v215, s22, v190
	v_add_u32_e32 v226, 0x10000, v195
.LBB0_859:
	s_add_u32 s46, s48, 0x100
	s_addc_u32 s47, s49, 0
	s_add_i32 s11, 0, 0x10000
	s_cmp_eq_u32 s10, 28
	s_cselect_b32 vcc_hi, s59, s47
	s_cselect_b32 vcc_lo, s58, s46
	s_cselect_b32 s51, s21, s9
	s_cselect_b32 s50, s20, s8
	s_add_i32 s13, 0, 0x14000
	ds_read_b128 v[120:123], v226 offset:0
	ds_read_b128 v[124:127], v226 offset:1024
	ds_read_b128 v[136:139], v226 offset:2048
	ds_read_b128 v[140:143], v226 offset:3072
	ds_read_b128 v[144:147], v226 offset:16384
	ds_read_b128 v[148:151], v226 offset:17408
	ds_read_b128 v[152:155], v226 offset:18432
	ds_read_b128 v[156:159], v226 offset:19456
	s_add_i32 m0, s89, 0xc000
	ds_read_b128 v[160:163], v216
	ds_read_b128 v[164:167], v216 offset:1024
	ds_read_b128 v[168:171], v216 offset:2048
	ds_read_b128 v[172:175], v216 offset:3072
	ds_read_b128 v[176:179], v216 offset:4096
	ds_read_b128 v[180:183], v216 offset:5120
	ds_read_b128 v[218:221], v216 offset:6144
	ds_read_b128 v[222:225], v216 offset:7168
	global_load_lds_dwordx4 v210, s[48:49]
	s_add_i32 m0, s89, 0xe000
	s_nop 0
	global_load_lds_dwordx4 v212, s[48:49]
	s_waitcnt vmcnt(8)
	s_waitcnt lgkmcnt(0)
	s_setprio 1
	s_barrier
	v_mfma_f32_16x16x32_bf16 v[132:135], v[120:123], v[160:163], v[132:135]
	v_mfma_f32_16x16x32_bf16 v[128:131], v[136:139], v[160:163], v[128:131]
	v_mfma_f32_16x16x32_bf16 v[108:111], v[120:123], v[168:171], v[108:111]
	v_mfma_f32_16x16x32_bf16 v[104:107], v[136:139], v[168:171], v[104:107]
	v_mfma_f32_16x16x32_bf16 v[92:95], v[120:123], v[176:179], v[92:95]
	v_mfma_f32_16x16x32_bf16 v[88:91], v[136:139], v[176:179], v[88:91]
	v_mfma_f32_16x16x32_bf16 v[76:79], v[120:123], v[218:221], v[76:79]
	v_mfma_f32_16x16x32_bf16 v[72:75], v[136:139], v[218:221], v[72:75]
	v_mfma_f32_16x16x32_bf16 v[132:135], v[124:127], v[164:167], v[132:135]
	v_mfma_f32_16x16x32_bf16 v[128:131], v[140:143], v[164:167], v[128:131]
	v_mfma_f32_16x16x32_bf16 v[108:111], v[124:127], v[172:175], v[108:111]
	v_mfma_f32_16x16x32_bf16 v[104:107], v[140:143], v[172:175], v[104:107]
	v_mfma_f32_16x16x32_bf16 v[92:95], v[124:127], v[180:183], v[92:95]
	v_mfma_f32_16x16x32_bf16 v[88:91], v[140:143], v[180:183], v[88:91]
	v_mfma_f32_16x16x32_bf16 v[76:79], v[124:127], v[222:225], v[76:79]
	v_mfma_f32_16x16x32_bf16 v[72:75], v[140:143], v[222:225], v[72:75]
	s_setprio 0
	s_setprio 1
	v_mfma_f32_16x16x32_bf16 v[116:119], v[144:147], v[160:163], v[116:119]
	v_mfma_f32_16x16x32_bf16 v[112:115], v[152:155], v[160:163], v[112:115]
	v_mfma_f32_16x16x32_bf16 v[100:103], v[144:147], v[168:171], v[100:103]
	v_mfma_f32_16x16x32_bf16 v[96:99], v[152:155], v[168:171], v[96:99]
	v_mfma_f32_16x16x32_bf16 v[84:87], v[144:147], v[176:179], v[84:87]
	v_mfma_f32_16x16x32_bf16 v[80:83], v[152:155], v[176:179], v[80:83]
	v_mfma_f32_16x16x32_bf16 v[68:71], v[144:147], v[218:221], v[68:71]
	v_mfma_f32_16x16x32_bf16 v[64:67], v[152:155], v[218:221], v[64:67]
	v_mfma_f32_16x16x32_bf16 v[116:119], v[148:151], v[164:167], v[116:119]
	v_mfma_f32_16x16x32_bf16 v[112:115], v[156:159], v[164:167], v[112:115]
	v_mfma_f32_16x16x32_bf16 v[100:103], v[148:151], v[172:175], v[100:103]
	v_mfma_f32_16x16x32_bf16 v[96:99], v[156:159], v[172:175], v[96:99]
	v_mfma_f32_16x16x32_bf16 v[84:87], v[148:151], v[180:183], v[84:87]
	v_mfma_f32_16x16x32_bf16 v[80:83], v[156:159], v[180:183], v[80:83]
	v_mfma_f32_16x16x32_bf16 v[68:71], v[148:151], v[222:225], v[68:71]
	v_mfma_f32_16x16x32_bf16 v[64:67], v[156:159], v[222:225], v[64:67]
	s_barrier
	s_setprio 0
	s_add_i32 s11, s11, s29
	s_mov_b32 m0, s11
	ds_read_b128 v[160:163], v216 offset:16384
	ds_read_b128 v[164:167], v216 offset:17408
	ds_read_b128 v[168:171], v216 offset:18432
	ds_read_b128 v[172:175], v216 offset:19456
	ds_read_b128 v[176:179], v216 offset:20480
	ds_read_b128 v[180:183], v216 offset:21504
	ds_read_b128 v[218:221], v216 offset:22528
	ds_read_b128 v[222:225], v216 offset:23552
	global_load_lds_dwordx4 v186, s[50:51]
	s_add_i32 m0, s11, 0x2000
	s_add_u32 s48, s50, 0x80000
	s_addc_u32 s49, s51, 0
	s_add_i32 s11, s13, s29
	global_load_lds_dwordx4 v190, s[50:51]
	s_mov_b32 m0, s11
	s_nop 0
	global_load_lds_dwordx4 v186, s[48:49]
	s_add_i32 m0, s11, 0x2000
	s_nop 0
	global_load_lds_dwordx4 v190, s[48:49]
	s_mov_b32 m0, s89
	s_nop 0
	global_load_lds_dwordx4 v184, vcc
	s_mov_b32 m0, s90
	s_nop 0
	global_load_lds_dwordx4 v188, vcc
	s_waitcnt vmcnt(8)
	s_waitcnt lgkmcnt(0)
	s_setprio 1
	s_barrier
; #define PG8_STAGE(bufoff, gbase, voff) do { _Pragma("unroll") for (int _i = 0; _i < 2; ++_i) \
;         __builtin_amdgcn_global_load_lds((const unsigned*)((const char*)(gbase) + (voff)[_i]), (PG8_LAS unsigned*)(lds + (bufoff) + ldsw + _i * 8192), 16, 0, 0); } while (0)
; #define PG8_LDA(dst, b, h) do { _Pragma("unroll") for (int m = 0; m < 4; ++m) _Pragma("unroll") for (int k = 0; k < 2; ++k) dst[m][k] = *(const PG8_LAS bf16x8*)(lds + PG8_SA(b, h) + aoff + m * 2048 + k * 1024); } while (0)
; #define PG8_LDB(dst, b, h) do { _Pragma("unroll") for (int n = 0; n < 2; ++n) _Pragma("unroll") for (int k = 0; k < 2; ++k) dst[n][k] = *(const PG8_LAS bf16x8*)(lds + PG8_SB(b, h) + boff + n * 2048 + k * 1024); } while (0)
; #define PG8_MMA(ai, bj, At, Bt) do { __builtin_amdgcn_s_setprio(1); _Pragma("unroll") for (int m = 0; m < 4; ++m) _Pragma("unroll") for (int n = 0; n < 2; ++n) _Pragma("unroll") for (int k = 0; k < 2; ++k) \
;         acc[ai][bj][m][n] = __builtin_amdgcn_mfma_f32_16x16x32_bf16(Bt[n][k], At[m][k], acc[ai][bj][m][n], 0, 0, 0); __builtin_amdgcn_s_setprio(0); } while (0)
; #define PG8_WAIT_V(n) asm volatile("s_waitcnt vmcnt(" #n ")" ::: "memory")
; #define PG8_WAIT_L(n) asm volatile("s_waitcnt lgkmcnt(" #n ")" ::: "memory")
; #define PG8_BAR __builtin_amdgcn_s_barrier()
; #define PG8_SCHED __builtin_amdgcn_sched_barrier(0)
; template <class Epi>
; __device__ __forceinline__ void gemm_phase(PG8_LAS unsigned char* lds, PG8_LAS unsigned char* xl, const Gemm g, const Sched& S, const Epi& E, const int wid) {
;     ...
;             PG8_WAIT_V(8); PG8_WAIT_L(0); PG8_BAR; if (do1) { PG8_MMA(1, 0, At, B0); PG8_MMA(1, 1, At, B1); } PG8_BAR; PG8_SCHED;
;             PG8_LDB(B0, 1, 0); PG8_LDB(B1, 1, 1); PG8_SCHED; PG8_LDA(At, 1, 0); PG8_STAGE(PG8_SA(0, 1), a2 + hstepA, voffA);
;             PG8_WAIT_V(8); PG8_WAIT_L(0); PG8_BAR; if (do0) { PG8_MMA(0, 0, At, B0); PG8_MMA(0, 1, At, B1); } PG8_BAR; PG8_SCHED;
	v_mfma_f32_16x16x32_bf16 v[60:63], v[120:123], v[160:163], v[60:63]
	v_mfma_f32_16x16x32_bf16 v[56:59], v[136:139], v[160:163], v[56:59]
	v_mfma_f32_16x16x32_bf16 v[44:47], v[120:123], v[168:171], v[44:47]
	v_mfma_f32_16x16x32_bf16 v[40:43], v[136:139], v[168:171], v[40:43]
	v_mfma_f32_16x16x32_bf16 v[28:31], v[120:123], v[176:179], v[28:31]
	v_mfma_f32_16x16x32_bf16 v[24:27], v[136:139], v[176:179], v[24:27]
	v_mfma_f32_16x16x32_bf16 v[12:15], v[120:123], v[218:221], v[12:15]
	v_mfma_f32_16x16x32_bf16 v[8:11], v[136:139], v[218:221], v[8:11]
	v_mfma_f32_16x16x32_bf16 v[60:63], v[124:127], v[164:167], v[60:63]
	v_mfma_f32_16x16x32_bf16 v[56:59], v[140:143], v[164:167], v[56:59]
	v_mfma_f32_16x16x32_bf16 v[44:47], v[124:127], v[172:175], v[44:47]
	v_mfma_f32_16x16x32_bf16 v[40:43], v[140:143], v[172:175], v[40:43]
	v_mfma_f32_16x16x32_bf16 v[28:31], v[124:127], v[180:183], v[28:31]
	v_mfma_f32_16x16x32_bf16 v[24:27], v[140:143], v[180:183], v[24:27]
	v_mfma_f32_16x16x32_bf16 v[12:15], v[124:127], v[222:225], v[12:15]
	v_mfma_f32_16x16x32_bf16 v[8:11], v[140:143], v[222:225], v[8:11]
	s_setprio 0
	s_setprio 1
	v_mfma_f32_16x16x32_bf16 v[52:55], v[144:147], v[160:163], v[52:55]
	v_mfma_f32_16x16x32_bf16 v[48:51], v[152:155], v[160:163], v[48:51]
	v_mfma_f32_16x16x32_bf16 v[36:39], v[144:147], v[168:171], v[36:39]
	v_mfma_f32_16x16x32_bf16 v[32:35], v[152:155], v[168:171], v[32:35]
	v_mfma_f32_16x16x32_bf16 v[20:23], v[144:147], v[176:179], v[20:23]
	v_mfma_f32_16x16x32_bf16 v[16:19], v[152:155], v[176:179], v[16:19]
	v_mfma_f32_16x16x32_bf16 v[4:7], v[144:147], v[218:221], v[4:7]
	v_mfma_f32_16x16x32_bf16 v[0:3], v[152:155], v[218:221], v[0:3]
	v_mfma_f32_16x16x32_bf16 v[52:55], v[148:151], v[164:167], v[52:55]
	v_mfma_f32_16x16x32_bf16 v[48:51], v[156:159], v[164:167], v[48:51]
	v_mfma_f32_16x16x32_bf16 v[36:39], v[148:151], v[172:175], v[36:39]
	v_mfma_f32_16x16x32_bf16 v[32:35], v[156:159], v[172:175], v[32:35]
	v_mfma_f32_16x16x32_bf16 v[20:23], v[148:151], v[180:183], v[20:23]
	v_mfma_f32_16x16x32_bf16 v[16:19], v[156:159], v[180:183], v[16:19]
	v_mfma_f32_16x16x32_bf16 v[4:7], v[148:151], v[222:225], v[4:7]
	v_mfma_f32_16x16x32_bf16 v[0:3], v[156:159], v[222:225], v[0:3]
	s_barrier
	s_setprio 0
	s_add_i32 s11, 0, 0x18000
	s_add_i32 s13, 0, 0x1c000
	ds_read_b128 v[120:123], v226 offset:32768
	ds_read_b128 v[124:127], v226 offset:33792
	ds_read_b128 v[136:139], v226 offset:34816
	ds_read_b128 v[140:143], v226 offset:35840
	ds_read_b128 v[144:147], v226 offset:49152
	ds_read_b128 v[148:151], v226 offset:50176
	ds_read_b128 v[152:155], v226 offset:51200
	ds_read_b128 v[156:159], v226 offset:52224
	s_add_u32 s48, vcc_lo, 0x80000
	s_addc_u32 s49, vcc_hi, 0
	s_mov_b32 m0, s91
	ds_read_b128 v[160:163], v216 offset:32768
	ds_read_b128 v[164:167], v216 offset:33792
	ds_read_b128 v[168:171], v216 offset:34816
	ds_read_b128 v[172:175], v216 offset:35840
	ds_read_b128 v[176:179], v216 offset:36864
	ds_read_b128 v[180:183], v216 offset:37888
	ds_read_b128 v[218:221], v216 offset:38912
	ds_read_b128 v[222:225], v216 offset:39936
	global_load_lds_dwordx4 v184, s[48:49]
	s_mov_b32 m0, s92
	s_nop 0
	global_load_lds_dwordx4 v188, s[48:49]
	s_waitcnt vmcnt(8)
	s_waitcnt lgkmcnt(0)
	s_setprio 1
	s_barrier
	v_mfma_f32_16x16x32_bf16 v[132:135], v[120:123], v[160:163], v[132:135]
	v_mfma_f32_16x16x32_bf16 v[128:131], v[136:139], v[160:163], v[128:131]
	v_mfma_f32_16x16x32_bf16 v[108:111], v[120:123], v[168:171], v[108:111]
	v_mfma_f32_16x16x32_bf16 v[104:107], v[136:139], v[168:171], v[104:107]
	v_mfma_f32_16x16x32_bf16 v[92:95], v[120:123], v[176:179], v[92:95]
	v_mfma_f32_16x16x32_bf16 v[88:91], v[136:139], v[176:179], v[88:91]
	v_mfma_f32_16x16x32_bf16 v[76:79], v[120:123], v[218:221], v[76:79]
	v_mfma_f32_16x16x32_bf16 v[72:75], v[136:139], v[218:221], v[72:75]
	v_mfma_f32_16x16x32_bf16 v[132:135], v[124:127], v[164:167], v[132:135]
	v_mfma_f32_16x16x32_bf16 v[128:131], v[140:143], v[164:167], v[128:131]
	v_mfma_f32_16x16x32_bf16 v[108:111], v[124:127], v[172:175], v[108:111]
	v_mfma_f32_16x16x32_bf16 v[104:107], v[140:143], v[172:175], v[104:107]
	v_mfma_f32_16x16x32_bf16 v[92:95], v[124:127], v[180:183], v[92:95]
	v_mfma_f32_16x16x32_bf16 v[88:91], v[140:143], v[180:183], v[88:91]
	v_mfma_f32_16x16x32_bf16 v[76:79], v[124:127], v[222:225], v[76:79]
	v_mfma_f32_16x16x32_bf16 v[72:75], v[140:143], v[222:225], v[72:75]
	s_setprio 0
	s_setprio 1
	v_mfma_f32_16x16x32_bf16 v[116:119], v[144:147], v[160:163], v[116:119]
	v_mfma_f32_16x16x32_bf16 v[112:115], v[152:155], v[160:163], v[112:115]
	v_mfma_f32_16x16x32_bf16 v[100:103], v[144:147], v[168:171], v[100:103]
	v_mfma_f32_16x16x32_bf16 v[96:99], v[152:155], v[168:171], v[96:99]
	v_mfma_f32_16x16x32_bf16 v[84:87], v[144:147], v[176:179], v[84:87]
	v_mfma_f32_16x16x32_bf16 v[80:83], v[152:155], v[176:179], v[80:83]
	v_mfma_f32_16x16x32_bf16 v[68:71], v[144:147], v[218:221], v[68:71]
	v_mfma_f32_16x16x32_bf16 v[64:67], v[152:155], v[218:221], v[64:67]
	v_mfma_f32_16x16x32_bf16 v[116:119], v[148:151], v[164:167], v[116:119]
	v_mfma_f32_16x16x32_bf16 v[112:115], v[156:159], v[164:167], v[112:115]
	v_mfma_f32_16x16x32_bf16 v[100:103], v[148:151], v[172:175], v[100:103]
	v_mfma_f32_16x16x32_bf16 v[96:99], v[156:159], v[172:175], v[96:99]
	v_mfma_f32_16x16x32_bf16 v[84:87], v[148:151], v[180:183], v[84:87]
	v_mfma_f32_16x16x32_bf16 v[80:83], v[156:159], v[180:183], v[80:83]
	v_mfma_f32_16x16x32_bf16 v[68:71], v[148:151], v[222:225], v[68:71]
	v_mfma_f32_16x16x32_bf16 v[64:67], v[156:159], v[222:225], v[64:67]
	s_barrier
; #define PG8_STAGE(bufoff, gbase, voff) do { _Pragma("unroll") for (int _i = 0; _i < 2; ++_i) \
;         __builtin_amdgcn_global_load_lds((const unsigned*)((const char*)(gbase) + (voff)[_i]), (PG8_LAS unsigned*)(lds + (bufoff) + ldsw + _i * 8192), 16, 0, 0); } while (0)
; #define PG8_LDA(dst, b, h) do { _Pragma("unroll") for (int m = 0; m < 4; ++m) _Pragma("unroll") for (int k = 0; k < 2; ++k) dst[m][k] = *(const PG8_LAS bf16x8*)(lds + PG8_SA(b, h) + aoff + m * 2048 + k * 1024); } while (0)
; #define PG8_MMA(ai, bj, At, Bt) do { __builtin_amdgcn_s_setprio(1); _Pragma("unroll") for (int m = 0; m < 4; ++m) _Pragma("unroll") for (int n = 0; n < 2; ++n) _Pragma("unroll") for (int k = 0; k < 2; ++k) \
;         acc[ai][bj][m][n] = __builtin_amdgcn_mfma_f32_16x16x32_bf16(Bt[n][k], At[m][k], acc[ai][bj][m][n], 0, 0, 0); __builtin_amdgcn_s_setprio(0); } while (0)
; #define PG8_WAIT_V(n) asm volatile("s_waitcnt vmcnt(" #n ")" ::: "memory")
; #define PG8_WAIT_L(n) asm volatile("s_waitcnt lgkmcnt(" #n ")" ::: "memory")
; #define PG8_BAR __builtin_amdgcn_s_barrier()
; #define PG8_SCHED __builtin_amdgcn_sched_barrier(0)
; template <class Epi>
; __device__ __forceinline__ void gemm_phase(PG8_LAS unsigned char* lds, PG8_LAS unsigned char* xl, const Gemm g, const Sched& S, const Epi& E, const int wid) {
;     ...
;             PG8_LDA(At, 1, 1); PG8_STAGE(PG8_SB(1, 0), b3, voffB); PG8_STAGE(PG8_SB(1, 1), b3 + hstepB, voffB); PG8_STAGE(PG8_SA(1, 0), a3, voffA);
;             PG8_WAIT_V(8); PG8_WAIT_L(0); PG8_BAR; if (do1) { PG8_MMA(1, 0, At, B0); PG8_MMA(1, 1, At, B1); } PG8_BAR; PG8_SCHED;
;         }
	s_setprio 0
	s_add_i32 s11, s11, s29
	s_mov_b32 m0, s11
	ds_read_b128 v[160:163], v216 offset:49152
	ds_read_b128 v[164:167], v216 offset:50176
	ds_read_b128 v[168:171], v216 offset:51200
	ds_read_b128 v[172:175], v216 offset:52224
	ds_read_b128 v[176:179], v216 offset:53248
	ds_read_b128 v[180:183], v216 offset:54272
	ds_read_b128 v[218:221], v216 offset:55296
	ds_read_b128 v[222:225], v216 offset:56320
	global_load_lds_dwordx4 v205, s[50:51]
	s_add_i32 m0, s11, 0x2000
	s_add_u32 s48, s50, 0x80080
	global_load_lds_dwordx4 v215, s[50:51]
	s_addc_u32 s49, s51, 0
	s_add_i32 s11, s13, s29
	s_mov_b32 m0, s11
	s_nop 0
	global_load_lds_dwordx4 v186, s[48:49]
	s_add_i32 m0, s11, 0x2000
	s_nop 0
	global_load_lds_dwordx4 v190, s[48:49]
	s_mov_b32 m0, s95
	s_nop 0
	global_load_lds_dwordx4 v204, vcc
	s_mov_b32 m0, s96
	s_nop 0
	global_load_lds_dwordx4 v214, vcc
	s_waitcnt vmcnt(8)
	s_waitcnt lgkmcnt(0)
	s_setprio 1
	s_barrier
	v_mfma_f32_16x16x32_bf16 v[60:63], v[120:123], v[160:163], v[60:63]
	v_mfma_f32_16x16x32_bf16 v[56:59], v[136:139], v[160:163], v[56:59]
	v_mfma_f32_16x16x32_bf16 v[44:47], v[120:123], v[168:171], v[44:47]
	v_mfma_f32_16x16x32_bf16 v[40:43], v[136:139], v[168:171], v[40:43]
	v_mfma_f32_16x16x32_bf16 v[28:31], v[120:123], v[176:179], v[28:31]
	v_mfma_f32_16x16x32_bf16 v[24:27], v[136:139], v[176:179], v[24:27]
	v_mfma_f32_16x16x32_bf16 v[12:15], v[120:123], v[218:221], v[12:15]
	v_mfma_f32_16x16x32_bf16 v[8:11], v[136:139], v[218:221], v[8:11]
	v_mfma_f32_16x16x32_bf16 v[60:63], v[124:127], v[164:167], v[60:63]
	v_mfma_f32_16x16x32_bf16 v[56:59], v[140:143], v[164:167], v[56:59]
	v_mfma_f32_16x16x32_bf16 v[44:47], v[124:127], v[172:175], v[44:47]
	v_mfma_f32_16x16x32_bf16 v[40:43], v[140:143], v[172:175], v[40:43]
	v_mfma_f32_16x16x32_bf16 v[28:31], v[124:127], v[180:183], v[28:31]
	v_mfma_f32_16x16x32_bf16 v[24:27], v[140:143], v[180:183], v[24:27]
	v_mfma_f32_16x16x32_bf16 v[12:15], v[124:127], v[222:225], v[12:15]
	v_mfma_f32_16x16x32_bf16 v[8:11], v[140:143], v[222:225], v[8:11]
	s_setprio 0
	s_setprio 1
	v_mfma_f32_16x16x32_bf16 v[52:55], v[144:147], v[160:163], v[52:55]
	v_mfma_f32_16x16x32_bf16 v[48:51], v[152:155], v[160:163], v[48:51]
	v_mfma_f32_16x16x32_bf16 v[36:39], v[144:147], v[168:171], v[36:39]
	v_mfma_f32_16x16x32_bf16 v[32:35], v[152:155], v[168:171], v[32:35]
	v_mfma_f32_16x16x32_bf16 v[20:23], v[144:147], v[176:179], v[20:23]
	v_mfma_f32_16x16x32_bf16 v[16:19], v[152:155], v[176:179], v[16:19]
	v_mfma_f32_16x16x32_bf16 v[4:7], v[144:147], v[218:221], v[4:7]
	v_mfma_f32_16x16x32_bf16 v[0:3], v[152:155], v[218:221], v[0:3]
	v_mfma_f32_16x16x32_bf16 v[52:55], v[148:151], v[164:167], v[52:55]
	v_mfma_f32_16x16x32_bf16 v[48:51], v[156:159], v[164:167], v[48:51]
	v_mfma_f32_16x16x32_bf16 v[36:39], v[148:151], v[172:175], v[36:39]
	v_mfma_f32_16x16x32_bf16 v[32:35], v[156:159], v[172:175], v[32:35]
	v_mfma_f32_16x16x32_bf16 v[20:23], v[148:151], v[180:183], v[20:23]
	v_mfma_f32_16x16x32_bf16 v[16:19], v[156:159], v[180:183], v[16:19]
	v_mfma_f32_16x16x32_bf16 v[4:7], v[148:151], v[222:225], v[4:7]
	v_mfma_f32_16x16x32_bf16 v[0:3], v[156:159], v[222:225], v[0:3]
	s_barrier
	s_setprio 0
	s_add_i32 s10, s10, 2
	s_add_u32 s8, s8, 0x100
	s_addc_u32 s9, s9, 0
	s_cmp_gt_u32 s10, 29
	s_mov_b64 s[48:49], s[46:47]
	s_cbranch_scc0 .LBB0_859
	s_and_b64 vcc, exec, s[14:15]
	s_cbranch_vccz .LBB0_862
	s_barrier

; #define PG8_STAGE(bufoff, gbase, voff) do { _Pragma("unroll") for (int _i = 0; _i < 2; ++_i) \
;         __builtin_amdgcn_global_load_lds((const unsigned*)((const char*)(gbase) + (voff)[_i]), (PG8_LAS unsigned*)(lds + (bufoff) + ldsw + _i * 8192), 16, 0, 0); } while (0)
; #define PG8_LDA(dst, b, h) do { _Pragma("unroll") for (int m = 0; m < 4; ++m) _Pragma("unroll") for (int k = 0; k < 2; ++k) dst[m][k] = *(const PG8_LAS bf16x8*)(lds + PG8_SA(b, h) + aoff + m * 2048 + k * 1024); } while (0)
; #define PG8_LDB(dst, b, h) do { _Pragma("unroll") for (int n = 0; n < 2; ++n) _Pragma("unroll") for (int k = 0; k < 2; ++k) dst[n][k] = *(const PG8_LAS bf16x8*)(lds + PG8_SB(b, h) + boff + n * 2048 + k * 1024); } while (0)
; #define PG8_MMA(ai, bj, At, Bt) do { __builtin_amdgcn_s_setprio(1); _Pragma("unroll") for (int m = 0; m < 4; ++m) _Pragma("unroll") for (int n = 0; n < 2; ++n) _Pragma("unroll") for (int k = 0; k < 2; ++k) \
;         acc[ai][bj][m][n] = __builtin_amdgcn_mfma_f32_16x16x32_bf16(Bt[n][k], At[m][k], acc[ai][bj][m][n], 0, 0, 0); __builtin_amdgcn_s_setprio(0); } while (0)
; #define PG8_WAIT_V(n) asm volatile("s_waitcnt vmcnt(" #n ")" ::: "memory")
; #define PG8_WAIT_L(n) asm volatile("s_waitcnt lgkmcnt(" #n ")" ::: "memory")
; #define PG8_BAR __builtin_amdgcn_s_barrier()
; #define PG8_SCHED __builtin_amdgcn_sched_barrier(0)
; template <class Epi>
; __device__ __forceinline__ void gemm_phase(PG8_LAS unsigned char* lds, PG8_LAS unsigned char* xl, const Gemm g, const Sched& S, const Epi& E, const int wid) {
;     ...
;             const char* a1 = cA + (size_t)(t + 1) * kstep + j1;
;             const char* a2 = last ? nA : cA + (size_t)(t + 2) * kstep + ja2; const char* b2 = last ? nB : cB + (size_t)(t + 2) * kstep + jb2;
;             const char* a3 = a2 + kstep; const char* b3 = b2 + kstep;
;             PG8_LDB(B0, 0, 0); PG8_LDB(B1, 0, 1); PG8_SCHED; PG8_LDA(At, 0, 0); PG8_STAGE(PG8_SA(1, 1), a1 + hstepA, voffA);
;             PG8_WAIT_V(8); PG8_WAIT_L(0); PG8_BAR; if (do0) { PG8_MMA(0, 0, At, B0); PG8_MMA(0, 1, At, B1); } PG8_BAR; PG8_SCHED;
;             PG8_LDA(At, 0, 1); PG8_STAGE(PG8_SB(0, 0), b2, voffB); PG8_STAGE(PG8_SB(0, 1), b2 + hstepB, voffB); PG8_STAGE(PG8_SA(0, 0), a2, voffA);
;             PG8_WAIT_V(8); PG8_WAIT_L(0); PG8_BAR; if (do1) { PG8_MMA(1, 0, At, B0); PG8_MMA(1, 1, At, B1); } PG8_BAR; PG8_SCHED;
.LBB0_959:
	s_add_u32 s56, s52, 0x100
	s_addc_u32 s57, s53, 0
	s_add_i32 s11, 0, 0x10000
	s_cmp_eq_u32 s10, 12
	s_cselect_b32 s61, s47, s57
	s_cselect_b32 s60, s46, s56
	s_cselect_b32 s59, s51, s9
	s_cselect_b32 s58, s50, s8
	s_add_i32 s13, 0, 0x14000
	ds_read_b128 v[124:127], v226 offset:0
	ds_read_b128 v[128:131], v226 offset:1024
	ds_read_b128 v[136:139], v226 offset:2048
	ds_read_b128 v[140:143], v226 offset:3072
	ds_read_b128 v[144:147], v226 offset:16384
	ds_read_b128 v[148:151], v226 offset:17408
	ds_read_b128 v[152:155], v226 offset:18432
	ds_read_b128 v[156:159], v226 offset:19456
	s_add_i32 m0, s66, 0xc000
	ds_read_b128 v[160:163], v220
	ds_read_b128 v[164:167], v220 offset:1024
	ds_read_b128 v[168:171], v220 offset:2048
	ds_read_b128 v[172:175], v220 offset:3072
	ds_read_b128 v[176:179], v220 offset:4096
	ds_read_b128 v[180:183], v220 offset:5120
	ds_read_b128 v[184:187], v220 offset:6144
	ds_read_b128 v[222:225], v220 offset:7168
	global_load_lds_dwordx4 v214, s[52:53]
	s_add_i32 m0, s66, 0xe000
	s_nop 0
	global_load_lds_dwordx4 v216, s[52:53]
	s_waitcnt vmcnt(8)
	s_waitcnt lgkmcnt(0)
	s_setprio 1
	s_barrier
	v_mfma_f32_16x16x32_bf16 v[132:135], v[124:127], v[160:163], v[132:135]
	v_mfma_f32_16x16x32_bf16 v[120:123], v[136:139], v[160:163], v[120:123]
	v_mfma_f32_16x16x32_bf16 v[108:111], v[124:127], v[168:171], v[108:111]
	v_mfma_f32_16x16x32_bf16 v[104:107], v[136:139], v[168:171], v[104:107]
	v_mfma_f32_16x16x32_bf16 v[92:95], v[124:127], v[176:179], v[92:95]
	v_mfma_f32_16x16x32_bf16 v[88:91], v[136:139], v[176:179], v[88:91]
	v_mfma_f32_16x16x32_bf16 v[76:79], v[124:127], v[184:187], v[76:79]
	v_mfma_f32_16x16x32_bf16 v[72:75], v[136:139], v[184:187], v[72:75]
	v_mfma_f32_16x16x32_bf16 v[132:135], v[128:131], v[164:167], v[132:135]
	v_mfma_f32_16x16x32_bf16 v[120:123], v[140:143], v[164:167], v[120:123]
	v_mfma_f32_16x16x32_bf16 v[108:111], v[128:131], v[172:175], v[108:111]
	v_mfma_f32_16x16x32_bf16 v[104:107], v[140:143], v[172:175], v[104:107]
	v_mfma_f32_16x16x32_bf16 v[92:95], v[128:131], v[180:183], v[92:95]
	v_mfma_f32_16x16x32_bf16 v[88:91], v[140:143], v[180:183], v[88:91]
	v_mfma_f32_16x16x32_bf16 v[76:79], v[128:131], v[222:225], v[76:79]
	v_mfma_f32_16x16x32_bf16 v[72:75], v[140:143], v[222:225], v[72:75]
	s_setprio 0
	s_setprio 1
	v_mfma_f32_16x16x32_bf16 v[116:119], v[144:147], v[160:163], v[116:119]
	v_mfma_f32_16x16x32_bf16 v[112:115], v[152:155], v[160:163], v[112:115]
	v_mfma_f32_16x16x32_bf16 v[100:103], v[144:147], v[168:171], v[100:103]
	v_mfma_f32_16x16x32_bf16 v[96:99], v[152:155], v[168:171], v[96:99]
	v_mfma_f32_16x16x32_bf16 v[84:87], v[144:147], v[176:179], v[84:87]
	v_mfma_f32_16x16x32_bf16 v[80:83], v[152:155], v[176:179], v[80:83]
	v_mfma_f32_16x16x32_bf16 v[68:71], v[144:147], v[184:187], v[68:71]
	v_mfma_f32_16x16x32_bf16 v[64:67], v[152:155], v[184:187], v[64:67]
	v_mfma_f32_16x16x32_bf16 v[116:119], v[148:151], v[164:167], v[116:119]
	v_mfma_f32_16x16x32_bf16 v[112:115], v[156:159], v[164:167], v[112:115]
	v_mfma_f32_16x16x32_bf16 v[100:103], v[148:151], v[172:175], v[100:103]
	v_mfma_f32_16x16x32_bf16 v[96:99], v[156:159], v[172:175], v[96:99]
	v_mfma_f32_16x16x32_bf16 v[84:87], v[148:151], v[180:183], v[84:87]
	v_mfma_f32_16x16x32_bf16 v[80:83], v[156:159], v[180:183], v[80:83]
	v_mfma_f32_16x16x32_bf16 v[68:71], v[148:151], v[222:225], v[68:71]
	v_mfma_f32_16x16x32_bf16 v[64:67], v[156:159], v[222:225], v[64:67]
	s_barrier
	s_setprio 0
	s_add_i32 s11, s11, s29
	s_mov_b32 m0, s11
	ds_read_b128 v[160:163], v220 offset:16384
	ds_read_b128 v[164:167], v220 offset:17408
	ds_read_b128 v[168:171], v220 offset:18432
	ds_read_b128 v[172:175], v220 offset:19456
	ds_read_b128 v[176:179], v220 offset:20480
	ds_read_b128 v[180:183], v220 offset:21504
	ds_read_b128 v[184:187], v220 offset:22528
	ds_read_b128 v[222:225], v220 offset:23552
	global_load_lds_dwordx4 v190, s[58:59]
	s_add_i32 m0, s11, 0x2000
	s_add_u32 s52, s58, 0x40000
	s_addc_u32 s53, s59, 0
	s_add_i32 s11, s13, s29
	global_load_lds_dwordx4 v212, s[58:59]
	s_mov_b32 m0, s11
	s_nop 0
	global_load_lds_dwordx4 v190, s[52:53]
	s_add_i32 m0, s11, 0x2000
	s_nop 0
	global_load_lds_dwordx4 v212, s[52:53]
	s_mov_b32 m0, s66
	s_nop 0
	global_load_lds_dwordx4 v188, s[60:61]
	s_mov_b32 m0, s67
	s_nop 0
	global_load_lds_dwordx4 v210, s[60:61]
	s_waitcnt vmcnt(8)
	s_waitcnt lgkmcnt(0)
	s_setprio 1
	s_barrier
	v_mfma_f32_16x16x32_bf16 v[60:63], v[124:127], v[160:163], v[60:63]
	v_mfma_f32_16x16x32_bf16 v[56:59], v[136:139], v[160:163], v[56:59]
	v_mfma_f32_16x16x32_bf16 v[44:47], v[124:127], v[168:171], v[44:47]
	v_mfma_f32_16x16x32_bf16 v[40:43], v[136:139], v[168:171], v[40:43]
	v_mfma_f32_16x16x32_bf16 v[28:31], v[124:127], v[176:179], v[28:31]
	v_mfma_f32_16x16x32_bf16 v[24:27], v[136:139], v[176:179], v[24:27]
	v_mfma_f32_16x16x32_bf16 v[12:15], v[124:127], v[184:187], v[12:15]
	v_mfma_f32_16x16x32_bf16 v[8:11], v[136:139], v[184:187], v[8:11]
	v_mfma_f32_16x16x32_bf16 v[60:63], v[128:131], v[164:167], v[60:63]
	v_mfma_f32_16x16x32_bf16 v[56:59], v[140:143], v[164:167], v[56:59]
	v_mfma_f32_16x16x32_bf16 v[44:47], v[128:131], v[172:175], v[44:47]
	v_mfma_f32_16x16x32_bf16 v[40:43], v[140:143], v[172:175], v[40:43]
	v_mfma_f32_16x16x32_bf16 v[28:31], v[128:131], v[180:183], v[28:31]
	v_mfma_f32_16x16x32_bf16 v[24:27], v[140:143], v[180:183], v[24:27]
	v_mfma_f32_16x16x32_bf16 v[12:15], v[128:131], v[222:225], v[12:15]
	v_mfma_f32_16x16x32_bf16 v[8:11], v[140:143], v[222:225], v[8:11]
	s_setprio 0
	s_setprio 1
	v_mfma_f32_16x16x32_bf16 v[52:55], v[144:147], v[160:163], v[52:55]
	v_mfma_f32_16x16x32_bf16 v[48:51], v[152:155], v[160:163], v[48:51]
	v_mfma_f32_16x16x32_bf16 v[36:39], v[144:147], v[168:171], v[36:39]
	v_mfma_f32_16x16x32_bf16 v[32:35], v[152:155], v[168:171], v[32:35]
	v_mfma_f32_16x16x32_bf16 v[20:23], v[144:147], v[176:179], v[20:23]
	v_mfma_f32_16x16x32_bf16 v[16:19], v[152:155], v[176:179], v[16:19]
	v_mfma_f32_16x16x32_bf16 v[4:7], v[144:147], v[184:187], v[4:7]
	v_mfma_f32_16x16x32_bf16 v[0:3], v[152:155], v[184:187], v[0:3]
	v_mfma_f32_16x16x32_bf16 v[52:55], v[148:151], v[164:167], v[52:55]
	v_mfma_f32_16x16x32_bf16 v[48:51], v[156:159], v[164:167], v[48:51]
	v_mfma_f32_16x16x32_bf16 v[36:39], v[148:151], v[172:175], v[36:39]
	v_mfma_f32_16x16x32_bf16 v[32:35], v[156:159], v[172:175], v[32:35]
	v_mfma_f32_16x16x32_bf16 v[20:23], v[148:151], v[180:183], v[20:23]
	v_mfma_f32_16x16x32_bf16 v[16:19], v[156:159], v[180:183], v[16:19]
	v_mfma_f32_16x16x32_bf16 v[4:7], v[148:151], v[222:225], v[4:7]
	v_mfma_f32_16x16x32_bf16 v[0:3], v[156:159], v[222:225], v[0:3]
	s_barrier
; #define PG8_STAGE(bufoff, gbase, voff) do { _Pragma("unroll") for (int _i = 0; _i < 2; ++_i) \
;         __builtin_amdgcn_global_load_lds((const unsigned*)((const char*)(gbase) + (voff)[_i]), (PG8_LAS unsigned*)(lds + (bufoff) + ldsw + _i * 8192), 16, 0, 0); } while (0)
; #define PG8_LDA(dst, b, h) do { _Pragma("unroll") for (int m = 0; m < 4; ++m) _Pragma("unroll") for (int k = 0; k < 2; ++k) dst[m][k] = *(const PG8_LAS bf16x8*)(lds + PG8_SA(b, h) + aoff + m * 2048 + k * 1024); } while (0)
; #define PG8_LDB(dst, b, h) do { _Pragma("unroll") for (int n = 0; n < 2; ++n) _Pragma("unroll") for (int k = 0; k < 2; ++k) dst[n][k] = *(const PG8_LAS bf16x8*)(lds + PG8_SB(b, h) + boff + n * 2048 + k * 1024); } while (0)
; #define PG8_MMA(ai, bj, At, Bt) do { __builtin_amdgcn_s_setprio(1); _Pragma("unroll") for (int m = 0; m < 4; ++m) _Pragma("unroll") for (int n = 0; n < 2; ++n) _Pragma("unroll") for (int k = 0; k < 2; ++k) \
;         acc[ai][bj][m][n] = __builtin_amdgcn_mfma_f32_16x16x32_bf16(Bt[n][k], At[m][k], acc[ai][bj][m][n], 0, 0, 0); __builtin_amdgcn_s_setprio(0); } while (0)
; #define PG8_WAIT_V(n) asm volatile("s_waitcnt vmcnt(" #n ")" ::: "memory")
; #define PG8_WAIT_L(n) asm volatile("s_waitcnt lgkmcnt(" #n ")" ::: "memory")
; #define PG8_BAR __builtin_amdgcn_s_barrier()
; #define PG8_SCHED __builtin_amdgcn_sched_barrier(0)
; template <class Epi>
; __device__ __forceinline__ void gemm_phase(PG8_LAS unsigned char* lds, PG8_LAS unsigned char* xl, const Gemm g, const Sched& S, const Epi& E, const int wid) {
;     ...
;             PG8_LDB(B0, 1, 0); PG8_LDB(B1, 1, 1); PG8_SCHED; PG8_LDA(At, 1, 0); PG8_STAGE(PG8_SA(0, 1), a2 + hstepA, voffA);
;             PG8_WAIT_V(8); PG8_WAIT_L(0); PG8_BAR; if (do0) { PG8_MMA(0, 0, At, B0); PG8_MMA(0, 1, At, B1); } PG8_BAR; PG8_SCHED;
;             PG8_LDA(At, 1, 1); PG8_STAGE(PG8_SB(1, 0), b3, voffB); PG8_STAGE(PG8_SB(1, 1), b3 + hstepB, voffB); PG8_STAGE(PG8_SA(1, 0), a3, voffA);
;             PG8_WAIT_V(8); PG8_WAIT_L(0); PG8_BAR; if (do1) { PG8_MMA(1, 0, At, B0); PG8_MMA(1, 1, At, B1); } PG8_BAR; PG8_SCHED;
;         }
;         if (wr == 0) PG8_BAR;
	s_setprio 0
	s_add_i32 s11, 0, 0x18000
	s_add_i32 s13, 0, 0x1c000
	ds_read_b128 v[124:127], v226 offset:32768
	ds_read_b128 v[128:131], v226 offset:33792
	ds_read_b128 v[136:139], v226 offset:34816
	ds_read_b128 v[140:143], v226 offset:35840
	ds_read_b128 v[144:147], v226 offset:49152
	ds_read_b128 v[148:151], v226 offset:50176
	ds_read_b128 v[152:155], v226 offset:51200
	ds_read_b128 v[156:159], v226 offset:52224
	s_add_u32 s52, s60, 0x40000
	s_addc_u32 s53, s61, 0
	s_mov_b32 m0, s68
	ds_read_b128 v[160:163], v220 offset:32768
	ds_read_b128 v[164:167], v220 offset:33792
	ds_read_b128 v[168:171], v220 offset:34816
	ds_read_b128 v[172:175], v220 offset:35840
	ds_read_b128 v[176:179], v220 offset:36864
	ds_read_b128 v[180:183], v220 offset:37888
	ds_read_b128 v[184:187], v220 offset:38912
	ds_read_b128 v[222:225], v220 offset:39936
	global_load_lds_dwordx4 v188, s[52:53]
	s_mov_b32 m0, s69
	s_nop 0
	global_load_lds_dwordx4 v210, s[52:53]
	s_waitcnt vmcnt(8)
	s_waitcnt lgkmcnt(0)
	s_setprio 1
	s_barrier
	v_mfma_f32_16x16x32_bf16 v[132:135], v[124:127], v[160:163], v[132:135]
	v_mfma_f32_16x16x32_bf16 v[120:123], v[136:139], v[160:163], v[120:123]
	v_mfma_f32_16x16x32_bf16 v[108:111], v[124:127], v[168:171], v[108:111]
	v_mfma_f32_16x16x32_bf16 v[104:107], v[136:139], v[168:171], v[104:107]
	v_mfma_f32_16x16x32_bf16 v[92:95], v[124:127], v[176:179], v[92:95]
	v_mfma_f32_16x16x32_bf16 v[88:91], v[136:139], v[176:179], v[88:91]
	v_mfma_f32_16x16x32_bf16 v[76:79], v[124:127], v[184:187], v[76:79]
	v_mfma_f32_16x16x32_bf16 v[72:75], v[136:139], v[184:187], v[72:75]
	v_mfma_f32_16x16x32_bf16 v[132:135], v[128:131], v[164:167], v[132:135]
	v_mfma_f32_16x16x32_bf16 v[120:123], v[140:143], v[164:167], v[120:123]
	v_mfma_f32_16x16x32_bf16 v[108:111], v[128:131], v[172:175], v[108:111]
	v_mfma_f32_16x16x32_bf16 v[104:107], v[140:143], v[172:175], v[104:107]
	v_mfma_f32_16x16x32_bf16 v[92:95], v[128:131], v[180:183], v[92:95]
	v_mfma_f32_16x16x32_bf16 v[88:91], v[140:143], v[180:183], v[88:91]
	v_mfma_f32_16x16x32_bf16 v[76:79], v[128:131], v[222:225], v[76:79]
	v_mfma_f32_16x16x32_bf16 v[72:75], v[140:143], v[222:225], v[72:75]
	s_setprio 0
	s_setprio 1
	v_mfma_f32_16x16x32_bf16 v[116:119], v[144:147], v[160:163], v[116:119]
	v_mfma_f32_16x16x32_bf16 v[112:115], v[152:155], v[160:163], v[112:115]
	v_mfma_f32_16x16x32_bf16 v[100:103], v[144:147], v[168:171], v[100:103]
	v_mfma_f32_16x16x32_bf16 v[96:99], v[152:155], v[168:171], v[96:99]
	v_mfma_f32_16x16x32_bf16 v[84:87], v[144:147], v[176:179], v[84:87]
	v_mfma_f32_16x16x32_bf16 v[80:83], v[152:155], v[176:179], v[80:83]
	v_mfma_f32_16x16x32_bf16 v[68:71], v[144:147], v[184:187], v[68:71]
	v_mfma_f32_16x16x32_bf16 v[64:67], v[152:155], v[184:187], v[64:67]
	v_mfma_f32_16x16x32_bf16 v[116:119], v[148:151], v[164:167], v[116:119]
	v_mfma_f32_16x16x32_bf16 v[112:115], v[156:159], v[164:167], v[112:115]
	v_mfma_f32_16x16x32_bf16 v[100:103], v[148:151], v[172:175], v[100:103]
	v_mfma_f32_16x16x32_bf16 v[96:99], v[156:159], v[172:175], v[96:99]
	v_mfma_f32_16x16x32_bf16 v[84:87], v[148:151], v[180:183], v[84:87]
	v_mfma_f32_16x16x32_bf16 v[80:83], v[156:159], v[180:183], v[80:83]
	v_mfma_f32_16x16x32_bf16 v[68:71], v[148:151], v[222:225], v[68:71]
	v_mfma_f32_16x16x32_bf16 v[64:67], v[156:159], v[222:225], v[64:67]
	s_barrier
	s_setprio 0
	s_add_i32 s11, s11, s29
	s_mov_b32 m0, s11
	ds_read_b128 v[160:163], v220 offset:49152
	ds_read_b128 v[164:167], v220 offset:50176
	ds_read_b128 v[168:171], v220 offset:51200
	ds_read_b128 v[172:175], v220 offset:52224
	ds_read_b128 v[176:179], v220 offset:53248
	ds_read_b128 v[180:183], v220 offset:54272
	ds_read_b128 v[184:187], v220 offset:55296
	ds_read_b128 v[222:225], v220 offset:56320
	global_load_lds_dwordx4 v205, s[58:59]
	s_add_i32 m0, s11, 0x2000
	s_add_u32 s52, s58, 0x40080
	global_load_lds_dwordx4 v219, s[58:59]
	s_addc_u32 s53, s59, 0
	s_add_i32 s11, s13, s29
	s_mov_b32 m0, s11
	s_nop 0
	global_load_lds_dwordx4 v190, s[52:53]
	s_add_i32 m0, s11, 0x2000
	s_nop 0
	global_load_lds_dwordx4 v212, s[52:53]
	s_mov_b32 m0, s87
	s_nop 0
	global_load_lds_dwordx4 v204, s[60:61]
	s_mov_b32 m0, s88
	s_nop 0
	global_load_lds_dwordx4 v218, s[60:61]
	s_waitcnt vmcnt(8)
	s_waitcnt lgkmcnt(0)
	s_setprio 1
	s_barrier
	v_mfma_f32_16x16x32_bf16 v[60:63], v[124:127], v[160:163], v[60:63]
	v_mfma_f32_16x16x32_bf16 v[56:59], v[136:139], v[160:163], v[56:59]
	v_mfma_f32_16x16x32_bf16 v[44:47], v[124:127], v[168:171], v[44:47]
	v_mfma_f32_16x16x32_bf16 v[40:43], v[136:139], v[168:171], v[40:43]
	v_mfma_f32_16x16x32_bf16 v[28:31], v[124:127], v[176:179], v[28:31]
	v_mfma_f32_16x16x32_bf16 v[24:27], v[136:139], v[176:179], v[24:27]
	v_mfma_f32_16x16x32_bf16 v[12:15], v[124:127], v[184:187], v[12:15]
	v_mfma_f32_16x16x32_bf16 v[8:11], v[136:139], v[184:187], v[8:11]
	v_mfma_f32_16x16x32_bf16 v[60:63], v[128:131], v[164:167], v[60:63]
	v_mfma_f32_16x16x32_bf16 v[56:59], v[140:143], v[164:167], v[56:59]
	v_mfma_f32_16x16x32_bf16 v[44:47], v[128:131], v[172:175], v[44:47]
	v_mfma_f32_16x16x32_bf16 v[40:43], v[140:143], v[172:175], v[40:43]
	v_mfma_f32_16x16x32_bf16 v[28:31], v[128:131], v[180:183], v[28:31]
	v_mfma_f32_16x16x32_bf16 v[24:27], v[140:143], v[180:183], v[24:27]
	v_mfma_f32_16x16x32_bf16 v[12:15], v[128:131], v[222:225], v[12:15]
	v_mfma_f32_16x16x32_bf16 v[8:11], v[140:143], v[222:225], v[8:11]
	s_setprio 0
	s_setprio 1
	v_mfma_f32_16x16x32_bf16 v[52:55], v[144:147], v[160:163], v[52:55]
	v_mfma_f32_16x16x32_bf16 v[48:51], v[152:155], v[160:163], v[48:51]
	v_mfma_f32_16x16x32_bf16 v[36:39], v[144:147], v[168:171], v[36:39]
	v_mfma_f32_16x16x32_bf16 v[32:35], v[152:155], v[168:171], v[32:35]
	v_mfma_f32_16x16x32_bf16 v[20:23], v[144:147], v[176:179], v[20:23]
	v_mfma_f32_16x16x32_bf16 v[16:19], v[152:155], v[176:179], v[16:19]
	v_mfma_f32_16x16x32_bf16 v[4:7], v[144:147], v[184:187], v[4:7]
	v_mfma_f32_16x16x32_bf16 v[0:3], v[152:155], v[184:187], v[0:3]
	v_mfma_f32_16x16x32_bf16 v[52:55], v[148:151], v[164:167], v[52:55]
	v_mfma_f32_16x16x32_bf16 v[48:51], v[156:159], v[164:167], v[48:51]
	v_mfma_f32_16x16x32_bf16 v[36:39], v[148:151], v[172:175], v[36:39]
	v_mfma_f32_16x16x32_bf16 v[32:35], v[156:159], v[172:175], v[32:35]
	v_mfma_f32_16x16x32_bf16 v[20:23], v[148:151], v[180:183], v[20:23]
	v_mfma_f32_16x16x32_bf16 v[16:19], v[156:159], v[180:183], v[16:19]
	v_mfma_f32_16x16x32_bf16 v[4:7], v[148:151], v[222:225], v[4:7]
	v_mfma_f32_16x16x32_bf16 v[0:3], v[156:159], v[222:225], v[0:3]
	s_barrier
	s_setprio 0
	s_add_i32 s10, s10, 2
	s_add_u32 s8, s8, 0x100
	s_addc_u32 s9, s9, 0
	s_cmp_gt_u32 s10, 13
	s_mov_b64 s[52:53], s[56:57]
	s_cbranch_scc0 .LBB0_959
	s_and_b64 vcc, exec, s[14:15]
	s_cbranch_vccz .LBB0_962
	s_barrier

; #define PG8_STAGE(bufoff, gbase, voff) do { _Pragma("unroll") for (int _i = 0; _i < 2; ++_i) \
;         __builtin_amdgcn_global_load_lds((const unsigned*)((const char*)(gbase) + (voff)[_i]), (PG8_LAS unsigned*)(lds + (bufoff) + ldsw + _i * 8192), 16, 0, 0); } while (0)
; #define PG8_LDA(dst, b, h) do { _Pragma("unroll") for (int m = 0; m < 4; ++m) _Pragma("unroll") for (int k = 0; k < 2; ++k) dst[m][k] = *(const PG8_LAS bf16x8*)(lds + PG8_SA(b, h) + aoff + m * 2048 + k * 1024); } while (0)
; #define PG8_LDB(dst, b, h) do { _Pragma("unroll") for (int n = 0; n < 2; ++n) _Pragma("unroll") for (int k = 0; k < 2; ++k) dst[n][k] = *(const PG8_LAS bf16x8*)(lds + PG8_SB(b, h) + boff + n * 2048 + k * 1024); } while (0)
; #define PG8_MMA(ai, bj, At, Bt) do { __builtin_amdgcn_s_setprio(1); _Pragma("unroll") for (int m = 0; m < 4; ++m) _Pragma("unroll") for (int n = 0; n < 2; ++n) _Pragma("unroll") for (int k = 0; k < 2; ++k) \
;         acc[ai][bj][m][n] = __builtin_amdgcn_mfma_f32_16x16x32_bf16(Bt[n][k], At[m][k], acc[ai][bj][m][n], 0, 0, 0); __builtin_amdgcn_s_setprio(0); } while (0)
; #define PG8_WAIT_V(n) asm volatile("s_waitcnt vmcnt(" #n ")" ::: "memory")
; #define PG8_WAIT_L(n) asm volatile("s_waitcnt lgkmcnt(" #n ")" ::: "memory")
; #define PG8_BAR __builtin_amdgcn_s_barrier()
; #define PG8_SCHED __builtin_amdgcn_sched_barrier(0)
; template <class Epi>
; __device__ __forceinline__ void gemm_phase(PG8_LAS unsigned char* lds, PG8_LAS unsigned char* xl, const Gemm g, const Sched& S, const Epi& E, const int wid) {
;     ...
;             const char* a1 = cA + (size_t)(t + 1) * kstep + j1;
;             const char* a2 = last ? nA : cA + (size_t)(t + 2) * kstep + ja2; const char* b2 = last ? nB : cB + (size_t)(t + 2) * kstep + jb2;
;             const char* a3 = a2 + kstep; const char* b3 = b2 + kstep;
;             PG8_LDB(B0, 0, 0); PG8_LDB(B1, 0, 1); PG8_SCHED; PG8_LDA(At, 0, 0); PG8_STAGE(PG8_SA(1, 1), a1 + hstepA, voffA);
;             PG8_WAIT_V(8); PG8_WAIT_L(0); PG8_BAR; if (do0) { PG8_MMA(0, 0, At, B0); PG8_MMA(0, 1, At, B1); } PG8_BAR; PG8_SCHED;
;             PG8_LDA(At, 0, 1); PG8_STAGE(PG8_SB(0, 0), b2, voffB); PG8_STAGE(PG8_SB(0, 1), b2 + hstepB, voffB); PG8_STAGE(PG8_SA(0, 0), a2, voffA);
;             PG8_WAIT_V(8); PG8_WAIT_L(0); PG8_BAR; if (do1) { PG8_MMA(1, 0, At, B0); PG8_MMA(1, 1, At, B1); } PG8_BAR; PG8_SCHED;
.Ldefbar_skip_9:
	v_add_u32_e32 v204, s22, v210
	v_add_u32_e32 v205, s22, v212
	v_add_u32_e32 v226, s22, v214
	v_add_u32_e32 v227, s22, v216
	v_add_u32_e32 v248, 0x10000, v195
.LBB0_1106:
	s_add_u32 s76, s44, 0x100
	s_addc_u32 s77, s45, 0
	s_add_i32 s55, 0, 0x10000
	s_cmp_eq_u32 s54, 28
	s_cselect_b32 s11, s8, s77
	s_cselect_b32 s10, s9, s76
	s_cselect_b32 vcc_hi, s49, s73
	s_cselect_b32 vcc_lo, s61, s72
	s_add_i32 s4, 0, 0x14000
	ds_read_b128 v[4:7], v248 offset:0
	ds_read_b128 v[8:11], v248 offset:1024
	ds_read_b128 v[84:87], v248 offset:2048
	ds_read_b128 v[88:91], v248 offset:3072
	ds_read_b128 v[92:95], v248 offset:16384
	ds_read_b128 v[96:99], v248 offset:17408
	ds_read_b128 v[100:103], v248 offset:18432
	ds_read_b128 v[104:107], v248 offset:19456
	s_add_i32 m0, s90, 0xc000
	ds_read_b128 v[108:111], v225
	ds_read_b128 v[172:175], v225 offset:1024
	ds_read_b128 v[176:179], v225 offset:2048
	ds_read_b128 v[180:183], v225 offset:3072
	ds_read_b128 v[184:187], v225 offset:4096
	ds_read_b128 v[188:191], v225 offset:5120
	ds_read_b128 v[230:233], v225 offset:6144
	ds_read_b128 v[234:237], v225 offset:7168
	global_load_lds_dwordx4 v218, s[44:45]
	s_add_i32 m0, s90, 0xe000
	s_nop 0
	global_load_lds_dwordx4 v220, s[44:45]
	s_waitcnt vmcnt(8)
	s_waitcnt lgkmcnt(0)
	s_setprio 1
	s_barrier
	v_mfma_f32_16x16x32_bf16 v[60:63], v[4:7], v[108:111], v[60:63]
	v_mfma_f32_16x16x32_bf16 v[64:67], v[84:87], v[108:111], v[64:67]
	v_mfma_f32_16x16x32_bf16 v[120:123], v[4:7], v[176:179], v[120:123]
	v_mfma_f32_16x16x32_bf16 v[124:127], v[84:87], v[176:179], v[124:127]
	v_mfma_f32_16x16x32_bf16 v[164:167], v[4:7], v[184:187], v[164:167]
	v_mfma_f32_16x16x32_bf16 v[160:163], v[84:87], v[184:187], v[160:163]
	v_mfma_f32_16x16x32_bf16 v[80:83], v[4:7], v[230:233], v[80:83]
	v_mfma_f32_16x16x32_bf16 v[128:131], v[84:87], v[230:233], v[128:131]
	v_mfma_f32_16x16x32_bf16 v[60:63], v[8:11], v[172:175], v[60:63]
	v_mfma_f32_16x16x32_bf16 v[64:67], v[88:91], v[172:175], v[64:67]
	v_mfma_f32_16x16x32_bf16 v[120:123], v[8:11], v[180:183], v[120:123]
	v_mfma_f32_16x16x32_bf16 v[124:127], v[88:91], v[180:183], v[124:127]
	v_mfma_f32_16x16x32_bf16 v[164:167], v[8:11], v[188:191], v[164:167]
	v_mfma_f32_16x16x32_bf16 v[160:163], v[88:91], v[188:191], v[160:163]
	v_mfma_f32_16x16x32_bf16 v[80:83], v[8:11], v[234:237], v[80:83]
	v_mfma_f32_16x16x32_bf16 v[128:131], v[88:91], v[234:237], v[128:131]
	s_setprio 0
	s_setprio 1
	v_mfma_f32_16x16x32_bf16 v[112:115], v[92:95], v[108:111], v[112:115]
	v_mfma_f32_16x16x32_bf16 v[108:111], v[100:103], v[108:111], v[116:119]
	v_mfma_f32_16x16x32_bf16 v[116:119], v[92:95], v[176:179], v[156:159]
	v_mfma_f32_16x16x32_bf16 v[156:159], v[96:99], v[180:183], v[116:119]
	v_mfma_f32_16x16x32_bf16 v[116:119], v[100:103], v[176:179], v[152:155]
	v_mfma_f32_16x16x32_bf16 v[152:155], v[104:107], v[180:183], v[116:119]
	v_mfma_f32_16x16x32_bf16 v[116:119], v[92:95], v[184:187], v[148:151]
	v_mfma_f32_16x16x32_bf16 v[148:151], v[96:99], v[188:191], v[116:119]
	v_mfma_f32_16x16x32_bf16 v[116:119], v[100:103], v[184:187], v[144:147]
	v_mfma_f32_16x16x32_bf16 v[144:147], v[104:107], v[188:191], v[116:119]
	v_mfma_f32_16x16x32_bf16 v[116:119], v[92:95], v[230:233], v[140:143]
	v_mfma_f32_16x16x32_bf16 v[140:143], v[96:99], v[234:237], v[116:119]
	v_mfma_f32_16x16x32_bf16 v[116:119], v[100:103], v[230:233], v[136:139]
	v_mfma_f32_16x16x32_bf16 v[112:115], v[96:99], v[172:175], v[112:115]
	v_mfma_f32_16x16x32_bf16 v[136:139], v[104:107], v[234:237], v[116:119]
	v_mfma_f32_16x16x32_bf16 v[108:111], v[104:107], v[172:175], v[108:111]
	s_barrier
	s_setprio 0
	s_add_i32 s5, s55, s29
	s_mov_b32 m0, s5
	ds_read_b128 v[116:119], v225 offset:16384
	ds_read_b128 v[172:175], v225 offset:17408
	ds_read_b128 v[176:179], v225 offset:18432
	ds_read_b128 v[180:183], v225 offset:19456
	ds_read_b128 v[184:187], v225 offset:20480
	ds_read_b128 v[188:191], v225 offset:21504
	ds_read_b128 v[230:233], v225 offset:22528
	ds_read_b128 v[234:237], v225 offset:23552
	global_load_lds_dwordx4 v212, vcc
	s_add_i32 m0, s5, 0x2000
	s_add_u32 s44, vcc_lo, 0x80000
	s_addc_u32 s45, vcc_hi, 0
	s_add_i32 s4, s4, s29
	global_load_lds_dwordx4 v216, vcc
	s_mov_b32 m0, s4
	s_nop 0
	global_load_lds_dwordx4 v212, s[44:45]
	s_add_i32 m0, s4, 0x2000
	s_nop 0
	global_load_lds_dwordx4 v216, s[44:45]
	s_mov_b32 m0, s90
	s_nop 0
	global_load_lds_dwordx4 v210, s[10:11]
	s_mov_b32 m0, s13
	s_nop 0
	global_load_lds_dwordx4 v214, s[10:11]
	s_waitcnt vmcnt(8)
	s_waitcnt lgkmcnt(0)
	s_setprio 1
	s_barrier
	v_mfma_f32_16x16x32_bf16 v[132:135], v[4:7], v[116:119], v[132:135]
	v_mfma_f32_16x16x32_bf16 v[68:71], v[84:87], v[116:119], v[68:71]
	v_mfma_f32_16x16x32_bf16 v[56:59], v[4:7], v[176:179], v[56:59]
	v_mfma_f32_16x16x32_bf16 v[52:55], v[84:87], v[176:179], v[52:55]
	v_mfma_f32_16x16x32_bf16 v[40:43], v[4:7], v[184:187], v[40:43]
	v_mfma_f32_16x16x32_bf16 v[36:39], v[84:87], v[184:187], v[36:39]
	v_mfma_f32_16x16x32_bf16 v[4:7], v[4:7], v[230:233], v[168:171]
	v_mfma_f32_16x16x32_bf16 v[132:135], v[8:11], v[172:175], v[132:135]
	v_mfma_f32_16x16x32_bf16 v[68:71], v[88:91], v[172:175], v[68:71]
	v_mfma_f32_16x16x32_bf16 v[56:59], v[8:11], v[180:183], v[56:59]
	v_mfma_f32_16x16x32_bf16 v[52:55], v[88:91], v[180:183], v[52:55]
	v_mfma_f32_16x16x32_bf16 v[40:43], v[8:11], v[188:191], v[40:43]
	v_mfma_f32_16x16x32_bf16 v[36:39], v[88:91], v[188:191], v[36:39]
	v_mfma_f32_16x16x32_bf16 v[4:7], v[8:11], v[234:237], v[4:7]
	v_mfma_f32_16x16x32_bf16 v[8:11], v[84:87], v[230:233], v[72:75]
	v_mfma_f32_16x16x32_bf16 v[8:11], v[88:91], v[234:237], v[8:11]
	s_setprio 0
	s_setprio 1
	v_mfma_f32_16x16x32_bf16 v[48:51], v[92:95], v[116:119], v[48:51]
	v_mfma_f32_16x16x32_bf16 v[44:47], v[100:103], v[116:119], v[44:47]
	v_mfma_f32_16x16x32_bf16 v[32:35], v[92:95], v[176:179], v[32:35]
	v_mfma_f32_16x16x32_bf16 v[28:31], v[100:103], v[176:179], v[28:31]
	v_mfma_f32_16x16x32_bf16 v[24:27], v[92:95], v[184:187], v[24:27]
	v_mfma_f32_16x16x32_bf16 v[20:23], v[100:103], v[184:187], v[20:23]
	v_mfma_f32_16x16x32_bf16 v[16:19], v[92:95], v[230:233], v[16:19]
	v_mfma_f32_16x16x32_bf16 v[12:15], v[100:103], v[230:233], v[12:15]
	v_mfma_f32_16x16x32_bf16 v[48:51], v[96:99], v[172:175], v[48:51]
	v_mfma_f32_16x16x32_bf16 v[44:47], v[104:107], v[172:175], v[44:47]
	v_mfma_f32_16x16x32_bf16 v[32:35], v[96:99], v[180:183], v[32:35]
	v_mfma_f32_16x16x32_bf16 v[28:31], v[104:107], v[180:183], v[28:31]
	v_mfma_f32_16x16x32_bf16 v[24:27], v[96:99], v[188:191], v[24:27]
	v_mfma_f32_16x16x32_bf16 v[20:23], v[104:107], v[188:191], v[20:23]
	v_mfma_f32_16x16x32_bf16 v[16:19], v[96:99], v[234:237], v[16:19]
	v_mfma_f32_16x16x32_bf16 v[12:15], v[104:107], v[234:237], v[12:15]
	s_barrier
; #define PG8_STAGE(bufoff, gbase, voff) do { _Pragma("unroll") for (int _i = 0; _i < 2; ++_i) \
;         __builtin_amdgcn_global_load_lds((const unsigned*)((const char*)(gbase) + (voff)[_i]), (PG8_LAS unsigned*)(lds + (bufoff) + ldsw + _i * 8192), 16, 0, 0); } while (0)
; #define PG8_LDA(dst, b, h) do { _Pragma("unroll") for (int m = 0; m < 4; ++m) _Pragma("unroll") for (int k = 0; k < 2; ++k) dst[m][k] = *(const PG8_LAS bf16x8*)(lds + PG8_SA(b, h) + aoff + m * 2048 + k * 1024); } while (0)
; #define PG8_LDB(dst, b, h) do { _Pragma("unroll") for (int n = 0; n < 2; ++n) _Pragma("unroll") for (int k = 0; k < 2; ++k) dst[n][k] = *(const PG8_LAS bf16x8*)(lds + PG8_SB(b, h) + boff + n * 2048 + k * 1024); } while (0)
; #define PG8_MMA(ai, bj, At, Bt) do { __builtin_amdgcn_s_setprio(1); _Pragma("unroll") for (int m = 0; m < 4; ++m) _Pragma("unroll") for (int n = 0; n < 2; ++n) _Pragma("unroll") for (int k = 0; k < 2; ++k) \
;         acc[ai][bj][m][n] = __builtin_amdgcn_mfma_f32_16x16x32_bf16(Bt[n][k], At[m][k], acc[ai][bj][m][n], 0, 0, 0); __builtin_amdgcn_s_setprio(0); } while (0)
; #define PG8_WAIT_V(n) asm volatile("s_waitcnt vmcnt(" #n ")" ::: "memory")
; #define PG8_WAIT_L(n) asm volatile("s_waitcnt lgkmcnt(" #n ")" ::: "memory")
; #define PG8_BAR __builtin_amdgcn_s_barrier()
; #define PG8_SCHED __builtin_amdgcn_sched_barrier(0)
; template <class Epi>
; __device__ __forceinline__ void gemm_phase(PG8_LAS unsigned char* lds, PG8_LAS unsigned char* xl, const Gemm g, const Sched& S, const Epi& E, const int wid) {
;     ...
;             PG8_LDB(B0, 1, 0); PG8_LDB(B1, 1, 1); PG8_SCHED; PG8_LDA(At, 1, 0); PG8_STAGE(PG8_SA(0, 1), a2 + hstepA, voffA);
;             PG8_WAIT_V(8); PG8_WAIT_L(0); PG8_BAR; if (do0) { PG8_MMA(0, 0, At, B0); PG8_MMA(0, 1, At, B1); } PG8_BAR; PG8_SCHED;
;             PG8_LDA(At, 1, 1); PG8_STAGE(PG8_SB(1, 0), b3, voffB); PG8_STAGE(PG8_SB(1, 1), b3 + hstepB, voffB); PG8_STAGE(PG8_SA(1, 0), a3, voffA);
;             PG8_WAIT_V(8); PG8_WAIT_L(0); PG8_BAR; if (do1) { PG8_MMA(1, 0, At, B0); PG8_MMA(1, 1, At, B1); } PG8_BAR; PG8_SCHED;
;         }
;         if (wr == 0) PG8_BAR;
	s_setprio 0
	s_add_i32 s4, 0, 0x18000
	s_add_i32 s5, 0, 0x1c000
	ds_read_b128 v[72:75], v248 offset:32768
	ds_read_b128 v[84:87], v248 offset:33792
	ds_read_b128 v[88:91], v248 offset:34816
	ds_read_b128 v[92:95], v248 offset:35840
	ds_read_b128 v[96:99], v248 offset:49152
	ds_read_b128 v[100:103], v248 offset:50176
	ds_read_b128 v[104:107], v248 offset:51200
	ds_read_b128 v[172:175], v248 offset:52224
	s_add_u32 s100, s10, 0x80000
	s_addc_u32 s101, s11, 0
	s_mov_b32 m0, s91
	ds_read_b128 v[116:119], v225 offset:32768
	ds_read_b128 v[168:171], v225 offset:33792
	ds_read_b128 v[176:179], v225 offset:34816
	ds_read_b128 v[180:183], v225 offset:35840
	ds_read_b128 v[184:187], v225 offset:36864
	ds_read_b128 v[188:191], v225 offset:37888
	ds_read_b128 v[230:233], v225 offset:38912
	ds_read_b128 v[234:237], v225 offset:39936
	global_load_lds_dwordx4 v210, s[100:101]
	s_mov_b32 m0, s92
	s_nop 0
	global_load_lds_dwordx4 v214, s[100:101]
	s_waitcnt vmcnt(8)
	s_waitcnt lgkmcnt(0)
	s_setprio 1
	s_barrier
	v_mfma_f32_16x16x32_bf16 v[60:63], v[72:75], v[116:119], v[60:63]
	v_mfma_f32_16x16x32_bf16 v[64:67], v[88:91], v[116:119], v[64:67]
	v_mfma_f32_16x16x32_bf16 v[120:123], v[72:75], v[176:179], v[120:123]
	v_mfma_f32_16x16x32_bf16 v[124:127], v[88:91], v[176:179], v[124:127]
	v_mfma_f32_16x16x32_bf16 v[164:167], v[72:75], v[184:187], v[164:167]
	v_mfma_f32_16x16x32_bf16 v[160:163], v[88:91], v[184:187], v[160:163]
	v_mfma_f32_16x16x32_bf16 v[80:83], v[72:75], v[230:233], v[80:83]
	v_mfma_f32_16x16x32_bf16 v[128:131], v[88:91], v[230:233], v[128:131]
	v_mfma_f32_16x16x32_bf16 v[60:63], v[84:87], v[168:171], v[60:63]
	v_mfma_f32_16x16x32_bf16 v[64:67], v[92:95], v[168:171], v[64:67]
	v_mfma_f32_16x16x32_bf16 v[120:123], v[84:87], v[180:183], v[120:123]
	v_mfma_f32_16x16x32_bf16 v[124:127], v[92:95], v[180:183], v[124:127]
	v_mfma_f32_16x16x32_bf16 v[164:167], v[84:87], v[188:191], v[164:167]
	v_mfma_f32_16x16x32_bf16 v[160:163], v[92:95], v[188:191], v[160:163]
	v_mfma_f32_16x16x32_bf16 v[80:83], v[84:87], v[234:237], v[80:83]
	v_mfma_f32_16x16x32_bf16 v[128:131], v[92:95], v[234:237], v[128:131]
	s_setprio 0
	s_setprio 1
	v_mfma_f32_16x16x32_bf16 v[108:111], v[104:107], v[116:119], v[108:111]
	v_mfma_f32_16x16x32_bf16 v[112:115], v[96:99], v[116:119], v[112:115]
	v_mfma_f32_16x16x32_bf16 v[116:119], v[172:175], v[168:171], v[108:111]
	v_mfma_f32_16x16x32_bf16 v[108:111], v[96:99], v[176:179], v[156:159]
	v_mfma_f32_16x16x32_bf16 v[156:159], v[100:103], v[180:183], v[108:111]
	v_mfma_f32_16x16x32_bf16 v[108:111], v[104:107], v[176:179], v[152:155]
	v_mfma_f32_16x16x32_bf16 v[152:155], v[172:175], v[180:183], v[108:111]
	v_mfma_f32_16x16x32_bf16 v[108:111], v[96:99], v[184:187], v[148:151]
	v_mfma_f32_16x16x32_bf16 v[148:151], v[100:103], v[188:191], v[108:111]
	v_mfma_f32_16x16x32_bf16 v[108:111], v[104:107], v[184:187], v[144:147]
	v_mfma_f32_16x16x32_bf16 v[144:147], v[172:175], v[188:191], v[108:111]
	v_mfma_f32_16x16x32_bf16 v[108:111], v[96:99], v[230:233], v[140:143]
	v_mfma_f32_16x16x32_bf16 v[140:143], v[100:103], v[234:237], v[108:111]
	v_mfma_f32_16x16x32_bf16 v[108:111], v[104:107], v[230:233], v[136:139]
	v_mfma_f32_16x16x32_bf16 v[112:115], v[100:103], v[168:171], v[112:115]
	v_mfma_f32_16x16x32_bf16 v[136:139], v[172:175], v[234:237], v[108:111]
	s_barrier
	s_setprio 0
	s_add_i32 s4, s4, s29
	s_mov_b32 m0, s4
	s_nop 0
	ds_read_b128 v[108:111], v225 offset:49152
	ds_read_b128 v[176:179], v225 offset:50176
	ds_read_b128 v[180:183], v225 offset:51200
	ds_read_b128 v[184:187], v225 offset:52224
	ds_read_b128 v[188:191], v225 offset:53248
	ds_read_b128 v[230:233], v225 offset:54272
	ds_read_b128 v[234:237], v225 offset:55296
	ds_read_b128 v[238:241], v225 offset:56320
	global_load_lds_dwordx4 v205, vcc
	s_add_i32 m0, s4, 0x2000
	s_add_u32 s100, vcc_lo, 0x80080
	global_load_lds_dwordx4 v227, vcc
	s_addc_u32 s101, vcc_hi, 0
	s_add_i32 s4, s5, s29
	s_mov_b32 m0, s4
	s_nop 0
	global_load_lds_dwordx4 v212, s[100:101]
	s_add_i32 m0, s4, 0x2000
	s_nop 0
	global_load_lds_dwordx4 v216, s[100:101]
	s_mov_b32 m0, s40
	s_nop 0
	global_load_lds_dwordx4 v204, s[10:11]
	s_mov_b32 m0, s41
	s_nop 0
	global_load_lds_dwordx4 v226, s[10:11]
	s_waitcnt vmcnt(8)
	s_waitcnt lgkmcnt(0)
	s_setprio 1
	s_barrier
	v_mfma_f32_16x16x32_bf16 v[4:7], v[72:75], v[234:237], v[4:7]
	v_mfma_f32_16x16x32_bf16 v[132:135], v[72:75], v[108:111], v[132:135]
	v_mfma_f32_16x16x32_bf16 v[68:71], v[88:91], v[108:111], v[68:71]
	v_mfma_f32_16x16x32_bf16 v[56:59], v[72:75], v[180:183], v[56:59]
	v_mfma_f32_16x16x32_bf16 v[52:55], v[88:91], v[180:183], v[52:55]
	v_mfma_f32_16x16x32_bf16 v[40:43], v[72:75], v[188:191], v[40:43]
	v_mfma_f32_16x16x32_bf16 v[36:39], v[88:91], v[188:191], v[36:39]
	v_mfma_f32_16x16x32_bf16 v[168:171], v[84:87], v[238:241], v[4:7]
	v_mfma_f32_16x16x32_bf16 v[4:7], v[88:91], v[234:237], v[8:11]
	v_mfma_f32_16x16x32_bf16 v[132:135], v[84:87], v[176:179], v[132:135]
	v_mfma_f32_16x16x32_bf16 v[68:71], v[92:95], v[176:179], v[68:71]
	v_mfma_f32_16x16x32_bf16 v[56:59], v[84:87], v[184:187], v[56:59]
	v_mfma_f32_16x16x32_bf16 v[52:55], v[92:95], v[184:187], v[52:55]
	v_mfma_f32_16x16x32_bf16 v[40:43], v[84:87], v[230:233], v[40:43]
	v_mfma_f32_16x16x32_bf16 v[36:39], v[92:95], v[230:233], v[36:39]
	v_mfma_f32_16x16x32_bf16 v[72:75], v[92:95], v[238:241], v[4:7]
	s_setprio 0
	s_setprio 1
	v_mfma_f32_16x16x32_bf16 v[4:7], v[96:99], v[108:111], v[48:51]
	v_mfma_f32_16x16x32_bf16 v[48:51], v[100:103], v[176:179], v[4:7]
	v_mfma_f32_16x16x32_bf16 v[4:7], v[104:107], v[108:111], v[44:47]
	v_mfma_f32_16x16x32_bf16 v[44:47], v[172:175], v[176:179], v[4:7]
	v_mfma_f32_16x16x32_bf16 v[4:7], v[96:99], v[180:183], v[32:35]
	v_mfma_f32_16x16x32_bf16 v[32:35], v[100:103], v[184:187], v[4:7]
	v_mfma_f32_16x16x32_bf16 v[4:7], v[104:107], v[180:183], v[28:31]
	v_mfma_f32_16x16x32_bf16 v[28:31], v[172:175], v[184:187], v[4:7]
	v_mfma_f32_16x16x32_bf16 v[4:7], v[96:99], v[188:191], v[24:27]
	v_mfma_f32_16x16x32_bf16 v[24:27], v[100:103], v[230:233], v[4:7]
	v_mfma_f32_16x16x32_bf16 v[4:7], v[104:107], v[188:191], v[20:23]
	v_mfma_f32_16x16x32_bf16 v[20:23], v[172:175], v[230:233], v[4:7]
	v_mfma_f32_16x16x32_bf16 v[4:7], v[96:99], v[234:237], v[16:19]
	v_mfma_f32_16x16x32_bf16 v[16:19], v[100:103], v[238:241], v[4:7]
	v_mfma_f32_16x16x32_bf16 v[4:7], v[104:107], v[234:237], v[12:15]
	v_mfma_f32_16x16x32_bf16 v[12:15], v[172:175], v[238:241], v[4:7]
	s_barrier
	s_setprio 0
	s_add_i32 s54, s54, 2
	s_add_u32 s72, s72, 0x100
	s_addc_u32 s73, s73, 0
	s_cmp_gt_u32 s54, 29
	s_mov_b64 s[44:45], s[76:77]
	s_cbranch_scc0 .LBB0_1106
	s_mov_b32 s100, 0
	s_and_b64 vcc, exec, s[14:15]
	s_cbranch_vccz .LBB0_1109
	s_barrier

; #define PG8_STAGE(bufoff, gbase, voff) do { _Pragma("unroll") for (int _i = 0; _i < 2; ++_i) \
;         __builtin_amdgcn_global_load_lds((const unsigned*)((const char*)(gbase) + (voff)[_i]), (PG8_LAS unsigned*)(lds + (bufoff) + ldsw + _i * 8192), 16, 0, 0); } while (0)
; #define PG8_LDA(dst, b, h) do { _Pragma("unroll") for (int m = 0; m < 4; ++m) _Pragma("unroll") for (int k = 0; k < 2; ++k) dst[m][k] = *(const PG8_LAS bf16x8*)(lds + PG8_SA(b, h) + aoff + m * 2048 + k * 1024); } while (0)
; #define PG8_LDB(dst, b, h) do { _Pragma("unroll") for (int n = 0; n < 2; ++n) _Pragma("unroll") for (int k = 0; k < 2; ++k) dst[n][k] = *(const PG8_LAS bf16x8*)(lds + PG8_SB(b, h) + boff + n * 2048 + k * 1024); } while (0)
; #define PG8_MMA(ai, bj, At, Bt) do { __builtin_amdgcn_s_setprio(1); _Pragma("unroll") for (int m = 0; m < 4; ++m) _Pragma("unroll") for (int n = 0; n < 2; ++n) _Pragma("unroll") for (int k = 0; k < 2; ++k) \
;         acc[ai][bj][m][n] = __builtin_amdgcn_mfma_f32_16x16x32_bf16(Bt[n][k], At[m][k], acc[ai][bj][m][n], 0, 0, 0); __builtin_amdgcn_s_setprio(0); } while (0)
; #define PG8_WAIT_V(n) asm volatile("s_waitcnt vmcnt(" #n ")" ::: "memory")
; #define PG8_WAIT_L(n) asm volatile("s_waitcnt lgkmcnt(" #n ")" ::: "memory")
; #define PG8_BAR __builtin_amdgcn_s_barrier()
; #define PG8_SCHED __builtin_amdgcn_sched_barrier(0)
; template <class Epi>
; __device__ __forceinline__ void gemm_phase(PG8_LAS unsigned char* lds, PG8_LAS unsigned char* xl, const Gemm g, const Sched& S, const Epi& E, const int wid) {
;     ...
;             const char* a1 = cA + (size_t)(t + 1) * kstep + j1;
;             const char* a2 = last ? nA : cA + (size_t)(t + 2) * kstep + ja2; const char* b2 = last ? nB : cB + (size_t)(t + 2) * kstep + jb2;
;             const char* a3 = a2 + kstep; const char* b3 = b2 + kstep;
;             PG8_LDB(B0, 0, 0); PG8_LDB(B1, 0, 1); PG8_SCHED; PG8_LDA(At, 0, 0); PG8_STAGE(PG8_SA(1, 1), a1 + hstepA, voffA);
;             PG8_WAIT_V(8); PG8_WAIT_L(0); PG8_BAR; if (do0) { PG8_MMA(0, 0, At, B0); PG8_MMA(0, 1, At, B1); } PG8_BAR; PG8_SCHED;
;             PG8_LDA(At, 0, 1); PG8_STAGE(PG8_SB(0, 0), b2, voffB); PG8_STAGE(PG8_SB(0, 1), b2 + hstepB, voffB); PG8_STAGE(PG8_SA(0, 0), a2, voffA);
;             PG8_WAIT_V(8); PG8_WAIT_L(0); PG8_BAR; if (do1) { PG8_MMA(1, 0, At, B0); PG8_MMA(1, 1, At, B1); } PG8_BAR; PG8_SCHED;
.LBB0_1304:
	s_add_u32 s4, s36, 0xffea0080
	s_addc_u32 s5, s37, -1
	s_add_i32 s13, 0, 0x10000
	s_cmpk_eq_i32 s9, 0x54
	s_cselect_b32 s11, s21, s5
	s_cselect_b32 s10, s20, s4
	s_cselect_b32 s41, s31, s8
	s_cselect_b32 s40, s30, s1
	s_add_i32 s4, 0, 0x14000
	ds_read_b128 v[120:123], v226 offset:0
	ds_read_b128 v[124:127], v226 offset:1024
	ds_read_b128 v[128:131], v226 offset:2048
	ds_read_b128 v[136:139], v226 offset:3072
	ds_read_b128 v[144:147], v226 offset:16384
	ds_read_b128 v[148:151], v226 offset:17408
	ds_read_b128 v[152:155], v226 offset:18432
	ds_read_b128 v[156:159], v226 offset:19456
	s_add_i32 m0, s51, 0xc000
	ds_read_b128 v[160:163], v220
	ds_read_b128 v[164:167], v220 offset:1024
	ds_read_b128 v[168:171], v220 offset:2048
	ds_read_b128 v[172:175], v220 offset:3072
	ds_read_b128 v[176:179], v220 offset:4096
	ds_read_b128 v[180:183], v220 offset:5120
	ds_read_b128 v[184:187], v220 offset:6144
	ds_read_b128 v[222:225], v220 offset:7168
	global_load_lds_dwordx4 v214, s[36:37]
	s_add_i32 m0, s51, 0xe000
	s_nop 0
	global_load_lds_dwordx4 v216, s[36:37]
	s_waitcnt vmcnt(8)
	s_waitcnt lgkmcnt(0)
	s_setprio 1
	s_barrier
	v_mfma_f32_16x16x32_bf16 v[140:143], v[120:123], v[160:163], v[140:143]
	v_mfma_f32_16x16x32_bf16 v[132:135], v[128:131], v[160:163], v[132:135]
	v_mfma_f32_16x16x32_bf16 v[108:111], v[120:123], v[168:171], v[108:111]
	v_mfma_f32_16x16x32_bf16 v[104:107], v[128:131], v[168:171], v[104:107]
	v_mfma_f32_16x16x32_bf16 v[92:95], v[120:123], v[176:179], v[92:95]
	v_mfma_f32_16x16x32_bf16 v[88:91], v[128:131], v[176:179], v[88:91]
	v_mfma_f32_16x16x32_bf16 v[76:79], v[120:123], v[184:187], v[76:79]
	v_mfma_f32_16x16x32_bf16 v[72:75], v[128:131], v[184:187], v[72:75]
	v_mfma_f32_16x16x32_bf16 v[140:143], v[124:127], v[164:167], v[140:143]
	v_mfma_f32_16x16x32_bf16 v[132:135], v[136:139], v[164:167], v[132:135]
	v_mfma_f32_16x16x32_bf16 v[108:111], v[124:127], v[172:175], v[108:111]
	v_mfma_f32_16x16x32_bf16 v[104:107], v[136:139], v[172:175], v[104:107]
	v_mfma_f32_16x16x32_bf16 v[92:95], v[124:127], v[180:183], v[92:95]
	v_mfma_f32_16x16x32_bf16 v[88:91], v[136:139], v[180:183], v[88:91]
	v_mfma_f32_16x16x32_bf16 v[76:79], v[124:127], v[222:225], v[76:79]
	v_mfma_f32_16x16x32_bf16 v[72:75], v[136:139], v[222:225], v[72:75]
	s_setprio 0
	s_setprio 1
	v_mfma_f32_16x16x32_bf16 v[116:119], v[144:147], v[160:163], v[116:119]
	v_mfma_f32_16x16x32_bf16 v[112:115], v[152:155], v[160:163], v[112:115]
	v_mfma_f32_16x16x32_bf16 v[100:103], v[144:147], v[168:171], v[100:103]
	v_mfma_f32_16x16x32_bf16 v[96:99], v[152:155], v[168:171], v[96:99]
	v_mfma_f32_16x16x32_bf16 v[84:87], v[144:147], v[176:179], v[84:87]
	v_mfma_f32_16x16x32_bf16 v[80:83], v[152:155], v[176:179], v[80:83]
	v_mfma_f32_16x16x32_bf16 v[68:71], v[144:147], v[184:187], v[68:71]
	v_mfma_f32_16x16x32_bf16 v[64:67], v[152:155], v[184:187], v[64:67]
	v_mfma_f32_16x16x32_bf16 v[116:119], v[148:151], v[164:167], v[116:119]
	v_mfma_f32_16x16x32_bf16 v[112:115], v[156:159], v[164:167], v[112:115]
	v_mfma_f32_16x16x32_bf16 v[100:103], v[148:151], v[172:175], v[100:103]
	v_mfma_f32_16x16x32_bf16 v[96:99], v[156:159], v[172:175], v[96:99]
	v_mfma_f32_16x16x32_bf16 v[84:87], v[148:151], v[180:183], v[84:87]
	v_mfma_f32_16x16x32_bf16 v[80:83], v[156:159], v[180:183], v[80:83]
	v_mfma_f32_16x16x32_bf16 v[68:71], v[148:151], v[222:225], v[68:71]
	v_mfma_f32_16x16x32_bf16 v[64:67], v[156:159], v[222:225], v[64:67]
	s_barrier
	s_setprio 0
	s_add_i32 s5, s13, s29
	s_mov_b32 m0, s5
	ds_read_b128 v[160:163], v220 offset:16384
	ds_read_b128 v[164:167], v220 offset:17408
	ds_read_b128 v[168:171], v220 offset:18432
	ds_read_b128 v[172:175], v220 offset:19456
	ds_read_b128 v[176:179], v220 offset:20480
	ds_read_b128 v[180:183], v220 offset:21504
	ds_read_b128 v[184:187], v220 offset:22528
	ds_read_b128 v[222:225], v220 offset:23552
	global_load_lds_dwordx4 v190, s[40:41]
	s_add_i32 m0, s5, 0x2000
	s_add_u32 s44, s40, 0x160000
	s_addc_u32 s45, s41, 0
	s_add_i32 s4, s4, s29
	global_load_lds_dwordx4 v212, s[40:41]
	s_mov_b32 m0, s4
	s_nop 0
	global_load_lds_dwordx4 v190, s[44:45]
	s_add_i32 m0, s4, 0x2000
	s_nop 0
	global_load_lds_dwordx4 v212, s[44:45]
	s_mov_b32 m0, s51
	s_nop 0
	global_load_lds_dwordx4 v188, s[10:11]
	s_mov_b32 m0, s52
	s_nop 0
	global_load_lds_dwordx4 v210, s[10:11]
	s_waitcnt vmcnt(8)
	s_waitcnt lgkmcnt(0)
	s_setprio 1
	s_barrier
	v_mfma_f32_16x16x32_bf16 v[60:63], v[120:123], v[160:163], v[60:63]
	v_mfma_f32_16x16x32_bf16 v[56:59], v[128:131], v[160:163], v[56:59]
	v_mfma_f32_16x16x32_bf16 v[44:47], v[120:123], v[168:171], v[44:47]
	v_mfma_f32_16x16x32_bf16 v[40:43], v[128:131], v[168:171], v[40:43]
	v_mfma_f32_16x16x32_bf16 v[28:31], v[120:123], v[176:179], v[28:31]
	v_mfma_f32_16x16x32_bf16 v[24:27], v[128:131], v[176:179], v[24:27]
	v_mfma_f32_16x16x32_bf16 v[12:15], v[120:123], v[184:187], v[12:15]
	v_mfma_f32_16x16x32_bf16 v[8:11], v[128:131], v[184:187], v[8:11]
	v_mfma_f32_16x16x32_bf16 v[60:63], v[124:127], v[164:167], v[60:63]
	v_mfma_f32_16x16x32_bf16 v[56:59], v[136:139], v[164:167], v[56:59]
	v_mfma_f32_16x16x32_bf16 v[44:47], v[124:127], v[172:175], v[44:47]
	v_mfma_f32_16x16x32_bf16 v[40:43], v[136:139], v[172:175], v[40:43]
	v_mfma_f32_16x16x32_bf16 v[28:31], v[124:127], v[180:183], v[28:31]
	v_mfma_f32_16x16x32_bf16 v[24:27], v[136:139], v[180:183], v[24:27]
	v_mfma_f32_16x16x32_bf16 v[12:15], v[124:127], v[222:225], v[12:15]
	v_mfma_f32_16x16x32_bf16 v[8:11], v[136:139], v[222:225], v[8:11]
	s_setprio 0
	s_setprio 1
	v_mfma_f32_16x16x32_bf16 v[52:55], v[144:147], v[160:163], v[52:55]
	v_mfma_f32_16x16x32_bf16 v[48:51], v[152:155], v[160:163], v[48:51]
	v_mfma_f32_16x16x32_bf16 v[36:39], v[144:147], v[168:171], v[36:39]
	v_mfma_f32_16x16x32_bf16 v[32:35], v[152:155], v[168:171], v[32:35]
	v_mfma_f32_16x16x32_bf16 v[20:23], v[144:147], v[176:179], v[20:23]
	v_mfma_f32_16x16x32_bf16 v[16:19], v[152:155], v[176:179], v[16:19]
	v_mfma_f32_16x16x32_bf16 v[4:7], v[144:147], v[184:187], v[4:7]
	v_mfma_f32_16x16x32_bf16 v[0:3], v[152:155], v[184:187], v[0:3]
	v_mfma_f32_16x16x32_bf16 v[52:55], v[148:151], v[164:167], v[52:55]
	v_mfma_f32_16x16x32_bf16 v[48:51], v[156:159], v[164:167], v[48:51]
	v_mfma_f32_16x16x32_bf16 v[36:39], v[148:151], v[172:175], v[36:39]
	v_mfma_f32_16x16x32_bf16 v[32:35], v[156:159], v[172:175], v[32:35]
	v_mfma_f32_16x16x32_bf16 v[20:23], v[148:151], v[180:183], v[20:23]
	v_mfma_f32_16x16x32_bf16 v[16:19], v[156:159], v[180:183], v[16:19]
	v_mfma_f32_16x16x32_bf16 v[4:7], v[148:151], v[222:225], v[4:7]
	v_mfma_f32_16x16x32_bf16 v[0:3], v[156:159], v[222:225], v[0:3]
	s_barrier
; #define PG8_STAGE(bufoff, gbase, voff) do { _Pragma("unroll") for (int _i = 0; _i < 2; ++_i) \
;         __builtin_amdgcn_global_load_lds((const unsigned*)((const char*)(gbase) + (voff)[_i]), (PG8_LAS unsigned*)(lds + (bufoff) + ldsw + _i * 8192), 16, 0, 0); } while (0)
; #define PG8_LDA(dst, b, h) do { _Pragma("unroll") for (int m = 0; m < 4; ++m) _Pragma("unroll") for (int k = 0; k < 2; ++k) dst[m][k] = *(const PG8_LAS bf16x8*)(lds + PG8_SA(b, h) + aoff + m * 2048 + k * 1024); } while (0)
; #define PG8_LDB(dst, b, h) do { _Pragma("unroll") for (int n = 0; n < 2; ++n) _Pragma("unroll") for (int k = 0; k < 2; ++k) dst[n][k] = *(const PG8_LAS bf16x8*)(lds + PG8_SB(b, h) + boff + n * 2048 + k * 1024); } while (0)
; #define PG8_MMA(ai, bj, At, Bt) do { __builtin_amdgcn_s_setprio(1); _Pragma("unroll") for (int m = 0; m < 4; ++m) _Pragma("unroll") for (int n = 0; n < 2; ++n) _Pragma("unroll") for (int k = 0; k < 2; ++k) \
;         acc[ai][bj][m][n] = __builtin_amdgcn_mfma_f32_16x16x32_bf16(Bt[n][k], At[m][k], acc[ai][bj][m][n], 0, 0, 0); __builtin_amdgcn_s_setprio(0); } while (0)
; #define PG8_WAIT_V(n) asm volatile("s_waitcnt vmcnt(" #n ")" ::: "memory")
; #define PG8_WAIT_L(n) asm volatile("s_waitcnt lgkmcnt(" #n ")" ::: "memory")
; #define PG8_BAR __builtin_amdgcn_s_barrier()
; #define PG8_SCHED __builtin_amdgcn_sched_barrier(0)
; template <class Epi>
; __device__ __forceinline__ void gemm_phase(PG8_LAS unsigned char* lds, PG8_LAS unsigned char* xl, const Gemm g, const Sched& S, const Epi& E, const int wid) {
;     ...
;             PG8_LDB(B0, 1, 0); PG8_LDB(B1, 1, 1); PG8_SCHED; PG8_LDA(At, 1, 0); PG8_STAGE(PG8_SA(0, 1), a2 + hstepA, voffA);
;             PG8_WAIT_V(8); PG8_WAIT_L(0); PG8_BAR; if (do0) { PG8_MMA(0, 0, At, B0); PG8_MMA(0, 1, At, B1); } PG8_BAR; PG8_SCHED;
;             PG8_LDA(At, 1, 1); PG8_STAGE(PG8_SB(1, 0), b3, voffB); PG8_STAGE(PG8_SB(1, 1), b3 + hstepB, voffB); PG8_STAGE(PG8_SA(1, 0), a3, voffA);
;             PG8_WAIT_V(8); PG8_WAIT_L(0); PG8_BAR; if (do1) { PG8_MMA(1, 0, At, B0); PG8_MMA(1, 1, At, B1); } PG8_BAR; PG8_SCHED;
;         }
;         if (wr == 0) PG8_BAR;
	s_setprio 0
	s_add_i32 s4, 0, 0x18000
	s_add_i32 s5, 0, 0x1c000
	ds_read_b128 v[120:123], v226 offset:32768
	ds_read_b128 v[124:127], v226 offset:33792
	ds_read_b128 v[128:131], v226 offset:34816
	ds_read_b128 v[136:139], v226 offset:35840
	ds_read_b128 v[144:147], v226 offset:49152
	ds_read_b128 v[148:151], v226 offset:50176
	ds_read_b128 v[152:155], v226 offset:51200
	ds_read_b128 v[156:159], v226 offset:52224
	s_add_u32 s100, s10, 0x160000
	s_addc_u32 s101, s11, 0
	s_mov_b32 m0, s53
	ds_read_b128 v[160:163], v220 offset:32768
	ds_read_b128 v[164:167], v220 offset:33792
	ds_read_b128 v[168:171], v220 offset:34816
	ds_read_b128 v[172:175], v220 offset:35840
	ds_read_b128 v[176:179], v220 offset:36864
	ds_read_b128 v[180:183], v220 offset:37888
	ds_read_b128 v[184:187], v220 offset:38912
	ds_read_b128 v[222:225], v220 offset:39936
	global_load_lds_dwordx4 v188, s[100:101]
	s_mov_b32 m0, s56
	s_nop 0
	global_load_lds_dwordx4 v210, s[100:101]
	s_waitcnt vmcnt(8)
	s_waitcnt lgkmcnt(0)
	s_setprio 1
	s_barrier
	v_mfma_f32_16x16x32_bf16 v[140:143], v[120:123], v[160:163], v[140:143]
	v_mfma_f32_16x16x32_bf16 v[132:135], v[128:131], v[160:163], v[132:135]
	v_mfma_f32_16x16x32_bf16 v[108:111], v[120:123], v[168:171], v[108:111]
	v_mfma_f32_16x16x32_bf16 v[104:107], v[128:131], v[168:171], v[104:107]
	v_mfma_f32_16x16x32_bf16 v[92:95], v[120:123], v[176:179], v[92:95]
	v_mfma_f32_16x16x32_bf16 v[88:91], v[128:131], v[176:179], v[88:91]
	v_mfma_f32_16x16x32_bf16 v[76:79], v[120:123], v[184:187], v[76:79]
	v_mfma_f32_16x16x32_bf16 v[72:75], v[128:131], v[184:187], v[72:75]
	v_mfma_f32_16x16x32_bf16 v[140:143], v[124:127], v[164:167], v[140:143]
	v_mfma_f32_16x16x32_bf16 v[132:135], v[136:139], v[164:167], v[132:135]
	v_mfma_f32_16x16x32_bf16 v[108:111], v[124:127], v[172:175], v[108:111]
	v_mfma_f32_16x16x32_bf16 v[104:107], v[136:139], v[172:175], v[104:107]
	v_mfma_f32_16x16x32_bf16 v[92:95], v[124:127], v[180:183], v[92:95]
	v_mfma_f32_16x16x32_bf16 v[88:91], v[136:139], v[180:183], v[88:91]
	v_mfma_f32_16x16x32_bf16 v[76:79], v[124:127], v[222:225], v[76:79]
	v_mfma_f32_16x16x32_bf16 v[72:75], v[136:139], v[222:225], v[72:75]
	s_setprio 0
	s_setprio 1
	v_mfma_f32_16x16x32_bf16 v[116:119], v[144:147], v[160:163], v[116:119]
	v_mfma_f32_16x16x32_bf16 v[112:115], v[152:155], v[160:163], v[112:115]
	v_mfma_f32_16x16x32_bf16 v[100:103], v[144:147], v[168:171], v[100:103]
	v_mfma_f32_16x16x32_bf16 v[96:99], v[152:155], v[168:171], v[96:99]
	v_mfma_f32_16x16x32_bf16 v[84:87], v[144:147], v[176:179], v[84:87]
	v_mfma_f32_16x16x32_bf16 v[80:83], v[152:155], v[176:179], v[80:83]
	v_mfma_f32_16x16x32_bf16 v[68:71], v[144:147], v[184:187], v[68:71]
	v_mfma_f32_16x16x32_bf16 v[64:67], v[152:155], v[184:187], v[64:67]
	v_mfma_f32_16x16x32_bf16 v[116:119], v[148:151], v[164:167], v[116:119]
	v_mfma_f32_16x16x32_bf16 v[112:115], v[156:159], v[164:167], v[112:115]
	v_mfma_f32_16x16x32_bf16 v[100:103], v[148:151], v[172:175], v[100:103]
	v_mfma_f32_16x16x32_bf16 v[96:99], v[156:159], v[172:175], v[96:99]
	v_mfma_f32_16x16x32_bf16 v[84:87], v[148:151], v[180:183], v[84:87]
	v_mfma_f32_16x16x32_bf16 v[80:83], v[156:159], v[180:183], v[80:83]
	v_mfma_f32_16x16x32_bf16 v[68:71], v[148:151], v[222:225], v[68:71]
	v_mfma_f32_16x16x32_bf16 v[64:67], v[156:159], v[222:225], v[64:67]
	s_barrier
	s_setprio 0
	s_add_i32 s4, s4, s29
	s_mov_b32 m0, s4
	ds_read_b128 v[160:163], v220 offset:49152
	ds_read_b128 v[164:167], v220 offset:50176
	ds_read_b128 v[168:171], v220 offset:51200
	ds_read_b128 v[172:175], v220 offset:52224
	ds_read_b128 v[176:179], v220 offset:53248
	ds_read_b128 v[180:183], v220 offset:54272
	ds_read_b128 v[184:187], v220 offset:55296
	ds_read_b128 v[222:225], v220 offset:56320
	global_load_lds_dwordx4 v205, s[40:41]
	s_add_i32 m0, s4, 0x2000
	s_add_u32 s100, s40, 0x160080
	global_load_lds_dwordx4 v219, s[40:41]
	s_addc_u32 s101, s41, 0
	s_add_i32 s4, s5, s29
	s_mov_b32 m0, s4
	s_nop 0
	global_load_lds_dwordx4 v190, s[100:101]
	s_add_i32 m0, s4, 0x2000
	s_nop 0
	global_load_lds_dwordx4 v212, s[100:101]
	s_mov_b32 m0, s61
	s_nop 0
	global_load_lds_dwordx4 v204, s[10:11]
	s_mov_b32 m0, s62
	s_nop 0
	global_load_lds_dwordx4 v218, s[10:11]
	s_waitcnt vmcnt(8)
	s_waitcnt lgkmcnt(0)
	s_setprio 1
	s_barrier
	v_mfma_f32_16x16x32_bf16 v[60:63], v[120:123], v[160:163], v[60:63]
	v_mfma_f32_16x16x32_bf16 v[56:59], v[128:131], v[160:163], v[56:59]
	v_mfma_f32_16x16x32_bf16 v[44:47], v[120:123], v[168:171], v[44:47]
	v_mfma_f32_16x16x32_bf16 v[40:43], v[128:131], v[168:171], v[40:43]
	v_mfma_f32_16x16x32_bf16 v[28:31], v[120:123], v[176:179], v[28:31]
	v_mfma_f32_16x16x32_bf16 v[24:27], v[128:131], v[176:179], v[24:27]
	v_mfma_f32_16x16x32_bf16 v[12:15], v[120:123], v[184:187], v[12:15]
	v_mfma_f32_16x16x32_bf16 v[8:11], v[128:131], v[184:187], v[8:11]
	v_mfma_f32_16x16x32_bf16 v[60:63], v[124:127], v[164:167], v[60:63]
	v_mfma_f32_16x16x32_bf16 v[56:59], v[136:139], v[164:167], v[56:59]
	v_mfma_f32_16x16x32_bf16 v[44:47], v[124:127], v[172:175], v[44:47]
	v_mfma_f32_16x16x32_bf16 v[40:43], v[136:139], v[172:175], v[40:43]
	v_mfma_f32_16x16x32_bf16 v[28:31], v[124:127], v[180:183], v[28:31]
	v_mfma_f32_16x16x32_bf16 v[24:27], v[136:139], v[180:183], v[24:27]
	v_mfma_f32_16x16x32_bf16 v[12:15], v[124:127], v[222:225], v[12:15]
	v_mfma_f32_16x16x32_bf16 v[8:11], v[136:139], v[222:225], v[8:11]
	s_setprio 0
	s_setprio 1
	v_mfma_f32_16x16x32_bf16 v[52:55], v[144:147], v[160:163], v[52:55]
	v_mfma_f32_16x16x32_bf16 v[48:51], v[152:155], v[160:163], v[48:51]
	v_mfma_f32_16x16x32_bf16 v[36:39], v[144:147], v[168:171], v[36:39]
	v_mfma_f32_16x16x32_bf16 v[32:35], v[152:155], v[168:171], v[32:35]
	v_mfma_f32_16x16x32_bf16 v[20:23], v[144:147], v[176:179], v[20:23]
	v_mfma_f32_16x16x32_bf16 v[16:19], v[152:155], v[176:179], v[16:19]
	v_mfma_f32_16x16x32_bf16 v[4:7], v[144:147], v[184:187], v[4:7]
	v_mfma_f32_16x16x32_bf16 v[0:3], v[152:155], v[184:187], v[0:3]
	v_mfma_f32_16x16x32_bf16 v[52:55], v[148:151], v[164:167], v[52:55]
	v_mfma_f32_16x16x32_bf16 v[48:51], v[156:159], v[164:167], v[48:51]
	v_mfma_f32_16x16x32_bf16 v[36:39], v[148:151], v[172:175], v[36:39]
	v_mfma_f32_16x16x32_bf16 v[32:35], v[156:159], v[172:175], v[32:35]
	v_mfma_f32_16x16x32_bf16 v[20:23], v[148:151], v[180:183], v[20:23]
	v_mfma_f32_16x16x32_bf16 v[16:19], v[156:159], v[180:183], v[16:19]
	v_mfma_f32_16x16x32_bf16 v[4:7], v[148:151], v[222:225], v[4:7]
	v_mfma_f32_16x16x32_bf16 v[0:3], v[156:159], v[222:225], v[0:3]
	s_barrier
	s_setprio 0
	s_add_i32 s9, s9, 2
	s_add_u32 s36, s36, 0x100
	s_addc_u32 s37, s37, 0
	s_add_u32 s1, s1, 0x100
	s_addc_u32 s8, s8, 0
	s_cmpk_gt_u32 s9, 0x55
	s_cbranch_scc0 .LBB0_1304
	s_mov_b32 s100, 0
	s_and_b64 vcc, exec, s[14:15]
	s_cbranch_vccz .LBB0_1307
	s_barrier
